# v19 plus loop-invariant LDS fragment-read base addresses computed once before each GEMM K loop (last per-iteration v_add_u32 removed)
# baseline (speedup 1.0000x reference)
.LBB0_232:
	s_ashr_i32 s25, s24, 31
	s_lshl_b64 s[26:27], s[24:25], 21
	s_add_u32 s26, s46, s26
	s_addc_u32 s27, s47, s27
	s_and_b64 s[28:29], s[2:3], exec
	s_cselect_b32 s25, s27, s35
	s_cselect_b32 s64, s26, s34
	s_ashr_i32 s23, s22, 31
	s_lshl_b64 s[28:29], s[22:23], 21
	s_add_u32 s28, s48, s28
	s_addc_u32 s29, s49, s29
	s_and_b64 s[38:39], s[2:3], exec
	s_cselect_b32 s23, s29, s37
	s_cselect_b32 s65, s28, s36
	s_add_u32 s66, s36, 0x100
	s_addc_u32 s67, s37, 0
	s_add_u32 s34, s34, 0x100080
	v_mov_b32_e32 v0, 0
	s_addc_u32 s35, s35, 0
	s_mov_b32 s68, -2
	v_mov_b32_e32 v1, v0
	v_mov_b32_e32 v2, v0
	v_mov_b32_e32 v3, v0
	v_mov_b32_e32 v4, v0
	v_mov_b32_e32 v5, v0
	v_mov_b32_e32 v6, v0
	v_mov_b32_e32 v7, v0
	v_mov_b32_e32 v12, v0
	v_mov_b32_e32 v13, v0
	v_mov_b32_e32 v14, v0
	v_mov_b32_e32 v15, v0
	v_mov_b32_e32 v20, v0
	v_mov_b32_e32 v21, v0
	v_mov_b32_e32 v22, v0
	v_mov_b32_e32 v23, v0
	v_mov_b32_e32 v28, v0
	v_mov_b32_e32 v29, v0
	v_mov_b32_e32 v30, v0
	v_mov_b32_e32 v31, v0
	v_mov_b32_e32 v36, v0
	v_mov_b32_e32 v37, v0
	v_mov_b32_e32 v38, v0
	v_mov_b32_e32 v39, v0
	v_mov_b32_e32 v44, v0
	v_mov_b32_e32 v45, v0
	v_mov_b32_e32 v46, v0
	v_mov_b32_e32 v47, v0
	v_mov_b32_e32 v52, v0
	v_mov_b32_e32 v53, v0
	v_mov_b32_e32 v54, v0
	v_mov_b32_e32 v55, v0
	v_mov_b32_e32 v8, v0
	v_mov_b32_e32 v9, v0
	v_mov_b32_e32 v10, v0
	v_mov_b32_e32 v11, v0
	v_mov_b32_e32 v16, v0
	v_mov_b32_e32 v17, v0
	v_mov_b32_e32 v18, v0
	v_mov_b32_e32 v19, v0
	v_mov_b32_e32 v24, v0
	v_mov_b32_e32 v25, v0
	v_mov_b32_e32 v26, v0
	v_mov_b32_e32 v27, v0
	v_mov_b32_e32 v32, v0
	v_mov_b32_e32 v33, v0
	v_mov_b32_e32 v34, v0
	v_mov_b32_e32 v35, v0
	v_mov_b32_e32 v40, v0
	v_mov_b32_e32 v41, v0
	v_mov_b32_e32 v42, v0
	v_mov_b32_e32 v43, v0
	v_mov_b32_e32 v48, v0
	v_mov_b32_e32 v49, v0
	v_mov_b32_e32 v50, v0
	v_mov_b32_e32 v51, v0
	v_mov_b32_e32 v56, v0
	v_mov_b32_e32 v57, v0
	v_mov_b32_e32 v58, v0
	v_mov_b32_e32 v59, v0
	v_mov_b32_e32 v60, v0
	v_mov_b32_e32 v61, v0
	v_mov_b32_e32 v62, v0
	v_mov_b32_e32 v63, v0
	v_mov_b32_e32 v64, v0
	v_mov_b32_e32 v65, v0
	v_mov_b32_e32 v66, v0
	v_mov_b32_e32 v67, v0
	v_mov_b32_e32 v68, v0
	v_mov_b32_e32 v69, v0
	v_mov_b32_e32 v70, v0
	v_mov_b32_e32 v71, v0
	v_mov_b32_e32 v80, v0
	v_mov_b32_e32 v81, v0
	v_mov_b32_e32 v82, v0
	v_mov_b32_e32 v83, v0
	v_mov_b32_e32 v84, v0
	v_mov_b32_e32 v85, v0
	v_mov_b32_e32 v86, v0
	v_mov_b32_e32 v87, v0
	v_mov_b32_e32 v96, v0
	v_mov_b32_e32 v97, v0
	v_mov_b32_e32 v98, v0
	v_mov_b32_e32 v99, v0
	v_mov_b32_e32 v100, v0
	v_mov_b32_e32 v101, v0
	v_mov_b32_e32 v102, v0
	v_mov_b32_e32 v103, v0
	v_mov_b32_e32 v112, v0
	v_mov_b32_e32 v113, v0
	v_mov_b32_e32 v114, v0
	v_mov_b32_e32 v115, v0
	v_mov_b32_e32 v116, v0
	v_mov_b32_e32 v117, v0
	v_mov_b32_e32 v118, v0
	v_mov_b32_e32 v119, v0
	v_mov_b32_e32 v72, v0
	v_mov_b32_e32 v73, v0
	v_mov_b32_e32 v74, v0
	v_mov_b32_e32 v75, v0
	v_mov_b32_e32 v76, v0
	v_mov_b32_e32 v77, v0
	v_mov_b32_e32 v78, v0
	v_mov_b32_e32 v79, v0
	v_mov_b32_e32 v88, v0
	v_mov_b32_e32 v89, v0
	v_mov_b32_e32 v90, v0
	v_mov_b32_e32 v91, v0
	v_mov_b32_e32 v92, v0
	v_mov_b32_e32 v93, v0
	v_mov_b32_e32 v94, v0
	v_mov_b32_e32 v95, v0
	v_mov_b32_e32 v104, v0
	v_mov_b32_e32 v105, v0
	v_mov_b32_e32 v106, v0
	v_mov_b32_e32 v107, v0
	v_mov_b32_e32 v108, v0
	v_mov_b32_e32 v109, v0
	v_mov_b32_e32 v110, v0
	v_mov_b32_e32 v111, v0
	v_mov_b32_e32 v120, v0
	v_mov_b32_e32 v121, v0
	v_mov_b32_e32 v122, v0
	v_mov_b32_e32 v123, v0
	v_mov_b32_e32 v124, v0
	v_mov_b32_e32 v125, v0
	v_mov_b32_e32 v126, v0
	v_mov_b32_e32 v127, v0
	v_add_u32_e32 v248, 0x18000, v149
	v_add_u32_e32 v249, 0x1c000, v149
	s_cmp_lt_u32 s81, 4
	s_cbranch_scc0 .Lsp_skip0
	s_setprio 1
.Lsp_skip0:
.LBB0_233:
	ds_read_b128 v[162:165], v155
	ds_read_b128 v[166:169], v155 offset:1024
	ds_read_b128 v[170:173], v155 offset:2048
	ds_read_b128 v[174:177], v155 offset:3072
	ds_read_b128 v[178:181], v158
	ds_read_b128 v[182:185], v158 offset:1024
	ds_read_b128 v[186:189], v158 offset:2048
	ds_read_b128 v[190:193], v158 offset:3072
	ds_read_b128 v[194:197], v159
	ds_read_b128 v[198:201], v159 offset:1024
	ds_read_b128 v[202:205], v159 offset:2048
	ds_read_b128 v[206:209], v159 offset:3072
	ds_read_b128 v[210:213], v159 offset:4096
	ds_read_b128 v[214:217], v159 offset:5120
	ds_read_b128 v[218:221], v159 offset:6144
	ds_read_b128 v[222:225], v159 offset:7168
	s_add_u32 s36, s34, 0xfff00080
	s_addc_u32 s37, s35, -1
	s_cmp_eq_u32 s68, 60
	s_cselect_b32 s39, s25, s37
	s_cselect_b32 s38, s64, s36
	s_cselect_b32 s37, s23, s67
	s_cselect_b32 s36, s65, s66
	s_add_i32 m0, s31, 0xc000
	s_nop 0
	global_load_lds_dwordx4 v138, s[34:35]
	s_add_i32 m0, s31, 0xe000
	s_nop 0
	global_load_lds_dwordx4 v136, s[34:35]
	s_waitcnt vmcnt(8)
	s_waitcnt lgkmcnt(0)
	s_barrier
	s_waitcnt lgkmcnt(0)
	v_mfma_f32_16x16x32_bf16 v[124:127], v[162:165], v[194:197], v[124:127]
	v_mfma_f32_16x16x32_bf16 v[120:123], v[170:173], v[194:197], v[120:123]
	v_mfma_f32_16x16x32_bf16 v[108:111], v[162:165], v[202:205], v[108:111]
	v_mfma_f32_16x16x32_bf16 v[104:107], v[170:173], v[202:205], v[104:107]
	s_add_u32 s98, s36, s12
	s_addc_u32 s99, s37, s13
	s_add_i32 s69, s57, s40
	v_mfma_f32_16x16x32_bf16 v[92:95], v[162:165], v[210:213], v[92:95]
	s_add_u32 s100, s38, s12
	s_addc_u32 s101, s39, s13
	v_mfma_f32_16x16x32_bf16 v[88:91], v[170:173], v[210:213], v[88:91]
	v_mfma_f32_16x16x32_bf16 v[76:79], v[162:165], v[218:221], v[76:79]
	v_mfma_f32_16x16x32_bf16 v[72:75], v[170:173], v[218:221], v[72:75]
	s_add_u32 s70, s36, 0x100000
	v_mfma_f32_16x16x32_bf16 v[124:127], v[166:169], v[198:201], v[124:127]
	v_mfma_f32_16x16x32_bf16 v[120:123], v[174:177], v[198:201], v[120:123]
	v_mfma_f32_16x16x32_bf16 v[108:111], v[166:169], v[206:209], v[108:111]
	v_mfma_f32_16x16x32_bf16 v[104:107], v[174:177], v[206:209], v[104:107]
	s_addc_u32 s71, s37, 0
	v_mfma_f32_16x16x32_bf16 v[92:95], v[166:169], v[214:217], v[92:95]
	v_mfma_f32_16x16x32_bf16 v[88:91], v[174:177], v[214:217], v[88:91]
	v_mfma_f32_16x16x32_bf16 v[76:79], v[166:169], v[222:225], v[76:79]
	v_mfma_f32_16x16x32_bf16 v[72:75], v[174:177], v[222:225], v[72:75]
	v_mfma_f32_16x16x32_bf16 v[116:119], v[178:181], v[194:197], v[116:119]
	v_mfma_f32_16x16x32_bf16 v[112:115], v[186:189], v[194:197], v[112:115]
	v_mfma_f32_16x16x32_bf16 v[100:103], v[178:181], v[202:205], v[100:103]
	v_mfma_f32_16x16x32_bf16 v[96:99], v[186:189], v[202:205], v[96:99]
	v_mfma_f32_16x16x32_bf16 v[84:87], v[178:181], v[210:213], v[84:87]
	v_mfma_f32_16x16x32_bf16 v[80:83], v[186:189], v[210:213], v[80:83]
	v_mfma_f32_16x16x32_bf16 v[68:71], v[178:181], v[218:221], v[68:71]
	v_mfma_f32_16x16x32_bf16 v[64:67], v[186:189], v[218:221], v[64:67]
	v_mfma_f32_16x16x32_bf16 v[116:119], v[182:185], v[198:201], v[116:119]
	v_mfma_f32_16x16x32_bf16 v[112:115], v[190:193], v[198:201], v[112:115]
	v_mfma_f32_16x16x32_bf16 v[100:103], v[182:185], v[206:209], v[100:103]
	v_mfma_f32_16x16x32_bf16 v[96:99], v[190:193], v[206:209], v[96:99]
	v_mfma_f32_16x16x32_bf16 v[84:87], v[182:185], v[214:217], v[84:87]
	v_mfma_f32_16x16x32_bf16 v[80:83], v[190:193], v[214:217], v[80:83]
	v_mfma_f32_16x16x32_bf16 v[68:71], v[182:185], v[222:225], v[68:71]
	v_mfma_f32_16x16x32_bf16 v[64:67], v[190:193], v[222:225], v[64:67]
	s_barrier
	ds_read_b128 v[194:197], v159 offset:16384
	ds_read_b128 v[198:201], v159 offset:17408
	ds_read_b128 v[202:205], v159 offset:18432
	ds_read_b128 v[206:209], v159 offset:19456
	ds_read_b128 v[210:213], v159 offset:20480
	ds_read_b128 v[214:217], v159 offset:21504
	ds_read_b128 v[218:221], v159 offset:22528
	ds_read_b128 v[222:225], v159 offset:23552
	s_mov_b32 m0, s69
	s_nop 0
	global_load_lds_dwordx4 v130, s[36:37]
	s_add_i32 m0, s69, 0x2000
	s_add_i32 s69, s58, s40
	global_load_lds_dwordx4 v134, s[36:37]
	s_mov_b32 m0, s69
	s_nop 0
	global_load_lds_dwordx4 v130, s[70:71]
	s_add_i32 m0, s69, 0x2000
	s_nop 0
	global_load_lds_dwordx4 v134, s[70:71]
	s_mov_b32 m0, s31
	s_nop 0
	global_load_lds_dwordx4 v128, s[38:39]
	s_mov_b32 m0, s50
	s_nop 0
	global_load_lds_dwordx4 v132, s[38:39]
	s_waitcnt vmcnt(8)
	s_waitcnt lgkmcnt(0)
	s_barrier
	s_waitcnt lgkmcnt(0)
	v_mfma_f32_16x16x32_bf16 v[60:63], v[162:165], v[194:197], v[60:63]
	v_mfma_f32_16x16x32_bf16 v[56:59], v[170:173], v[194:197], v[56:59]
	v_mfma_f32_16x16x32_bf16 v[48:51], v[162:165], v[202:205], v[48:51]
	v_mfma_f32_16x16x32_bf16 v[40:43], v[170:173], v[202:205], v[40:43]
	s_add_i32 s69, 0, 0x18000
	v_mfma_f32_16x16x32_bf16 v[32:35], v[162:165], v[210:213], v[32:35]
	v_mfma_f32_16x16x32_bf16 v[24:27], v[170:173], v[210:213], v[24:27]
	v_mfma_f32_16x16x32_bf16 v[16:19], v[162:165], v[218:221], v[16:19]
	v_mfma_f32_16x16x32_bf16 v[8:11], v[170:173], v[218:221], v[8:11]
	s_add_i32 s70, 0, 0x1c000
	v_mfma_f32_16x16x32_bf16 v[60:63], v[166:169], v[198:201], v[60:63]
	v_mfma_f32_16x16x32_bf16 v[56:59], v[174:177], v[198:201], v[56:59]
	s_add_u32 s38, s38, 0x100000
	v_mfma_f32_16x16x32_bf16 v[48:51], v[166:169], v[206:209], v[48:51]
	v_mfma_f32_16x16x32_bf16 v[40:43], v[174:177], v[206:209], v[40:43]
	s_addc_u32 s39, s39, 0
	v_mfma_f32_16x16x32_bf16 v[32:35], v[166:169], v[214:217], v[32:35]
	v_mfma_f32_16x16x32_bf16 v[24:27], v[174:177], v[214:217], v[24:27]
	v_mfma_f32_16x16x32_bf16 v[16:19], v[166:169], v[222:225], v[16:19]
	v_mfma_f32_16x16x32_bf16 v[8:11], v[174:177], v[222:225], v[8:11]
	v_mfma_f32_16x16x32_bf16 v[52:55], v[178:181], v[194:197], v[52:55]
	v_mfma_f32_16x16x32_bf16 v[44:47], v[186:189], v[194:197], v[44:47]
	v_mfma_f32_16x16x32_bf16 v[36:39], v[178:181], v[202:205], v[36:39]
	v_mfma_f32_16x16x32_bf16 v[28:31], v[186:189], v[202:205], v[28:31]
	v_mfma_f32_16x16x32_bf16 v[20:23], v[178:181], v[210:213], v[20:23]
	v_mfma_f32_16x16x32_bf16 v[12:15], v[186:189], v[210:213], v[12:15]
	v_mfma_f32_16x16x32_bf16 v[4:7], v[178:181], v[218:221], v[4:7]
	v_mfma_f32_16x16x32_bf16 v[0:3], v[186:189], v[218:221], v[0:3]
	v_mfma_f32_16x16x32_bf16 v[52:55], v[182:185], v[198:201], v[52:55]
	v_mfma_f32_16x16x32_bf16 v[44:47], v[190:193], v[198:201], v[44:47]
	v_mfma_f32_16x16x32_bf16 v[36:39], v[182:185], v[206:209], v[36:39]
	v_mfma_f32_16x16x32_bf16 v[28:31], v[190:193], v[206:209], v[28:31]
	v_mfma_f32_16x16x32_bf16 v[20:23], v[182:185], v[214:217], v[20:23]
	v_mfma_f32_16x16x32_bf16 v[12:15], v[190:193], v[214:217], v[12:15]
	v_mfma_f32_16x16x32_bf16 v[4:7], v[182:185], v[222:225], v[4:7]
	v_mfma_f32_16x16x32_bf16 v[0:3], v[190:193], v[222:225], v[0:3]
	s_barrier
	ds_read_b128 v[194:197], v159 offset:32768
	ds_read_b128 v[198:201], v159 offset:33792
	ds_read_b128 v[202:205], v159 offset:34816
	ds_read_b128 v[206:209], v159 offset:35840
	ds_read_b128 v[210:213], v159 offset:36864
	ds_read_b128 v[214:217], v159 offset:37888
	ds_read_b128 v[218:221], v159 offset:38912
	ds_read_b128 v[222:225], v159 offset:39936
	ds_read_b128 v[162:165], v248
	ds_read_b128 v[166:169], v248 offset:1024
	ds_read_b128 v[170:173], v248 offset:2048
	ds_read_b128 v[174:177], v248 offset:3072
	ds_read_b128 v[178:181], v249
	ds_read_b128 v[182:185], v249 offset:1024
	ds_read_b128 v[186:189], v249 offset:2048
	ds_read_b128 v[190:193], v249 offset:3072
	s_mov_b32 m0, s51
	s_nop 0
	global_load_lds_dwordx4 v128, s[38:39]
	s_mov_b32 m0, s52
	s_nop 0
	global_load_lds_dwordx4 v132, s[38:39]
	s_waitcnt vmcnt(8)
	s_waitcnt lgkmcnt(0)
	s_barrier
	s_waitcnt lgkmcnt(0)
	v_mfma_f32_16x16x32_bf16 v[124:127], v[162:165], v[194:197], v[124:127]
	v_mfma_f32_16x16x32_bf16 v[120:123], v[170:173], v[194:197], v[120:123]
	v_mfma_f32_16x16x32_bf16 v[108:111], v[162:165], v[202:205], v[108:111]
	v_mfma_f32_16x16x32_bf16 v[104:107], v[170:173], v[202:205], v[104:107]
	s_add_i32 s38, s69, s40
	v_mfma_f32_16x16x32_bf16 v[92:95], v[162:165], v[210:213], v[92:95]
	v_mfma_f32_16x16x32_bf16 v[88:91], v[170:173], v[210:213], v[88:91]
	v_mfma_f32_16x16x32_bf16 v[76:79], v[162:165], v[218:221], v[76:79]
	v_mfma_f32_16x16x32_bf16 v[72:75], v[170:173], v[218:221], v[72:75]
	s_add_u32 s36, s36, 0x100080
	v_mfma_f32_16x16x32_bf16 v[124:127], v[166:169], v[198:201], v[124:127]
	v_mfma_f32_16x16x32_bf16 v[120:123], v[174:177], v[198:201], v[120:123]
	v_mfma_f32_16x16x32_bf16 v[108:111], v[166:169], v[206:209], v[108:111]
	v_mfma_f32_16x16x32_bf16 v[104:107], v[174:177], v[206:209], v[104:107]
	s_addc_u32 s37, s37, 0
	v_mfma_f32_16x16x32_bf16 v[92:95], v[166:169], v[214:217], v[92:95]
	v_mfma_f32_16x16x32_bf16 v[88:91], v[174:177], v[214:217], v[88:91]
	v_mfma_f32_16x16x32_bf16 v[76:79], v[166:169], v[222:225], v[76:79]
	v_mfma_f32_16x16x32_bf16 v[72:75], v[174:177], v[222:225], v[72:75]
	v_mfma_f32_16x16x32_bf16 v[116:119], v[178:181], v[194:197], v[116:119]
	v_mfma_f32_16x16x32_bf16 v[112:115], v[186:189], v[194:197], v[112:115]
	v_mfma_f32_16x16x32_bf16 v[100:103], v[178:181], v[202:205], v[100:103]
	v_mfma_f32_16x16x32_bf16 v[96:99], v[186:189], v[202:205], v[96:99]
	v_mfma_f32_16x16x32_bf16 v[84:87], v[178:181], v[210:213], v[84:87]
	v_mfma_f32_16x16x32_bf16 v[80:83], v[186:189], v[210:213], v[80:83]
	v_mfma_f32_16x16x32_bf16 v[68:71], v[178:181], v[218:221], v[68:71]
	v_mfma_f32_16x16x32_bf16 v[64:67], v[186:189], v[218:221], v[64:67]
	v_mfma_f32_16x16x32_bf16 v[116:119], v[182:185], v[198:201], v[116:119]
	v_mfma_f32_16x16x32_bf16 v[112:115], v[190:193], v[198:201], v[112:115]
	v_mfma_f32_16x16x32_bf16 v[100:103], v[182:185], v[206:209], v[100:103]
	v_mfma_f32_16x16x32_bf16 v[96:99], v[190:193], v[206:209], v[96:99]
	v_mfma_f32_16x16x32_bf16 v[84:87], v[182:185], v[214:217], v[84:87]
	v_mfma_f32_16x16x32_bf16 v[80:83], v[190:193], v[214:217], v[80:83]
	v_mfma_f32_16x16x32_bf16 v[68:71], v[182:185], v[222:225], v[68:71]
	v_mfma_f32_16x16x32_bf16 v[64:67], v[190:193], v[222:225], v[64:67]
	s_barrier
	ds_read_b128 v[194:197], v159 offset:49152
	ds_read_b128 v[198:201], v159 offset:50176
	ds_read_b128 v[202:205], v159 offset:51200
	ds_read_b128 v[206:209], v159 offset:52224
	ds_read_b128 v[210:213], v159 offset:53248
	ds_read_b128 v[214:217], v159 offset:54272
	ds_read_b128 v[218:221], v159 offset:55296
	ds_read_b128 v[222:225], v159 offset:56320
	s_mov_b32 m0, s38
	s_nop 0
	global_load_lds_dwordx4 v130, s[98:99]
	s_add_i32 m0, s38, 0x2000
	s_add_i32 s38, s70, s40
	global_load_lds_dwordx4 v134, s[98:99]
	s_mov_b32 m0, s38
	s_nop 0
	global_load_lds_dwordx4 v130, s[36:37]
	s_add_i32 m0, s38, 0x2000
	s_nop 0
	global_load_lds_dwordx4 v134, s[36:37]
	s_mov_b32 m0, s54
	s_nop 0
	global_load_lds_dwordx4 v128, s[100:101]
	s_mov_b32 m0, s55
	s_nop 0
	global_load_lds_dwordx4 v132, s[100:101]
	s_waitcnt vmcnt(8)
	s_waitcnt lgkmcnt(0)
	s_barrier
	s_waitcnt lgkmcnt(0)
	v_mfma_f32_16x16x32_bf16 v[60:63], v[162:165], v[194:197], v[60:63]
	v_mfma_f32_16x16x32_bf16 v[56:59], v[170:173], v[194:197], v[56:59]
	v_mfma_f32_16x16x32_bf16 v[48:51], v[162:165], v[202:205], v[48:51]
	v_mfma_f32_16x16x32_bf16 v[40:43], v[170:173], v[202:205], v[40:43]
	v_mfma_f32_16x16x32_bf16 v[32:35], v[162:165], v[210:213], v[32:35]
	v_mfma_f32_16x16x32_bf16 v[24:27], v[170:173], v[210:213], v[24:27]
	v_mfma_f32_16x16x32_bf16 v[16:19], v[162:165], v[218:221], v[16:19]
	v_mfma_f32_16x16x32_bf16 v[8:11], v[170:173], v[218:221], v[8:11]
	v_mfma_f32_16x16x32_bf16 v[60:63], v[166:169], v[198:201], v[60:63]
	v_mfma_f32_16x16x32_bf16 v[56:59], v[174:177], v[198:201], v[56:59]
	v_mfma_f32_16x16x32_bf16 v[48:51], v[166:169], v[206:209], v[48:51]
	v_mfma_f32_16x16x32_bf16 v[40:43], v[174:177], v[206:209], v[40:43]
	v_mfma_f32_16x16x32_bf16 v[32:35], v[166:169], v[214:217], v[32:35]
	v_mfma_f32_16x16x32_bf16 v[24:27], v[174:177], v[214:217], v[24:27]
	v_mfma_f32_16x16x32_bf16 v[16:19], v[166:169], v[222:225], v[16:19]
	v_mfma_f32_16x16x32_bf16 v[8:11], v[174:177], v[222:225], v[8:11]
	v_mfma_f32_16x16x32_bf16 v[52:55], v[178:181], v[194:197], v[52:55]
	v_mfma_f32_16x16x32_bf16 v[44:47], v[186:189], v[194:197], v[44:47]
	v_mfma_f32_16x16x32_bf16 v[36:39], v[178:181], v[202:205], v[36:39]
	v_mfma_f32_16x16x32_bf16 v[28:31], v[186:189], v[202:205], v[28:31]
	v_mfma_f32_16x16x32_bf16 v[20:23], v[178:181], v[210:213], v[20:23]
	v_mfma_f32_16x16x32_bf16 v[12:15], v[186:189], v[210:213], v[12:15]
	v_mfma_f32_16x16x32_bf16 v[4:7], v[178:181], v[218:221], v[4:7]
	v_mfma_f32_16x16x32_bf16 v[0:3], v[186:189], v[218:221], v[0:3]
	v_mfma_f32_16x16x32_bf16 v[52:55], v[182:185], v[198:201], v[52:55]
	v_mfma_f32_16x16x32_bf16 v[44:47], v[190:193], v[198:201], v[44:47]
	v_mfma_f32_16x16x32_bf16 v[36:39], v[182:185], v[206:209], v[36:39]
	v_mfma_f32_16x16x32_bf16 v[28:31], v[190:193], v[206:209], v[28:31]
	v_mfma_f32_16x16x32_bf16 v[20:23], v[182:185], v[214:217], v[20:23]
	v_mfma_f32_16x16x32_bf16 v[12:15], v[190:193], v[214:217], v[12:15]
	v_mfma_f32_16x16x32_bf16 v[4:7], v[182:185], v[222:225], v[4:7]
	v_mfma_f32_16x16x32_bf16 v[0:3], v[190:193], v[222:225], v[0:3]
	s_barrier
	s_add_i32 s68, s68, 2
	s_add_u32 s66, s66, 0x100
	s_addc_u32 s67, s67, 0
	s_add_u32 s34, s34, 0x100
	s_addc_u32 s35, s35, 0
	s_cmp_gt_u32 s68, 61
	s_cbranch_scc0 .LBB0_233
	s_setprio 0
	s_and_b64 vcc, exec, s[14:15]
	s_cbranch_vccz .LBB0_236
	s_barrier

.LBB0_253:
	s_add_u32 s65, s26, 0x100
	v_mov_b32_e32 v0, 0
	s_addc_u32 s66, s27, 0
	s_mov_b32 s67, -2
	v_mov_b32_e32 v1, v0
	v_mov_b32_e32 v2, v0
	v_mov_b32_e32 v3, v0
	v_mov_b32_e32 v4, v0
	v_mov_b32_e32 v5, v0
	v_mov_b32_e32 v6, v0
	v_mov_b32_e32 v7, v0
	v_mov_b32_e32 v8, v0
	v_mov_b32_e32 v9, v0
	v_mov_b32_e32 v10, v0
	v_mov_b32_e32 v11, v0
	v_mov_b32_e32 v16, v0
	v_mov_b32_e32 v17, v0
	v_mov_b32_e32 v18, v0
	v_mov_b32_e32 v19, v0
	v_mov_b32_e32 v24, v0
	v_mov_b32_e32 v25, v0
	v_mov_b32_e32 v26, v0
	v_mov_b32_e32 v27, v0
	v_mov_b32_e32 v32, v0
	v_mov_b32_e32 v33, v0
	v_mov_b32_e32 v34, v0
	v_mov_b32_e32 v35, v0
	v_mov_b32_e32 v40, v0
	v_mov_b32_e32 v41, v0
	v_mov_b32_e32 v42, v0
	v_mov_b32_e32 v43, v0
	v_mov_b32_e32 v48, v0
	v_mov_b32_e32 v49, v0
	v_mov_b32_e32 v50, v0
	v_mov_b32_e32 v51, v0
	v_mov_b32_e32 v12, v0
	v_mov_b32_e32 v13, v0
	v_mov_b32_e32 v14, v0
	v_mov_b32_e32 v15, v0
	v_mov_b32_e32 v20, v0
	v_mov_b32_e32 v21, v0
	v_mov_b32_e32 v22, v0
	v_mov_b32_e32 v23, v0
	v_mov_b32_e32 v28, v0
	v_mov_b32_e32 v29, v0
	v_mov_b32_e32 v30, v0
	v_mov_b32_e32 v31, v0
	v_mov_b32_e32 v36, v0
	v_mov_b32_e32 v37, v0
	v_mov_b32_e32 v38, v0
	v_mov_b32_e32 v39, v0
	v_mov_b32_e32 v44, v0
	v_mov_b32_e32 v45, v0
	v_mov_b32_e32 v46, v0
	v_mov_b32_e32 v47, v0
	v_mov_b32_e32 v52, v0
	v_mov_b32_e32 v53, v0
	v_mov_b32_e32 v54, v0
	v_mov_b32_e32 v55, v0
	v_mov_b32_e32 v56, v0
	v_mov_b32_e32 v57, v0
	v_mov_b32_e32 v58, v0
	v_mov_b32_e32 v59, v0
	v_mov_b32_e32 v60, v0
	v_mov_b32_e32 v61, v0
	v_mov_b32_e32 v62, v0
	v_mov_b32_e32 v63, v0
	v_mov_b32_e32 v64, v0
	v_mov_b32_e32 v65, v0
	v_mov_b32_e32 v66, v0
	v_mov_b32_e32 v67, v0
	v_mov_b32_e32 v68, v0
	v_mov_b32_e32 v69, v0
	v_mov_b32_e32 v70, v0
	v_mov_b32_e32 v71, v0
	v_mov_b32_e32 v72, v0
	v_mov_b32_e32 v73, v0
	v_mov_b32_e32 v74, v0
	v_mov_b32_e32 v75, v0
	v_mov_b32_e32 v80, v0
	v_mov_b32_e32 v81, v0
	v_mov_b32_e32 v82, v0
	v_mov_b32_e32 v83, v0
	v_mov_b32_e32 v88, v0
	v_mov_b32_e32 v89, v0
	v_mov_b32_e32 v90, v0
	v_mov_b32_e32 v91, v0
	v_mov_b32_e32 v96, v0
	v_mov_b32_e32 v97, v0
	v_mov_b32_e32 v98, v0
	v_mov_b32_e32 v99, v0
	v_mov_b32_e32 v104, v0
	v_mov_b32_e32 v105, v0
	v_mov_b32_e32 v106, v0
	v_mov_b32_e32 v107, v0
	v_mov_b32_e32 v112, v0
	v_mov_b32_e32 v113, v0
	v_mov_b32_e32 v114, v0
	v_mov_b32_e32 v115, v0
	v_mov_b32_e32 v76, v0
	v_mov_b32_e32 v77, v0
	v_mov_b32_e32 v78, v0
	v_mov_b32_e32 v79, v0
	v_mov_b32_e32 v84, v0
	v_mov_b32_e32 v85, v0
	v_mov_b32_e32 v86, v0
	v_mov_b32_e32 v87, v0
	v_mov_b32_e32 v92, v0
	v_mov_b32_e32 v93, v0
	v_mov_b32_e32 v94, v0
	v_mov_b32_e32 v95, v0
	v_mov_b32_e32 v100, v0
	v_mov_b32_e32 v101, v0
	v_mov_b32_e32 v102, v0
	v_mov_b32_e32 v103, v0
	v_mov_b32_e32 v108, v0
	v_mov_b32_e32 v109, v0
	v_mov_b32_e32 v110, v0
	v_mov_b32_e32 v111, v0
	v_mov_b32_e32 v116, v0
	v_mov_b32_e32 v117, v0
	v_mov_b32_e32 v118, v0
	v_mov_b32_e32 v119, v0
	v_mov_b32_e32 v120, v0
	v_mov_b32_e32 v121, v0
	v_mov_b32_e32 v122, v0
	v_mov_b32_e32 v123, v0
	v_mov_b32_e32 v124, v0
	v_mov_b32_e32 v125, v0
	v_mov_b32_e32 v126, v0
	v_mov_b32_e32 v127, v0
	v_add_u32_e32 v248, 0x18000, v147
	v_add_u32_e32 v249, 0x1c000, v147
	s_cmp_lt_u32 s81, 4
	s_cbranch_scc0 .Lsp_skip1
	s_setprio 1
.Lsp_skip1:
.LBB0_254:
	ds_read_b128 v[152:155], v149
	ds_read_b128 v[156:159], v149 offset:1024
	ds_read_b128 v[160:163], v149 offset:2048
	ds_read_b128 v[164:167], v149 offset:3072
	ds_read_b128 v[168:171], v150
	ds_read_b128 v[172:175], v150 offset:1024
	ds_read_b128 v[176:179], v150 offset:2048
	ds_read_b128 v[180:183], v150 offset:3072
	ds_read_b128 v[184:187], v151
	ds_read_b128 v[188:191], v151 offset:1024
	ds_read_b128 v[192:195], v151 offset:2048
	ds_read_b128 v[196:199], v151 offset:3072
	ds_read_b128 v[200:203], v151 offset:4096
	ds_read_b128 v[204:207], v151 offset:5120
	ds_read_b128 v[208:211], v151 offset:6144
	ds_read_b128 v[212:215], v151 offset:7168
	s_add_u32 s26, s24, 0x100
	s_addc_u32 s27, s25, 0
	s_cmp_eq_u32 s67, 8
	s_cselect_b32 s31, s1, s27
	s_cselect_b32 s30, s0, s26
	s_cselect_b32 s29, s23, s66
	s_cselect_b32 s28, s22, s65
	s_add_i32 m0, s46, 0xc000
	s_nop 0
	global_load_lds_dwordx4 v138, s[24:25]
	s_add_i32 m0, s46, 0xe000
	s_nop 0
	global_load_lds_dwordx4 v136, s[24:25]
	s_waitcnt vmcnt(8)
	s_waitcnt lgkmcnt(0)
	s_barrier
	s_waitcnt lgkmcnt(0)
	v_mfma_f32_16x16x32_bf16 v[124:127], v[152:155], v[184:187], v[124:127]
	v_mfma_f32_16x16x32_bf16 v[120:123], v[160:163], v[184:187], v[120:123]
	v_mfma_f32_16x16x32_bf16 v[116:119], v[152:155], v[192:195], v[116:119]
	v_mfma_f32_16x16x32_bf16 v[108:111], v[160:163], v[192:195], v[108:111]
	s_add_u32 s98, s28, s10
	s_addc_u32 s99, s29, s11
	s_add_i32 s24, s55, s40
	v_mfma_f32_16x16x32_bf16 v[100:103], v[152:155], v[200:203], v[100:103]
	s_add_u32 s100, s30, s10
	s_addc_u32 s101, s31, s11
	v_mfma_f32_16x16x32_bf16 v[92:95], v[160:163], v[200:203], v[92:95]
	v_mfma_f32_16x16x32_bf16 v[84:87], v[152:155], v[208:211], v[84:87]
	v_mfma_f32_16x16x32_bf16 v[76:79], v[160:163], v[208:211], v[76:79]
	v_mfma_f32_16x16x32_bf16 v[124:127], v[156:159], v[188:191], v[124:127]
	v_mfma_f32_16x16x32_bf16 v[120:123], v[164:167], v[188:191], v[120:123]
	s_add_i32 s68, s56, s40
	v_mfma_f32_16x16x32_bf16 v[116:119], v[156:159], v[196:199], v[116:119]
	v_mfma_f32_16x16x32_bf16 v[108:111], v[164:167], v[196:199], v[108:111]
	v_mfma_f32_16x16x32_bf16 v[100:103], v[156:159], v[204:207], v[100:103]
	v_mfma_f32_16x16x32_bf16 v[92:95], v[164:167], v[204:207], v[92:95]
	v_mfma_f32_16x16x32_bf16 v[84:87], v[156:159], v[212:215], v[84:87]
	v_mfma_f32_16x16x32_bf16 v[76:79], v[164:167], v[212:215], v[76:79]
	v_mfma_f32_16x16x32_bf16 v[112:115], v[168:171], v[184:187], v[112:115]
	v_mfma_f32_16x16x32_bf16 v[104:107], v[176:179], v[184:187], v[104:107]
	v_mfma_f32_16x16x32_bf16 v[96:99], v[168:171], v[192:195], v[96:99]
	v_mfma_f32_16x16x32_bf16 v[88:91], v[176:179], v[192:195], v[88:91]
	v_mfma_f32_16x16x32_bf16 v[80:83], v[168:171], v[200:203], v[80:83]
	v_mfma_f32_16x16x32_bf16 v[72:75], v[176:179], v[200:203], v[72:75]
	v_mfma_f32_16x16x32_bf16 v[68:71], v[168:171], v[208:211], v[68:71]
	v_mfma_f32_16x16x32_bf16 v[64:67], v[176:179], v[208:211], v[64:67]
	v_mfma_f32_16x16x32_bf16 v[112:115], v[172:175], v[188:191], v[112:115]
	v_mfma_f32_16x16x32_bf16 v[104:107], v[180:183], v[188:191], v[104:107]
	v_mfma_f32_16x16x32_bf16 v[96:99], v[172:175], v[196:199], v[96:99]
	v_mfma_f32_16x16x32_bf16 v[88:91], v[180:183], v[196:199], v[88:91]
	v_mfma_f32_16x16x32_bf16 v[80:83], v[172:175], v[204:207], v[80:83]
	v_mfma_f32_16x16x32_bf16 v[72:75], v[180:183], v[204:207], v[72:75]
	v_mfma_f32_16x16x32_bf16 v[68:71], v[172:175], v[212:215], v[68:71]
	v_mfma_f32_16x16x32_bf16 v[64:67], v[180:183], v[212:215], v[64:67]
	s_barrier
	ds_read_b128 v[184:187], v151 offset:16384
	ds_read_b128 v[188:191], v151 offset:17408
	ds_read_b128 v[192:195], v151 offset:18432
	ds_read_b128 v[196:199], v151 offset:19456
	ds_read_b128 v[200:203], v151 offset:20480
	ds_read_b128 v[204:207], v151 offset:21504
	ds_read_b128 v[208:211], v151 offset:22528
	ds_read_b128 v[212:215], v151 offset:23552
	s_mov_b32 m0, s24
	s_nop 0
	global_load_lds_dwordx4 v132, s[28:29]
	s_add_i32 m0, s24, 0x2000
	s_add_u32 s24, s28, 0x30000
	s_addc_u32 s25, s29, 0
	global_load_lds_dwordx4 v128, s[28:29]
	s_mov_b32 m0, s68
	s_nop 0
	global_load_lds_dwordx4 v132, s[24:25]
	s_add_i32 m0, s68, 0x2000
	s_nop 0
	global_load_lds_dwordx4 v128, s[24:25]
	s_mov_b32 m0, s46
	s_nop 0
	global_load_lds_dwordx4 v134, s[30:31]
	s_mov_b32 m0, s47
	s_nop 0
	global_load_lds_dwordx4 v130, s[30:31]
	s_waitcnt vmcnt(8)
	s_waitcnt lgkmcnt(0)
	s_barrier
	s_waitcnt lgkmcnt(0)
	v_mfma_f32_16x16x32_bf16 v[60:63], v[152:155], v[184:187], v[60:63]
	v_mfma_f32_16x16x32_bf16 v[56:59], v[160:163], v[184:187], v[56:59]
	v_mfma_f32_16x16x32_bf16 v[52:55], v[152:155], v[192:195], v[52:55]
	v_mfma_f32_16x16x32_bf16 v[44:47], v[160:163], v[192:195], v[44:47]
	s_add_i32 s68, 0, 0x18000
	v_mfma_f32_16x16x32_bf16 v[36:39], v[152:155], v[200:203], v[36:39]
	v_mfma_f32_16x16x32_bf16 v[28:31], v[160:163], v[200:203], v[28:31]
	s_add_i32 s69, 0, 0x1c000
	v_mfma_f32_16x16x32_bf16 v[20:23], v[152:155], v[208:211], v[20:23]
	v_mfma_f32_16x16x32_bf16 v[12:15], v[160:163], v[208:211], v[12:15]
	s_add_u32 s24, s30, 0xc0000
	v_mfma_f32_16x16x32_bf16 v[60:63], v[156:159], v[188:191], v[60:63]
	v_mfma_f32_16x16x32_bf16 v[56:59], v[164:167], v[188:191], v[56:59]
	s_addc_u32 s25, s31, 0
	v_mfma_f32_16x16x32_bf16 v[52:55], v[156:159], v[196:199], v[52:55]
	v_mfma_f32_16x16x32_bf16 v[44:47], v[164:167], v[196:199], v[44:47]
	v_mfma_f32_16x16x32_bf16 v[36:39], v[156:159], v[204:207], v[36:39]
	v_mfma_f32_16x16x32_bf16 v[28:31], v[164:167], v[204:207], v[28:31]
	v_mfma_f32_16x16x32_bf16 v[20:23], v[156:159], v[212:215], v[20:23]
	v_mfma_f32_16x16x32_bf16 v[12:15], v[164:167], v[212:215], v[12:15]
	v_mfma_f32_16x16x32_bf16 v[48:51], v[168:171], v[184:187], v[48:51]
	v_mfma_f32_16x16x32_bf16 v[40:43], v[176:179], v[184:187], v[40:43]
	v_mfma_f32_16x16x32_bf16 v[32:35], v[168:171], v[192:195], v[32:35]
	v_mfma_f32_16x16x32_bf16 v[24:27], v[176:179], v[192:195], v[24:27]
	v_mfma_f32_16x16x32_bf16 v[16:19], v[168:171], v[200:203], v[16:19]
	v_mfma_f32_16x16x32_bf16 v[8:11], v[176:179], v[200:203], v[8:11]
	v_mfma_f32_16x16x32_bf16 v[4:7], v[168:171], v[208:211], v[4:7]
	v_mfma_f32_16x16x32_bf16 v[0:3], v[176:179], v[208:211], v[0:3]
	v_mfma_f32_16x16x32_bf16 v[48:51], v[172:175], v[188:191], v[48:51]
	v_mfma_f32_16x16x32_bf16 v[40:43], v[180:183], v[188:191], v[40:43]
	v_mfma_f32_16x16x32_bf16 v[32:35], v[172:175], v[196:199], v[32:35]
	v_mfma_f32_16x16x32_bf16 v[24:27], v[180:183], v[196:199], v[24:27]
	v_mfma_f32_16x16x32_bf16 v[16:19], v[172:175], v[204:207], v[16:19]
	v_mfma_f32_16x16x32_bf16 v[8:11], v[180:183], v[204:207], v[8:11]
	v_mfma_f32_16x16x32_bf16 v[4:7], v[172:175], v[212:215], v[4:7]
	v_mfma_f32_16x16x32_bf16 v[0:3], v[180:183], v[212:215], v[0:3]
	s_barrier
	ds_read_b128 v[184:187], v151 offset:32768
	ds_read_b128 v[188:191], v151 offset:33792
	ds_read_b128 v[192:195], v151 offset:34816
	ds_read_b128 v[196:199], v151 offset:35840
	ds_read_b128 v[200:203], v151 offset:36864
	ds_read_b128 v[204:207], v151 offset:37888
	ds_read_b128 v[208:211], v151 offset:38912
	ds_read_b128 v[212:215], v151 offset:39936
	ds_read_b128 v[152:155], v248
	ds_read_b128 v[156:159], v248 offset:1024
	ds_read_b128 v[160:163], v248 offset:2048
	ds_read_b128 v[164:167], v248 offset:3072
	ds_read_b128 v[168:171], v249
	ds_read_b128 v[172:175], v249 offset:1024
	ds_read_b128 v[176:179], v249 offset:2048
	ds_read_b128 v[180:183], v249 offset:3072
	s_mov_b32 m0, s48
	s_nop 0
	global_load_lds_dwordx4 v134, s[24:25]
	s_mov_b32 m0, s49
	s_nop 0
	global_load_lds_dwordx4 v130, s[24:25]
	s_waitcnt vmcnt(8)
	s_waitcnt lgkmcnt(0)
	s_barrier
	s_waitcnt lgkmcnt(0)
	v_mfma_f32_16x16x32_bf16 v[124:127], v[152:155], v[184:187], v[124:127]
	v_mfma_f32_16x16x32_bf16 v[120:123], v[160:163], v[184:187], v[120:123]
	v_mfma_f32_16x16x32_bf16 v[116:119], v[152:155], v[192:195], v[116:119]
	v_mfma_f32_16x16x32_bf16 v[108:111], v[160:163], v[192:195], v[108:111]
	s_add_i32 s24, s68, s40
	v_mfma_f32_16x16x32_bf16 v[100:103], v[152:155], v[200:203], v[100:103]
	v_mfma_f32_16x16x32_bf16 v[92:95], v[160:163], v[200:203], v[92:95]
	v_mfma_f32_16x16x32_bf16 v[84:87], v[152:155], v[208:211], v[84:87]
	v_mfma_f32_16x16x32_bf16 v[76:79], v[160:163], v[208:211], v[76:79]
	v_mfma_f32_16x16x32_bf16 v[124:127], v[156:159], v[188:191], v[124:127]
	v_mfma_f32_16x16x32_bf16 v[120:123], v[164:167], v[188:191], v[120:123]
	v_mfma_f32_16x16x32_bf16 v[116:119], v[156:159], v[196:199], v[116:119]
	v_mfma_f32_16x16x32_bf16 v[108:111], v[164:167], v[196:199], v[108:111]
	v_mfma_f32_16x16x32_bf16 v[100:103], v[156:159], v[204:207], v[100:103]
	v_mfma_f32_16x16x32_bf16 v[92:95], v[164:167], v[204:207], v[92:95]
	v_mfma_f32_16x16x32_bf16 v[84:87], v[156:159], v[212:215], v[84:87]
	v_mfma_f32_16x16x32_bf16 v[76:79], v[164:167], v[212:215], v[76:79]
	v_mfma_f32_16x16x32_bf16 v[112:115], v[168:171], v[184:187], v[112:115]
	v_mfma_f32_16x16x32_bf16 v[104:107], v[176:179], v[184:187], v[104:107]
	v_mfma_f32_16x16x32_bf16 v[96:99], v[168:171], v[192:195], v[96:99]
	v_mfma_f32_16x16x32_bf16 v[88:91], v[176:179], v[192:195], v[88:91]
	v_mfma_f32_16x16x32_bf16 v[80:83], v[168:171], v[200:203], v[80:83]
	v_mfma_f32_16x16x32_bf16 v[72:75], v[176:179], v[200:203], v[72:75]
	v_mfma_f32_16x16x32_bf16 v[68:71], v[168:171], v[208:211], v[68:71]
	v_mfma_f32_16x16x32_bf16 v[64:67], v[176:179], v[208:211], v[64:67]
	v_mfma_f32_16x16x32_bf16 v[112:115], v[172:175], v[188:191], v[112:115]
	v_mfma_f32_16x16x32_bf16 v[104:107], v[180:183], v[188:191], v[104:107]
	v_mfma_f32_16x16x32_bf16 v[96:99], v[172:175], v[196:199], v[96:99]
	v_mfma_f32_16x16x32_bf16 v[88:91], v[180:183], v[196:199], v[88:91]
	v_mfma_f32_16x16x32_bf16 v[80:83], v[172:175], v[204:207], v[80:83]
	v_mfma_f32_16x16x32_bf16 v[72:75], v[180:183], v[204:207], v[72:75]
	v_mfma_f32_16x16x32_bf16 v[68:71], v[172:175], v[212:215], v[68:71]
	v_mfma_f32_16x16x32_bf16 v[64:67], v[180:183], v[212:215], v[64:67]
	s_barrier
	ds_read_b128 v[184:187], v151 offset:49152
	ds_read_b128 v[188:191], v151 offset:50176
	ds_read_b128 v[192:195], v151 offset:51200
	ds_read_b128 v[196:199], v151 offset:52224
	ds_read_b128 v[200:203], v151 offset:53248
	ds_read_b128 v[204:207], v151 offset:54272
	ds_read_b128 v[208:211], v151 offset:55296
	ds_read_b128 v[212:215], v151 offset:56320
	s_mov_b32 m0, s24
	s_nop 0
	global_load_lds_dwordx4 v132, s[98:99]
	s_add_i32 m0, s24, 0x2000
	s_add_u32 s24, s28, 0x30080
	s_addc_u32 s25, s29, 0
	s_add_i32 s28, s69, s40
	global_load_lds_dwordx4 v128, s[98:99]
	s_mov_b32 m0, s28
	s_nop 0
	global_load_lds_dwordx4 v132, s[24:25]
	s_add_i32 m0, s28, 0x2000
	s_nop 0
	global_load_lds_dwordx4 v128, s[24:25]
	s_mov_b32 m0, s52
	s_nop 0
	global_load_lds_dwordx4 v134, s[100:101]
	s_mov_b32 m0, s53
	s_nop 0
	global_load_lds_dwordx4 v130, s[100:101]
	s_waitcnt vmcnt(8)
	s_waitcnt lgkmcnt(0)
	s_barrier
	s_waitcnt lgkmcnt(0)
	v_mfma_f32_16x16x32_bf16 v[60:63], v[152:155], v[184:187], v[60:63]
	v_mfma_f32_16x16x32_bf16 v[56:59], v[160:163], v[184:187], v[56:59]
	v_mfma_f32_16x16x32_bf16 v[52:55], v[152:155], v[192:195], v[52:55]
	v_mfma_f32_16x16x32_bf16 v[44:47], v[160:163], v[192:195], v[44:47]
	v_mfma_f32_16x16x32_bf16 v[36:39], v[152:155], v[200:203], v[36:39]
	v_mfma_f32_16x16x32_bf16 v[28:31], v[160:163], v[200:203], v[28:31]
	v_mfma_f32_16x16x32_bf16 v[20:23], v[152:155], v[208:211], v[20:23]
	v_mfma_f32_16x16x32_bf16 v[12:15], v[160:163], v[208:211], v[12:15]
	v_mfma_f32_16x16x32_bf16 v[60:63], v[156:159], v[188:191], v[60:63]
	v_mfma_f32_16x16x32_bf16 v[56:59], v[164:167], v[188:191], v[56:59]
	v_mfma_f32_16x16x32_bf16 v[52:55], v[156:159], v[196:199], v[52:55]
	v_mfma_f32_16x16x32_bf16 v[44:47], v[164:167], v[196:199], v[44:47]
	v_mfma_f32_16x16x32_bf16 v[36:39], v[156:159], v[204:207], v[36:39]
	v_mfma_f32_16x16x32_bf16 v[28:31], v[164:167], v[204:207], v[28:31]
	v_mfma_f32_16x16x32_bf16 v[20:23], v[156:159], v[212:215], v[20:23]
	v_mfma_f32_16x16x32_bf16 v[12:15], v[164:167], v[212:215], v[12:15]
	v_mfma_f32_16x16x32_bf16 v[48:51], v[168:171], v[184:187], v[48:51]
	v_mfma_f32_16x16x32_bf16 v[40:43], v[176:179], v[184:187], v[40:43]
	v_mfma_f32_16x16x32_bf16 v[32:35], v[168:171], v[192:195], v[32:35]
	v_mfma_f32_16x16x32_bf16 v[24:27], v[176:179], v[192:195], v[24:27]
	v_mfma_f32_16x16x32_bf16 v[16:19], v[168:171], v[200:203], v[16:19]
	v_mfma_f32_16x16x32_bf16 v[8:11], v[176:179], v[200:203], v[8:11]
	v_mfma_f32_16x16x32_bf16 v[4:7], v[168:171], v[208:211], v[4:7]
	v_mfma_f32_16x16x32_bf16 v[0:3], v[176:179], v[208:211], v[0:3]
	v_mfma_f32_16x16x32_bf16 v[48:51], v[172:175], v[188:191], v[48:51]
	v_mfma_f32_16x16x32_bf16 v[40:43], v[180:183], v[188:191], v[40:43]
	v_mfma_f32_16x16x32_bf16 v[32:35], v[172:175], v[196:199], v[32:35]
	v_mfma_f32_16x16x32_bf16 v[24:27], v[180:183], v[196:199], v[24:27]
	v_mfma_f32_16x16x32_bf16 v[16:19], v[172:175], v[204:207], v[16:19]
	v_mfma_f32_16x16x32_bf16 v[8:11], v[180:183], v[204:207], v[8:11]
	v_mfma_f32_16x16x32_bf16 v[4:7], v[172:175], v[212:215], v[4:7]
	v_mfma_f32_16x16x32_bf16 v[0:3], v[180:183], v[212:215], v[0:3]
	s_barrier
	s_add_i32 s67, s67, 2
	s_add_u32 s65, s65, 0x100
	s_addc_u32 s66, s66, 0
	s_cmp_gt_u32 s67, 9
	s_mov_b64 s[24:25], s[26:27]
	s_cbranch_scc0 .LBB0_254
	s_setprio 0
	s_and_b64 vcc, exec, s[12:13]
	s_cbranch_vccz .LBB0_257
	s_barrier

.LBB0_280:
	s_ashr_i32 s23, s22, 31
	s_lshl_b64 s[24:25], s[22:23], 20
	s_add_u32 s24, s39, s24
	s_addc_u32 s25, s45, s25
	s_and_b64 s[26:27], s[2:3], exec
	s_cselect_b32 s23, s25, s35
	s_cselect_b32 s57, s24, s34
	s_ashr_i32 s21, s20, 31
	s_lshl_b64 s[26:27], s[20:21], 20
	s_add_u32 s26, s46, s26
	s_addc_u32 s27, s47, s27
	s_and_b64 s[36:37], s[2:3], exec
	s_cselect_b32 s21, s27, s31
	s_cselect_b32 s58, s26, s30
	s_add_u32 s59, s30, 0x100
	s_addc_u32 s60, s31, 0
	s_add_u32 s30, s34, 0x80080
	v_mov_b32_e32 v0, 0
	s_addc_u32 s31, s35, 0
	s_mov_b32 s61, -2
	v_mov_b32_e32 v1, v0
	v_mov_b32_e32 v2, v0
	v_mov_b32_e32 v3, v0
	v_mov_b32_e32 v4, v0
	v_mov_b32_e32 v5, v0
	v_mov_b32_e32 v6, v0
	v_mov_b32_e32 v7, v0
	v_mov_b32_e32 v16, v0
	v_mov_b32_e32 v17, v0
	v_mov_b32_e32 v18, v0
	v_mov_b32_e32 v19, v0
	v_mov_b32_e32 v20, v0
	v_mov_b32_e32 v21, v0
	v_mov_b32_e32 v22, v0
	v_mov_b32_e32 v23, v0
	v_mov_b32_e32 v32, v0
	v_mov_b32_e32 v33, v0
	v_mov_b32_e32 v34, v0
	v_mov_b32_e32 v35, v0
	v_mov_b32_e32 v36, v0
	v_mov_b32_e32 v37, v0
	v_mov_b32_e32 v38, v0
	v_mov_b32_e32 v39, v0
	v_mov_b32_e32 v48, v0
	v_mov_b32_e32 v49, v0
	v_mov_b32_e32 v50, v0
	v_mov_b32_e32 v51, v0
	v_mov_b32_e32 v52, v0
	v_mov_b32_e32 v53, v0
	v_mov_b32_e32 v54, v0
	v_mov_b32_e32 v55, v0
	v_mov_b32_e32 v8, v0
	v_mov_b32_e32 v9, v0
	v_mov_b32_e32 v10, v0
	v_mov_b32_e32 v11, v0
	v_mov_b32_e32 v12, v0
	v_mov_b32_e32 v13, v0
	v_mov_b32_e32 v14, v0
	v_mov_b32_e32 v15, v0
	v_mov_b32_e32 v24, v0
	v_mov_b32_e32 v25, v0
	v_mov_b32_e32 v26, v0
	v_mov_b32_e32 v27, v0
	v_mov_b32_e32 v28, v0
	v_mov_b32_e32 v29, v0
	v_mov_b32_e32 v30, v0
	v_mov_b32_e32 v31, v0
	v_mov_b32_e32 v40, v0
	v_mov_b32_e32 v41, v0
	v_mov_b32_e32 v42, v0
	v_mov_b32_e32 v43, v0
	v_mov_b32_e32 v44, v0
	v_mov_b32_e32 v45, v0
	v_mov_b32_e32 v46, v0
	v_mov_b32_e32 v47, v0
	v_mov_b32_e32 v56, v0
	v_mov_b32_e32 v57, v0
	v_mov_b32_e32 v58, v0
	v_mov_b32_e32 v59, v0
	v_mov_b32_e32 v60, v0
	v_mov_b32_e32 v61, v0
	v_mov_b32_e32 v62, v0
	v_mov_b32_e32 v63, v0
	v_mov_b32_e32 v64, v0
	v_mov_b32_e32 v65, v0
	v_mov_b32_e32 v66, v0
	v_mov_b32_e32 v67, v0
	v_mov_b32_e32 v68, v0
	v_mov_b32_e32 v69, v0
	v_mov_b32_e32 v70, v0
	v_mov_b32_e32 v71, v0
	v_mov_b32_e32 v80, v0
	v_mov_b32_e32 v81, v0
	v_mov_b32_e32 v82, v0
	v_mov_b32_e32 v83, v0
	v_mov_b32_e32 v84, v0
	v_mov_b32_e32 v85, v0
	v_mov_b32_e32 v86, v0
	v_mov_b32_e32 v87, v0
	v_mov_b32_e32 v96, v0
	v_mov_b32_e32 v97, v0
	v_mov_b32_e32 v98, v0
	v_mov_b32_e32 v99, v0
	v_mov_b32_e32 v100, v0
	v_mov_b32_e32 v101, v0
	v_mov_b32_e32 v102, v0
	v_mov_b32_e32 v103, v0
	v_mov_b32_e32 v112, v0
	v_mov_b32_e32 v113, v0
	v_mov_b32_e32 v114, v0
	v_mov_b32_e32 v115, v0
	v_mov_b32_e32 v116, v0
	v_mov_b32_e32 v117, v0
	v_mov_b32_e32 v118, v0
	v_mov_b32_e32 v119, v0
	v_mov_b32_e32 v72, v0
	v_mov_b32_e32 v73, v0
	v_mov_b32_e32 v74, v0
	v_mov_b32_e32 v75, v0
	v_mov_b32_e32 v76, v0
	v_mov_b32_e32 v77, v0
	v_mov_b32_e32 v78, v0
	v_mov_b32_e32 v79, v0
	v_mov_b32_e32 v88, v0
	v_mov_b32_e32 v89, v0
	v_mov_b32_e32 v90, v0
	v_mov_b32_e32 v91, v0
	v_mov_b32_e32 v92, v0
	v_mov_b32_e32 v93, v0
	v_mov_b32_e32 v94, v0
	v_mov_b32_e32 v95, v0
	v_mov_b32_e32 v104, v0
	v_mov_b32_e32 v105, v0
	v_mov_b32_e32 v106, v0
	v_mov_b32_e32 v107, v0
	v_mov_b32_e32 v108, v0
	v_mov_b32_e32 v109, v0
	v_mov_b32_e32 v110, v0
	v_mov_b32_e32 v111, v0
	v_mov_b32_e32 v120, v0
	v_mov_b32_e32 v121, v0
	v_mov_b32_e32 v122, v0
	v_mov_b32_e32 v123, v0
	v_mov_b32_e32 v124, v0
	v_mov_b32_e32 v125, v0
	v_mov_b32_e32 v126, v0
	v_mov_b32_e32 v127, v0
	v_add_u32_e32 v248, 0x18000, v151
	v_add_u32_e32 v249, 0x1c000, v151
	s_cmp_lt_u32 s81, 4
	s_cbranch_scc0 .Lsp_skip2
	s_setprio 1
.Lsp_skip2:
.LBB0_281:
	ds_read_b128 v[144:147], v153
	ds_read_b128 v[156:159], v153 offset:1024
	ds_read_b128 v[160:163], v153 offset:2048
	ds_read_b128 v[164:167], v153 offset:3072
	ds_read_b128 v[168:171], v154
	ds_read_b128 v[172:175], v154 offset:1024
	ds_read_b128 v[176:179], v154 offset:2048
	ds_read_b128 v[180:183], v154 offset:3072
	ds_read_b128 v[184:187], v155
	ds_read_b128 v[188:191], v155 offset:1024
	ds_read_b128 v[192:195], v155 offset:2048
	ds_read_b128 v[196:199], v155 offset:3072
	ds_read_b128 v[200:203], v155 offset:4096
	ds_read_b128 v[204:207], v155 offset:5120
	ds_read_b128 v[208:211], v155 offset:6144
	ds_read_b128 v[212:215], v155 offset:7168
	s_add_u32 s34, s30, 0xfff80080
	s_addc_u32 s35, s31, -1
	s_cmp_eq_u32 s61, 28
	s_cselect_b32 s37, s23, s35
	s_cselect_b32 s36, s57, s34
	s_cselect_b32 s35, s21, s60
	s_cselect_b32 s34, s58, s59
	s_add_i32 m0, s29, 0xc000
	s_nop 0
	global_load_lds_dwordx4 v138, s[30:31]
	s_add_i32 m0, s29, 0xe000
	s_nop 0
	global_load_lds_dwordx4 v136, s[30:31]
	s_waitcnt vmcnt(8)
	s_waitcnt lgkmcnt(0)
	s_barrier
	s_waitcnt lgkmcnt(0)
	v_mfma_i32_16x16x64_i8 v[124:127], v[144:147], v[184:187], v[124:127]
	v_mfma_i32_16x16x64_i8 v[120:123], v[160:163], v[184:187], v[120:123]
	v_mfma_i32_16x16x64_i8 v[108:111], v[144:147], v[192:195], v[108:111]
	v_mfma_i32_16x16x64_i8 v[104:107], v[160:163], v[192:195], v[104:107]
	s_add_u32 s98, s34, s6
	s_addc_u32 s99, s35, s7
	s_add_i32 s62, s41, s40
	v_mfma_i32_16x16x64_i8 v[92:95], v[144:147], v[200:203], v[92:95]
	s_add_u32 s100, s36, s6
	s_addc_u32 s101, s37, s7
	v_mfma_i32_16x16x64_i8 v[88:91], v[160:163], v[200:203], v[88:91]
	v_mfma_i32_16x16x64_i8 v[76:79], v[144:147], v[208:211], v[76:79]
	v_mfma_i32_16x16x64_i8 v[72:75], v[160:163], v[208:211], v[72:75]
	v_mfma_i32_16x16x64_i8 v[124:127], v[156:159], v[188:191], v[124:127]
	v_mfma_i32_16x16x64_i8 v[120:123], v[164:167], v[188:191], v[120:123]
	s_add_i32 s64, s42, s40
	v_mfma_i32_16x16x64_i8 v[108:111], v[156:159], v[196:199], v[108:111]
	v_mfma_i32_16x16x64_i8 v[104:107], v[164:167], v[196:199], v[104:107]
	v_mfma_i32_16x16x64_i8 v[92:95], v[156:159], v[204:207], v[92:95]
	v_mfma_i32_16x16x64_i8 v[88:91], v[164:167], v[204:207], v[88:91]
	v_mfma_i32_16x16x64_i8 v[76:79], v[156:159], v[212:215], v[76:79]
	v_mfma_i32_16x16x64_i8 v[72:75], v[164:167], v[212:215], v[72:75]
	v_mfma_i32_16x16x64_i8 v[116:119], v[168:171], v[184:187], v[116:119]
	v_mfma_i32_16x16x64_i8 v[112:115], v[176:179], v[184:187], v[112:115]
	v_mfma_i32_16x16x64_i8 v[100:103], v[168:171], v[192:195], v[100:103]
	v_mfma_i32_16x16x64_i8 v[96:99], v[176:179], v[192:195], v[96:99]
	v_mfma_i32_16x16x64_i8 v[84:87], v[168:171], v[200:203], v[84:87]
	v_mfma_i32_16x16x64_i8 v[80:83], v[176:179], v[200:203], v[80:83]
	v_mfma_i32_16x16x64_i8 v[68:71], v[168:171], v[208:211], v[68:71]
	v_mfma_i32_16x16x64_i8 v[64:67], v[176:179], v[208:211], v[64:67]
	v_mfma_i32_16x16x64_i8 v[116:119], v[172:175], v[188:191], v[116:119]
	v_mfma_i32_16x16x64_i8 v[112:115], v[180:183], v[188:191], v[112:115]
	v_mfma_i32_16x16x64_i8 v[100:103], v[172:175], v[196:199], v[100:103]
	v_mfma_i32_16x16x64_i8 v[96:99], v[180:183], v[196:199], v[96:99]
	v_mfma_i32_16x16x64_i8 v[84:87], v[172:175], v[204:207], v[84:87]
	v_mfma_i32_16x16x64_i8 v[80:83], v[180:183], v[204:207], v[80:83]
	v_mfma_i32_16x16x64_i8 v[68:71], v[172:175], v[212:215], v[68:71]
	v_mfma_i32_16x16x64_i8 v[64:67], v[180:183], v[212:215], v[64:67]
	s_barrier
	ds_read_b128 v[184:187], v155 offset:16384
	ds_read_b128 v[188:191], v155 offset:17408
	ds_read_b128 v[192:195], v155 offset:18432
	ds_read_b128 v[196:199], v155 offset:19456
	ds_read_b128 v[200:203], v155 offset:20480
	ds_read_b128 v[204:207], v155 offset:21504
	ds_read_b128 v[208:211], v155 offset:22528
	ds_read_b128 v[212:215], v155 offset:23552
	s_mov_b32 m0, s62
	s_nop 0
	global_load_lds_dwordx4 v130, s[34:35]
	s_add_i32 m0, s62, 0x2000
	s_add_u32 s62, s34, 0x80000
	s_addc_u32 s63, s35, 0
	global_load_lds_dwordx4 v134, s[34:35]
	s_mov_b32 m0, s64
	s_nop 0
	global_load_lds_dwordx4 v130, s[62:63]
	s_add_i32 m0, s64, 0x2000
	s_nop 0
	global_load_lds_dwordx4 v134, s[62:63]
	s_mov_b32 m0, s29
	s_nop 0
	global_load_lds_dwordx4 v128, s[36:37]
	s_mov_b32 m0, s48
	s_nop 0
	global_load_lds_dwordx4 v132, s[36:37]
	s_waitcnt vmcnt(8)
	s_waitcnt lgkmcnt(0)
	s_barrier
	s_waitcnt lgkmcnt(0)
	v_mfma_i32_16x16x64_i8 v[60:63], v[144:147], v[184:187], v[60:63]
	v_mfma_i32_16x16x64_i8 v[56:59], v[160:163], v[184:187], v[56:59]
	v_mfma_i32_16x16x64_i8 v[44:47], v[144:147], v[192:195], v[44:47]
	v_mfma_i32_16x16x64_i8 v[40:43], v[160:163], v[192:195], v[40:43]
	s_add_i32 s62, 0, 0x18000
	v_mfma_i32_16x16x64_i8 v[28:31], v[144:147], v[200:203], v[28:31]
	v_mfma_i32_16x16x64_i8 v[24:27], v[160:163], v[200:203], v[24:27]
	s_add_i32 s63, 0, 0x1c000
	v_mfma_i32_16x16x64_i8 v[12:15], v[144:147], v[208:211], v[12:15]
	v_mfma_i32_16x16x64_i8 v[8:11], v[160:163], v[208:211], v[8:11]
	s_add_u32 s36, s36, 0x80000
	v_mfma_i32_16x16x64_i8 v[60:63], v[156:159], v[188:191], v[60:63]
	v_mfma_i32_16x16x64_i8 v[56:59], v[164:167], v[188:191], v[56:59]
	s_addc_u32 s37, s37, 0
	v_mfma_i32_16x16x64_i8 v[44:47], v[156:159], v[196:199], v[44:47]
	v_mfma_i32_16x16x64_i8 v[40:43], v[164:167], v[196:199], v[40:43]
	v_mfma_i32_16x16x64_i8 v[28:31], v[156:159], v[204:207], v[28:31]
	v_mfma_i32_16x16x64_i8 v[24:27], v[164:167], v[204:207], v[24:27]
	v_mfma_i32_16x16x64_i8 v[12:15], v[156:159], v[212:215], v[12:15]
	v_mfma_i32_16x16x64_i8 v[8:11], v[164:167], v[212:215], v[8:11]
	v_mfma_i32_16x16x64_i8 v[52:55], v[168:171], v[184:187], v[52:55]
	v_mfma_i32_16x16x64_i8 v[48:51], v[176:179], v[184:187], v[48:51]
	v_mfma_i32_16x16x64_i8 v[36:39], v[168:171], v[192:195], v[36:39]
	v_mfma_i32_16x16x64_i8 v[32:35], v[176:179], v[192:195], v[32:35]
	v_mfma_i32_16x16x64_i8 v[20:23], v[168:171], v[200:203], v[20:23]
	v_mfma_i32_16x16x64_i8 v[16:19], v[176:179], v[200:203], v[16:19]
	v_mfma_i32_16x16x64_i8 v[4:7], v[168:171], v[208:211], v[4:7]
	v_mfma_i32_16x16x64_i8 v[0:3], v[176:179], v[208:211], v[0:3]
	v_mfma_i32_16x16x64_i8 v[52:55], v[172:175], v[188:191], v[52:55]
	v_mfma_i32_16x16x64_i8 v[48:51], v[180:183], v[188:191], v[48:51]
	v_mfma_i32_16x16x64_i8 v[36:39], v[172:175], v[196:199], v[36:39]
	v_mfma_i32_16x16x64_i8 v[32:35], v[180:183], v[196:199], v[32:35]
	v_mfma_i32_16x16x64_i8 v[20:23], v[172:175], v[204:207], v[20:23]
	v_mfma_i32_16x16x64_i8 v[16:19], v[180:183], v[204:207], v[16:19]
	v_mfma_i32_16x16x64_i8 v[4:7], v[172:175], v[212:215], v[4:7]
	v_mfma_i32_16x16x64_i8 v[0:3], v[180:183], v[212:215], v[0:3]
	s_barrier
	ds_read_b128 v[184:187], v155 offset:32768
	ds_read_b128 v[188:191], v155 offset:33792
	ds_read_b128 v[192:195], v155 offset:34816
	ds_read_b128 v[196:199], v155 offset:35840
	ds_read_b128 v[200:203], v155 offset:36864
	ds_read_b128 v[204:207], v155 offset:37888
	ds_read_b128 v[208:211], v155 offset:38912
	ds_read_b128 v[212:215], v155 offset:39936
	ds_read_b128 v[144:147], v248
	ds_read_b128 v[156:159], v248 offset:1024
	ds_read_b128 v[160:163], v248 offset:2048
	ds_read_b128 v[164:167], v248 offset:3072
	ds_read_b128 v[168:171], v249
	ds_read_b128 v[172:175], v249 offset:1024
	ds_read_b128 v[176:179], v249 offset:2048
	ds_read_b128 v[180:183], v249 offset:3072
	s_mov_b32 m0, s49
	s_nop 0
	global_load_lds_dwordx4 v128, s[36:37]
	s_mov_b32 m0, s50
	s_nop 0
	global_load_lds_dwordx4 v132, s[36:37]
	s_waitcnt vmcnt(8)
	s_waitcnt lgkmcnt(0)
	s_barrier
	s_waitcnt lgkmcnt(0)
	v_mfma_i32_16x16x64_i8 v[124:127], v[144:147], v[184:187], v[124:127]
	v_mfma_i32_16x16x64_i8 v[120:123], v[160:163], v[184:187], v[120:123]
	v_mfma_i32_16x16x64_i8 v[108:111], v[144:147], v[192:195], v[108:111]
	v_mfma_i32_16x16x64_i8 v[104:107], v[160:163], v[192:195], v[104:107]
	s_add_i32 s36, s62, s40
	v_mfma_i32_16x16x64_i8 v[92:95], v[144:147], v[200:203], v[92:95]
	v_mfma_i32_16x16x64_i8 v[88:91], v[160:163], v[200:203], v[88:91]
	v_mfma_i32_16x16x64_i8 v[76:79], v[144:147], v[208:211], v[76:79]
	v_mfma_i32_16x16x64_i8 v[72:75], v[160:163], v[208:211], v[72:75]
	s_add_u32 s34, s34, 0x80080
	v_mfma_i32_16x16x64_i8 v[124:127], v[156:159], v[188:191], v[124:127]
	v_mfma_i32_16x16x64_i8 v[120:123], v[164:167], v[188:191], v[120:123]
	v_mfma_i32_16x16x64_i8 v[108:111], v[156:159], v[196:199], v[108:111]
	v_mfma_i32_16x16x64_i8 v[104:107], v[164:167], v[196:199], v[104:107]
	s_addc_u32 s35, s35, 0
	v_mfma_i32_16x16x64_i8 v[92:95], v[156:159], v[204:207], v[92:95]
	v_mfma_i32_16x16x64_i8 v[88:91], v[164:167], v[204:207], v[88:91]
	v_mfma_i32_16x16x64_i8 v[76:79], v[156:159], v[212:215], v[76:79]
	v_mfma_i32_16x16x64_i8 v[72:75], v[164:167], v[212:215], v[72:75]
	v_mfma_i32_16x16x64_i8 v[116:119], v[168:171], v[184:187], v[116:119]
	v_mfma_i32_16x16x64_i8 v[112:115], v[176:179], v[184:187], v[112:115]
	v_mfma_i32_16x16x64_i8 v[100:103], v[168:171], v[192:195], v[100:103]
	v_mfma_i32_16x16x64_i8 v[96:99], v[176:179], v[192:195], v[96:99]
	v_mfma_i32_16x16x64_i8 v[84:87], v[168:171], v[200:203], v[84:87]
	v_mfma_i32_16x16x64_i8 v[80:83], v[176:179], v[200:203], v[80:83]
	v_mfma_i32_16x16x64_i8 v[68:71], v[168:171], v[208:211], v[68:71]
	v_mfma_i32_16x16x64_i8 v[64:67], v[176:179], v[208:211], v[64:67]
	v_mfma_i32_16x16x64_i8 v[116:119], v[172:175], v[188:191], v[116:119]
	v_mfma_i32_16x16x64_i8 v[112:115], v[180:183], v[188:191], v[112:115]
	v_mfma_i32_16x16x64_i8 v[100:103], v[172:175], v[196:199], v[100:103]
	v_mfma_i32_16x16x64_i8 v[96:99], v[180:183], v[196:199], v[96:99]
	v_mfma_i32_16x16x64_i8 v[84:87], v[172:175], v[204:207], v[84:87]
	v_mfma_i32_16x16x64_i8 v[80:83], v[180:183], v[204:207], v[80:83]
	v_mfma_i32_16x16x64_i8 v[68:71], v[172:175], v[212:215], v[68:71]
	v_mfma_i32_16x16x64_i8 v[64:67], v[180:183], v[212:215], v[64:67]
	s_barrier
	ds_read_b128 v[184:187], v155 offset:49152
	ds_read_b128 v[188:191], v155 offset:50176
	ds_read_b128 v[192:195], v155 offset:51200
	ds_read_b128 v[196:199], v155 offset:52224
	ds_read_b128 v[200:203], v155 offset:53248
	ds_read_b128 v[204:207], v155 offset:54272
	ds_read_b128 v[208:211], v155 offset:55296
	ds_read_b128 v[212:215], v155 offset:56320
	s_mov_b32 m0, s36
	s_nop 0
	global_load_lds_dwordx4 v130, s[98:99]
	s_add_i32 m0, s36, 0x2000
	s_add_i32 s36, s63, s40
	global_load_lds_dwordx4 v134, s[98:99]
	s_mov_b32 m0, s36
	s_nop 0
	global_load_lds_dwordx4 v130, s[34:35]
	s_add_i32 m0, s36, 0x2000
	s_nop 0
	global_load_lds_dwordx4 v134, s[34:35]
	s_mov_b32 m0, s44
	s_nop 0
	global_load_lds_dwordx4 v128, s[100:101]
	s_mov_b32 m0, s52
	s_nop 0
	global_load_lds_dwordx4 v132, s[100:101]
	s_waitcnt vmcnt(8)
	s_waitcnt lgkmcnt(0)
	s_barrier
	s_waitcnt lgkmcnt(0)
	v_mfma_i32_16x16x64_i8 v[60:63], v[144:147], v[184:187], v[60:63]
	v_mfma_i32_16x16x64_i8 v[56:59], v[160:163], v[184:187], v[56:59]
	v_mfma_i32_16x16x64_i8 v[44:47], v[144:147], v[192:195], v[44:47]
	v_mfma_i32_16x16x64_i8 v[40:43], v[160:163], v[192:195], v[40:43]
	v_mfma_i32_16x16x64_i8 v[28:31], v[144:147], v[200:203], v[28:31]
	v_mfma_i32_16x16x64_i8 v[24:27], v[160:163], v[200:203], v[24:27]
	v_mfma_i32_16x16x64_i8 v[12:15], v[144:147], v[208:211], v[12:15]
	v_mfma_i32_16x16x64_i8 v[8:11], v[160:163], v[208:211], v[8:11]
	v_mfma_i32_16x16x64_i8 v[60:63], v[156:159], v[188:191], v[60:63]
	v_mfma_i32_16x16x64_i8 v[56:59], v[164:167], v[188:191], v[56:59]
	v_mfma_i32_16x16x64_i8 v[44:47], v[156:159], v[196:199], v[44:47]
	v_mfma_i32_16x16x64_i8 v[40:43], v[164:167], v[196:199], v[40:43]
	v_mfma_i32_16x16x64_i8 v[28:31], v[156:159], v[204:207], v[28:31]
	v_mfma_i32_16x16x64_i8 v[24:27], v[164:167], v[204:207], v[24:27]
	v_mfma_i32_16x16x64_i8 v[12:15], v[156:159], v[212:215], v[12:15]
	v_mfma_i32_16x16x64_i8 v[8:11], v[164:167], v[212:215], v[8:11]
	v_mfma_i32_16x16x64_i8 v[52:55], v[168:171], v[184:187], v[52:55]
	v_mfma_i32_16x16x64_i8 v[48:51], v[176:179], v[184:187], v[48:51]
	v_mfma_i32_16x16x64_i8 v[36:39], v[168:171], v[192:195], v[36:39]
	v_mfma_i32_16x16x64_i8 v[32:35], v[176:179], v[192:195], v[32:35]
	v_mfma_i32_16x16x64_i8 v[20:23], v[168:171], v[200:203], v[20:23]
	v_mfma_i32_16x16x64_i8 v[16:19], v[176:179], v[200:203], v[16:19]
	v_mfma_i32_16x16x64_i8 v[4:7], v[168:171], v[208:211], v[4:7]
	v_mfma_i32_16x16x64_i8 v[0:3], v[176:179], v[208:211], v[0:3]
	v_mfma_i32_16x16x64_i8 v[52:55], v[172:175], v[188:191], v[52:55]
	v_mfma_i32_16x16x64_i8 v[48:51], v[180:183], v[188:191], v[48:51]
	v_mfma_i32_16x16x64_i8 v[36:39], v[172:175], v[196:199], v[36:39]
	v_mfma_i32_16x16x64_i8 v[32:35], v[180:183], v[196:199], v[32:35]
	v_mfma_i32_16x16x64_i8 v[20:23], v[172:175], v[204:207], v[20:23]
	v_mfma_i32_16x16x64_i8 v[16:19], v[180:183], v[204:207], v[16:19]
	v_mfma_i32_16x16x64_i8 v[4:7], v[172:175], v[212:215], v[4:7]
	v_mfma_i32_16x16x64_i8 v[0:3], v[180:183], v[212:215], v[0:3]
	s_barrier
	s_add_i32 s61, s61, 2
	s_add_u32 s59, s59, 0x100
	s_addc_u32 s60, s60, 0
	s_add_u32 s30, s30, 0x100
	s_addc_u32 s31, s31, 0
	s_cmp_gt_u32 s61, 29
	s_cbranch_scc0 .LBB0_281
	s_setprio 0
	s_and_b64 vcc, exec, s[8:9]
	s_cbranch_vccz .LBB0_284
	s_barrier

.LBB0_450:
	s_ashr_i32 s21, s20, 31
	s_lshl_b64 s[22:23], s[20:21], 21
	s_add_u32 s22, s33, s22
	s_addc_u32 s23, s38, s23
	s_and_b64 s[24:25], s[4:5], exec
	s_cselect_b32 s21, s23, s35
	s_cselect_b32 s27, s22, s34
	s_ashr_i32 s19, s18, 31
	s_lshl_b64 s[24:25], s[18:19], 21
	s_add_u32 s24, s39, s24
	s_addc_u32 s25, s40, s25
	s_and_b64 s[36:37], s[4:5], exec
	s_cselect_b32 s19, s25, s31
	s_cselect_b32 s55, s24, s30
	s_add_u32 s56, s30, 0x100
	s_addc_u32 s57, s31, 0
	s_add_u32 s30, s34, 0x100080
	v_mov_b32_e32 v0, 0
	s_addc_u32 s31, s35, 0
	s_mov_b32 s58, -2
	s_waitcnt lgkmcnt(0)
	v_mov_b32_e32 v1, v0
	v_mov_b32_e32 v2, v0
	v_mov_b32_e32 v3, v0
	v_mov_b32_e32 v4, v0
	v_mov_b32_e32 v5, v0
	v_mov_b32_e32 v6, v0
	v_mov_b32_e32 v7, v0
	v_mov_b32_e32 v16, v0
	v_mov_b32_e32 v17, v0
	v_mov_b32_e32 v18, v0
	v_mov_b32_e32 v19, v0
	v_mov_b32_e32 v20, v0
	v_mov_b32_e32 v21, v0
	v_mov_b32_e32 v22, v0
	v_mov_b32_e32 v23, v0
	v_mov_b32_e32 v32, v0
	v_mov_b32_e32 v33, v0
	v_mov_b32_e32 v34, v0
	v_mov_b32_e32 v35, v0
	v_mov_b32_e32 v36, v0
	v_mov_b32_e32 v37, v0
	v_mov_b32_e32 v38, v0
	v_mov_b32_e32 v39, v0
	v_mov_b32_e32 v48, v0
	v_mov_b32_e32 v49, v0
	v_mov_b32_e32 v50, v0
	v_mov_b32_e32 v51, v0
	v_mov_b32_e32 v52, v0
	v_mov_b32_e32 v53, v0
	v_mov_b32_e32 v54, v0
	v_mov_b32_e32 v55, v0
	v_mov_b32_e32 v8, v0
	v_mov_b32_e32 v9, v0
	v_mov_b32_e32 v10, v0
	v_mov_b32_e32 v11, v0
	v_mov_b32_e32 v12, v0
	v_mov_b32_e32 v13, v0
	v_mov_b32_e32 v14, v0
	v_mov_b32_e32 v15, v0
	v_mov_b32_e32 v24, v0
	v_mov_b32_e32 v25, v0
	v_mov_b32_e32 v26, v0
	v_mov_b32_e32 v27, v0
	v_mov_b32_e32 v28, v0
	v_mov_b32_e32 v29, v0
	v_mov_b32_e32 v30, v0
	v_mov_b32_e32 v31, v0
	v_mov_b32_e32 v40, v0
	v_mov_b32_e32 v41, v0
	v_mov_b32_e32 v42, v0
	v_mov_b32_e32 v43, v0
	v_mov_b32_e32 v44, v0
	v_mov_b32_e32 v45, v0
	v_mov_b32_e32 v46, v0
	v_mov_b32_e32 v47, v0
	v_mov_b32_e32 v56, v0
	v_mov_b32_e32 v57, v0
	v_mov_b32_e32 v58, v0
	v_mov_b32_e32 v59, v0
	v_mov_b32_e32 v60, v0
	v_mov_b32_e32 v61, v0
	v_mov_b32_e32 v62, v0
	v_mov_b32_e32 v63, v0
	v_mov_b32_e32 v64, v0
	v_mov_b32_e32 v65, v0
	v_mov_b32_e32 v66, v0
	v_mov_b32_e32 v67, v0
	v_mov_b32_e32 v68, v0
	v_mov_b32_e32 v69, v0
	v_mov_b32_e32 v70, v0
	v_mov_b32_e32 v71, v0
	v_mov_b32_e32 v80, v0
	v_mov_b32_e32 v81, v0
	v_mov_b32_e32 v82, v0
	v_mov_b32_e32 v83, v0
	v_mov_b32_e32 v84, v0
	v_mov_b32_e32 v85, v0
	v_mov_b32_e32 v86, v0
	v_mov_b32_e32 v87, v0
	v_mov_b32_e32 v96, v0
	v_mov_b32_e32 v97, v0
	v_mov_b32_e32 v98, v0
	v_mov_b32_e32 v99, v0
	v_mov_b32_e32 v100, v0
	v_mov_b32_e32 v101, v0
	v_mov_b32_e32 v102, v0
	v_mov_b32_e32 v103, v0
	v_mov_b32_e32 v116, v0
	v_mov_b32_e32 v117, v0
	v_mov_b32_e32 v118, v0
	v_mov_b32_e32 v119, v0
	v_mov_b32_e32 v120, v0
	v_mov_b32_e32 v121, v0
	v_mov_b32_e32 v122, v0
	v_mov_b32_e32 v123, v0
	v_mov_b32_e32 v72, v0
	v_mov_b32_e32 v73, v0
	v_mov_b32_e32 v74, v0
	v_mov_b32_e32 v75, v0
	v_mov_b32_e32 v76, v0
	v_mov_b32_e32 v77, v0
	v_mov_b32_e32 v78, v0
	v_mov_b32_e32 v79, v0
	v_mov_b32_e32 v88, v0
	v_mov_b32_e32 v89, v0
	v_mov_b32_e32 v90, v0
	v_mov_b32_e32 v91, v0
	v_mov_b32_e32 v92, v0
	v_mov_b32_e32 v93, v0
	v_mov_b32_e32 v94, v0
	v_mov_b32_e32 v95, v0
	v_mov_b32_e32 v104, v0
	v_mov_b32_e32 v105, v0
	v_mov_b32_e32 v106, v0
	v_mov_b32_e32 v107, v0
	v_mov_b32_e32 v108, v0
	v_mov_b32_e32 v109, v0
	v_mov_b32_e32 v110, v0
	v_mov_b32_e32 v111, v0
	v_mov_b32_e32 v128, v0
	v_mov_b32_e32 v129, v0
	v_mov_b32_e32 v130, v0
	v_mov_b32_e32 v131, v0
	v_mov_b32_e32 v132, v0
	v_mov_b32_e32 v133, v0
	v_mov_b32_e32 v134, v0
	v_mov_b32_e32 v135, v0
	v_add_u32_e32 v248, 0x18000, v191
	v_add_u32_e32 v249, 0x1c000, v191
	s_cmp_lt_u32 s81, 4
	s_cbranch_scc0 .Lsp_skip3
	s_setprio 1
.Lsp_skip3:
.LBB0_451:
	ds_read_b128 v[112:115], v193
	ds_read_b128 v[124:127], v193 offset:1024
	ds_read_b128 v[136:139], v193 offset:2048
	ds_read_b128 v[140:143], v193 offset:3072
	ds_read_b128 v[144:147], v194
	ds_read_b128 v[148:151], v194 offset:1024
	ds_read_b128 v[168:171], v194 offset:2048
	ds_read_b128 v[172:175], v194 offset:3072
	ds_read_b128 v[176:179], v195
	ds_read_b128 v[180:183], v195 offset:1024
	ds_read_b128 v[184:187], v195 offset:2048
	ds_read_b128 v[200:203], v195 offset:3072
	ds_read_b128 v[204:207], v195 offset:4096
	ds_read_b128 v[208:211], v195 offset:5120
	ds_read_b128 v[212:215], v195 offset:6144
	ds_read_b128 v[216:219], v195 offset:7168
	s_add_u32 s34, s30, 0xfff00080
	s_addc_u32 s35, s31, -1
	s_cmp_eq_u32 s58, 60
	s_cselect_b32 s37, s21, s35
	s_cselect_b32 s36, s27, s34
	s_cselect_b32 s35, s19, s57
	s_cselect_b32 s34, s55, s56
	s_add_i32 m0, s29, 0xc000
	s_nop 0
	global_load_lds_dwordx4 v162, s[30:31]
	s_add_i32 m0, s29, 0xe000
	s_nop 0
	global_load_lds_dwordx4 v160, s[30:31]
	s_waitcnt vmcnt(8)
	s_waitcnt lgkmcnt(0)
	s_barrier
	s_waitcnt lgkmcnt(0)
	v_mfma_f32_16x16x32_bf16 v[132:135], v[112:115], v[176:179], v[132:135]
	v_mfma_f32_16x16x32_bf16 v[128:131], v[136:139], v[176:179], v[128:131]
	v_mfma_f32_16x16x32_bf16 v[108:111], v[112:115], v[184:187], v[108:111]
	v_mfma_f32_16x16x32_bf16 v[104:107], v[136:139], v[184:187], v[104:107]
	s_add_u32 s98, s34, s14
	s_addc_u32 s99, s35, s15
	s_add_i32 s59, s50, s41
	v_mfma_f32_16x16x32_bf16 v[92:95], v[112:115], v[204:207], v[92:95]
	s_add_u32 s100, s36, s14
	s_addc_u32 s101, s37, s15
	v_mfma_f32_16x16x32_bf16 v[88:91], v[136:139], v[204:207], v[88:91]
	v_mfma_f32_16x16x32_bf16 v[76:79], v[112:115], v[212:215], v[76:79]
	v_mfma_f32_16x16x32_bf16 v[72:75], v[136:139], v[212:215], v[72:75]
	s_add_u32 s60, s34, 0x100000
	v_mfma_f32_16x16x32_bf16 v[132:135], v[124:127], v[180:183], v[132:135]
	v_mfma_f32_16x16x32_bf16 v[128:131], v[140:143], v[180:183], v[128:131]
	v_mfma_f32_16x16x32_bf16 v[108:111], v[124:127], v[200:203], v[108:111]
	v_mfma_f32_16x16x32_bf16 v[104:107], v[140:143], v[200:203], v[104:107]
	s_addc_u32 s61, s35, 0
	v_mfma_f32_16x16x32_bf16 v[92:95], v[124:127], v[208:211], v[92:95]
	v_mfma_f32_16x16x32_bf16 v[88:91], v[140:143], v[208:211], v[88:91]
	v_mfma_f32_16x16x32_bf16 v[76:79], v[124:127], v[216:219], v[76:79]
	v_mfma_f32_16x16x32_bf16 v[72:75], v[140:143], v[216:219], v[72:75]
	v_mfma_f32_16x16x32_bf16 v[120:123], v[144:147], v[176:179], v[120:123]
	v_mfma_f32_16x16x32_bf16 v[116:119], v[168:171], v[176:179], v[116:119]
	v_mfma_f32_16x16x32_bf16 v[100:103], v[144:147], v[184:187], v[100:103]
	v_mfma_f32_16x16x32_bf16 v[96:99], v[168:171], v[184:187], v[96:99]
	v_mfma_f32_16x16x32_bf16 v[84:87], v[144:147], v[204:207], v[84:87]
	v_mfma_f32_16x16x32_bf16 v[80:83], v[168:171], v[204:207], v[80:83]
	v_mfma_f32_16x16x32_bf16 v[68:71], v[144:147], v[212:215], v[68:71]
	v_mfma_f32_16x16x32_bf16 v[64:67], v[168:171], v[212:215], v[64:67]
	v_mfma_f32_16x16x32_bf16 v[120:123], v[148:151], v[180:183], v[120:123]
	v_mfma_f32_16x16x32_bf16 v[116:119], v[172:175], v[180:183], v[116:119]
	v_mfma_f32_16x16x32_bf16 v[100:103], v[148:151], v[200:203], v[100:103]
	v_mfma_f32_16x16x32_bf16 v[96:99], v[172:175], v[200:203], v[96:99]
	v_mfma_f32_16x16x32_bf16 v[84:87], v[148:151], v[208:211], v[84:87]
	v_mfma_f32_16x16x32_bf16 v[80:83], v[172:175], v[208:211], v[80:83]
	v_mfma_f32_16x16x32_bf16 v[68:71], v[148:151], v[216:219], v[68:71]
	v_mfma_f32_16x16x32_bf16 v[64:67], v[172:175], v[216:219], v[64:67]
	s_barrier
	ds_read_b128 v[176:179], v195 offset:16384
	ds_read_b128 v[180:183], v195 offset:17408
	ds_read_b128 v[184:187], v195 offset:18432
	ds_read_b128 v[200:203], v195 offset:19456
	ds_read_b128 v[204:207], v195 offset:20480
	ds_read_b128 v[208:211], v195 offset:21504
	ds_read_b128 v[212:215], v195 offset:22528
	ds_read_b128 v[216:219], v195 offset:23552
	s_mov_b32 m0, s59
	s_nop 0
	global_load_lds_dwordx4 v154, s[34:35]
	s_add_i32 m0, s59, 0x2000
	s_add_i32 s59, s51, s41
	global_load_lds_dwordx4 v158, s[34:35]
	s_mov_b32 m0, s59
	s_nop 0
	global_load_lds_dwordx4 v154, s[60:61]
	s_add_i32 m0, s59, 0x2000
	s_nop 0
	global_load_lds_dwordx4 v158, s[60:61]
	s_mov_b32 m0, s29
	s_nop 0
	global_load_lds_dwordx4 v152, s[36:37]
	s_mov_b32 m0, s42
	s_nop 0
	global_load_lds_dwordx4 v156, s[36:37]
	s_waitcnt vmcnt(8)
	s_waitcnt lgkmcnt(0)
	s_barrier
	s_waitcnt lgkmcnt(0)
	v_mfma_f32_16x16x32_bf16 v[60:63], v[112:115], v[176:179], v[60:63]
	v_mfma_f32_16x16x32_bf16 v[56:59], v[136:139], v[176:179], v[56:59]
	v_mfma_f32_16x16x32_bf16 v[44:47], v[112:115], v[184:187], v[44:47]
	v_mfma_f32_16x16x32_bf16 v[40:43], v[136:139], v[184:187], v[40:43]
	s_add_i32 s59, 0, 0x18000
	v_mfma_f32_16x16x32_bf16 v[28:31], v[112:115], v[204:207], v[28:31]
	v_mfma_f32_16x16x32_bf16 v[24:27], v[136:139], v[204:207], v[24:27]
	s_add_i32 s60, 0, 0x1c000
	v_mfma_f32_16x16x32_bf16 v[12:15], v[112:115], v[212:215], v[12:15]
	v_mfma_f32_16x16x32_bf16 v[8:11], v[136:139], v[212:215], v[8:11]
	s_add_u32 s36, s36, 0x100000
	v_mfma_f32_16x16x32_bf16 v[60:63], v[124:127], v[180:183], v[60:63]
	v_mfma_f32_16x16x32_bf16 v[56:59], v[140:143], v[180:183], v[56:59]
	s_addc_u32 s37, s37, 0
	v_mfma_f32_16x16x32_bf16 v[44:47], v[124:127], v[200:203], v[44:47]
	v_mfma_f32_16x16x32_bf16 v[40:43], v[140:143], v[200:203], v[40:43]
	v_mfma_f32_16x16x32_bf16 v[28:31], v[124:127], v[208:211], v[28:31]
	v_mfma_f32_16x16x32_bf16 v[24:27], v[140:143], v[208:211], v[24:27]
	v_mfma_f32_16x16x32_bf16 v[12:15], v[124:127], v[216:219], v[12:15]
	v_mfma_f32_16x16x32_bf16 v[8:11], v[140:143], v[216:219], v[8:11]
	v_mfma_f32_16x16x32_bf16 v[52:55], v[144:147], v[176:179], v[52:55]
	v_mfma_f32_16x16x32_bf16 v[48:51], v[168:171], v[176:179], v[48:51]
	v_mfma_f32_16x16x32_bf16 v[36:39], v[144:147], v[184:187], v[36:39]
	v_mfma_f32_16x16x32_bf16 v[32:35], v[168:171], v[184:187], v[32:35]
	v_mfma_f32_16x16x32_bf16 v[20:23], v[144:147], v[204:207], v[20:23]
	v_mfma_f32_16x16x32_bf16 v[16:19], v[168:171], v[204:207], v[16:19]
	v_mfma_f32_16x16x32_bf16 v[4:7], v[144:147], v[212:215], v[4:7]
	v_mfma_f32_16x16x32_bf16 v[0:3], v[168:171], v[212:215], v[0:3]
	v_mfma_f32_16x16x32_bf16 v[52:55], v[148:151], v[180:183], v[52:55]
	v_mfma_f32_16x16x32_bf16 v[48:51], v[172:175], v[180:183], v[48:51]
	v_mfma_f32_16x16x32_bf16 v[36:39], v[148:151], v[200:203], v[36:39]
	v_mfma_f32_16x16x32_bf16 v[32:35], v[172:175], v[200:203], v[32:35]
	v_mfma_f32_16x16x32_bf16 v[20:23], v[148:151], v[208:211], v[20:23]
	v_mfma_f32_16x16x32_bf16 v[16:19], v[172:175], v[208:211], v[16:19]
	v_mfma_f32_16x16x32_bf16 v[4:7], v[148:151], v[216:219], v[4:7]
	v_mfma_f32_16x16x32_bf16 v[0:3], v[172:175], v[216:219], v[0:3]
	s_barrier
	ds_read_b128 v[176:179], v195 offset:32768
	ds_read_b128 v[180:183], v195 offset:33792
	ds_read_b128 v[184:187], v195 offset:34816
	ds_read_b128 v[200:203], v195 offset:35840
	ds_read_b128 v[204:207], v195 offset:36864
	ds_read_b128 v[208:211], v195 offset:37888
	ds_read_b128 v[212:215], v195 offset:38912
	ds_read_b128 v[216:219], v195 offset:39936
	ds_read_b128 v[112:115], v248
	ds_read_b128 v[124:127], v248 offset:1024
	ds_read_b128 v[136:139], v248 offset:2048
	ds_read_b128 v[140:143], v248 offset:3072
	ds_read_b128 v[144:147], v249
	ds_read_b128 v[148:151], v249 offset:1024
	ds_read_b128 v[168:171], v249 offset:2048
	ds_read_b128 v[172:175], v249 offset:3072
	s_mov_b32 m0, s43
	s_nop 0
	global_load_lds_dwordx4 v152, s[36:37]
	s_mov_b32 m0, s44
	s_nop 0
	global_load_lds_dwordx4 v156, s[36:37]
	s_waitcnt vmcnt(8)
	s_waitcnt lgkmcnt(0)
	s_barrier
	s_waitcnt lgkmcnt(0)
	v_mfma_f32_16x16x32_bf16 v[132:135], v[112:115], v[176:179], v[132:135]
	v_mfma_f32_16x16x32_bf16 v[128:131], v[136:139], v[176:179], v[128:131]
	v_mfma_f32_16x16x32_bf16 v[108:111], v[112:115], v[184:187], v[108:111]
	v_mfma_f32_16x16x32_bf16 v[104:107], v[136:139], v[184:187], v[104:107]
	s_add_i32 s36, s59, s41
	v_mfma_f32_16x16x32_bf16 v[92:95], v[112:115], v[204:207], v[92:95]
	v_mfma_f32_16x16x32_bf16 v[88:91], v[136:139], v[204:207], v[88:91]
	v_mfma_f32_16x16x32_bf16 v[76:79], v[112:115], v[212:215], v[76:79]
	v_mfma_f32_16x16x32_bf16 v[72:75], v[136:139], v[212:215], v[72:75]
	s_add_u32 s34, s34, 0x100080
	v_mfma_f32_16x16x32_bf16 v[132:135], v[124:127], v[180:183], v[132:135]
	v_mfma_f32_16x16x32_bf16 v[128:131], v[140:143], v[180:183], v[128:131]
	v_mfma_f32_16x16x32_bf16 v[108:111], v[124:127], v[200:203], v[108:111]
	v_mfma_f32_16x16x32_bf16 v[104:107], v[140:143], v[200:203], v[104:107]
	s_addc_u32 s35, s35, 0
	v_mfma_f32_16x16x32_bf16 v[92:95], v[124:127], v[208:211], v[92:95]
	v_mfma_f32_16x16x32_bf16 v[88:91], v[140:143], v[208:211], v[88:91]
	v_mfma_f32_16x16x32_bf16 v[76:79], v[124:127], v[216:219], v[76:79]
	v_mfma_f32_16x16x32_bf16 v[72:75], v[140:143], v[216:219], v[72:75]
	v_mfma_f32_16x16x32_bf16 v[120:123], v[144:147], v[176:179], v[120:123]
	v_mfma_f32_16x16x32_bf16 v[116:119], v[168:171], v[176:179], v[116:119]
	v_mfma_f32_16x16x32_bf16 v[100:103], v[144:147], v[184:187], v[100:103]
	v_mfma_f32_16x16x32_bf16 v[96:99], v[168:171], v[184:187], v[96:99]
	v_mfma_f32_16x16x32_bf16 v[84:87], v[144:147], v[204:207], v[84:87]
	v_mfma_f32_16x16x32_bf16 v[80:83], v[168:171], v[204:207], v[80:83]
	v_mfma_f32_16x16x32_bf16 v[68:71], v[144:147], v[212:215], v[68:71]
	v_mfma_f32_16x16x32_bf16 v[64:67], v[168:171], v[212:215], v[64:67]
	v_mfma_f32_16x16x32_bf16 v[120:123], v[148:151], v[180:183], v[120:123]
	v_mfma_f32_16x16x32_bf16 v[116:119], v[172:175], v[180:183], v[116:119]
	v_mfma_f32_16x16x32_bf16 v[100:103], v[148:151], v[200:203], v[100:103]
	v_mfma_f32_16x16x32_bf16 v[96:99], v[172:175], v[200:203], v[96:99]
	v_mfma_f32_16x16x32_bf16 v[84:87], v[148:151], v[208:211], v[84:87]
	v_mfma_f32_16x16x32_bf16 v[80:83], v[172:175], v[208:211], v[80:83]
	v_mfma_f32_16x16x32_bf16 v[68:71], v[148:151], v[216:219], v[68:71]
	v_mfma_f32_16x16x32_bf16 v[64:67], v[172:175], v[216:219], v[64:67]
	s_barrier
	ds_read_b128 v[176:179], v195 offset:49152
	ds_read_b128 v[180:183], v195 offset:50176
	ds_read_b128 v[184:187], v195 offset:51200
	ds_read_b128 v[200:203], v195 offset:52224
	ds_read_b128 v[204:207], v195 offset:53248
	ds_read_b128 v[208:211], v195 offset:54272
	ds_read_b128 v[212:215], v195 offset:55296
	ds_read_b128 v[216:219], v195 offset:56320
	s_mov_b32 m0, s36
	s_nop 0
	global_load_lds_dwordx4 v154, s[98:99]
	s_add_i32 m0, s36, 0x2000
	s_add_i32 s36, s60, s41
	global_load_lds_dwordx4 v158, s[98:99]
	s_mov_b32 m0, s36
	s_nop 0
	global_load_lds_dwordx4 v154, s[34:35]
	s_add_i32 m0, s36, 0x2000
	s_nop 0
	global_load_lds_dwordx4 v158, s[34:35]
	s_mov_b32 m0, s46
	s_nop 0
	global_load_lds_dwordx4 v152, s[100:101]
	s_mov_b32 m0, s47
	s_nop 0
	global_load_lds_dwordx4 v156, s[100:101]
	s_waitcnt vmcnt(8)
	s_waitcnt lgkmcnt(0)
	s_barrier
	s_waitcnt lgkmcnt(0)
	v_mfma_f32_16x16x32_bf16 v[60:63], v[112:115], v[176:179], v[60:63]
	v_mfma_f32_16x16x32_bf16 v[56:59], v[136:139], v[176:179], v[56:59]
	v_mfma_f32_16x16x32_bf16 v[44:47], v[112:115], v[184:187], v[44:47]
	v_mfma_f32_16x16x32_bf16 v[40:43], v[136:139], v[184:187], v[40:43]
	v_mfma_f32_16x16x32_bf16 v[28:31], v[112:115], v[204:207], v[28:31]
	v_mfma_f32_16x16x32_bf16 v[24:27], v[136:139], v[204:207], v[24:27]
	v_mfma_f32_16x16x32_bf16 v[12:15], v[112:115], v[212:215], v[12:15]
	v_mfma_f32_16x16x32_bf16 v[8:11], v[136:139], v[212:215], v[8:11]
	v_mfma_f32_16x16x32_bf16 v[60:63], v[124:127], v[180:183], v[60:63]
	v_mfma_f32_16x16x32_bf16 v[56:59], v[140:143], v[180:183], v[56:59]
	v_mfma_f32_16x16x32_bf16 v[44:47], v[124:127], v[200:203], v[44:47]
	v_mfma_f32_16x16x32_bf16 v[40:43], v[140:143], v[200:203], v[40:43]
	v_mfma_f32_16x16x32_bf16 v[28:31], v[124:127], v[208:211], v[28:31]
	v_mfma_f32_16x16x32_bf16 v[24:27], v[140:143], v[208:211], v[24:27]
	v_mfma_f32_16x16x32_bf16 v[12:15], v[124:127], v[216:219], v[12:15]
	v_mfma_f32_16x16x32_bf16 v[8:11], v[140:143], v[216:219], v[8:11]
	v_mfma_f32_16x16x32_bf16 v[52:55], v[144:147], v[176:179], v[52:55]
	v_mfma_f32_16x16x32_bf16 v[48:51], v[168:171], v[176:179], v[48:51]
	v_mfma_f32_16x16x32_bf16 v[36:39], v[144:147], v[184:187], v[36:39]
	v_mfma_f32_16x16x32_bf16 v[32:35], v[168:171], v[184:187], v[32:35]
	v_mfma_f32_16x16x32_bf16 v[20:23], v[144:147], v[204:207], v[20:23]
	v_mfma_f32_16x16x32_bf16 v[16:19], v[168:171], v[204:207], v[16:19]
	v_mfma_f32_16x16x32_bf16 v[4:7], v[144:147], v[212:215], v[4:7]
	v_mfma_f32_16x16x32_bf16 v[0:3], v[168:171], v[212:215], v[0:3]
	v_mfma_f32_16x16x32_bf16 v[52:55], v[148:151], v[180:183], v[52:55]
	v_mfma_f32_16x16x32_bf16 v[48:51], v[172:175], v[180:183], v[48:51]
	v_mfma_f32_16x16x32_bf16 v[36:39], v[148:151], v[200:203], v[36:39]
	v_mfma_f32_16x16x32_bf16 v[32:35], v[172:175], v[200:203], v[32:35]
	v_mfma_f32_16x16x32_bf16 v[20:23], v[148:151], v[208:211], v[20:23]
	v_mfma_f32_16x16x32_bf16 v[16:19], v[172:175], v[208:211], v[16:19]
	v_mfma_f32_16x16x32_bf16 v[4:7], v[148:151], v[216:219], v[4:7]
	v_mfma_f32_16x16x32_bf16 v[0:3], v[172:175], v[216:219], v[0:3]
	s_barrier
	s_add_i32 s58, s58, 2
	s_add_u32 s56, s56, 0x100
	s_addc_u32 s57, s57, 0
	s_add_u32 s30, s30, 0x100
	s_addc_u32 s31, s31, 0
	s_cmp_gt_u32 s58, 61
	s_cbranch_scc0 .LBB0_451
	s_setprio 0
	s_and_b64 vcc, exec, s[16:17]
	s_cbranch_vccz .LBB0_454
	s_barrier

.LBB0_549:
	s_ashr_i32 s31, s30, 31
	s_lshl_b64 s[34:35], s[30:31], 20
	s_add_u32 s34, s40, s34
	s_addc_u32 s35, s41, s35
	s_and_b64 s[36:37], s[2:3], exec
	s_cselect_b32 s1, s35, s7
	s_cselect_b32 s31, s34, s6
	s_ashr_i32 s29, s28, 31
	s_lshl_b64 s[36:37], s[28:29], 20
	s_add_u32 s36, s42, s36
	s_addc_u32 s37, s43, s37
	s_and_b64 s[38:39], s[2:3], exec
	s_cselect_b32 s29, s37, s5
	s_cselect_b32 s61, s36, s4
	s_add_u32 s62, s4, 0x100
	s_addc_u32 s63, s5, 0
	s_add_u32 s4, s6, 0x80080
	v_mov_b32_e32 v0, 0
	s_addc_u32 s5, s7, 0
	s_mov_b32 s64, -2
	v_mov_b32_e32 v1, v0
	v_mov_b32_e32 v2, v0
	v_mov_b32_e32 v3, v0
	v_mov_b32_e32 v4, v0
	v_mov_b32_e32 v5, v0
	v_mov_b32_e32 v6, v0
	v_mov_b32_e32 v7, v0
	v_mov_b32_e32 v16, v0
	v_mov_b32_e32 v17, v0
	v_mov_b32_e32 v18, v0
	v_mov_b32_e32 v19, v0
	v_mov_b32_e32 v20, v0
	v_mov_b32_e32 v21, v0
	v_mov_b32_e32 v22, v0
	v_mov_b32_e32 v23, v0
	v_mov_b32_e32 v32, v0
	v_mov_b32_e32 v33, v0
	v_mov_b32_e32 v34, v0
	v_mov_b32_e32 v35, v0
	v_mov_b32_e32 v36, v0
	v_mov_b32_e32 v37, v0
	v_mov_b32_e32 v38, v0
	v_mov_b32_e32 v39, v0
	v_mov_b32_e32 v48, v0
	v_mov_b32_e32 v49, v0
	v_mov_b32_e32 v50, v0
	v_mov_b32_e32 v51, v0
	v_mov_b32_e32 v52, v0
	v_mov_b32_e32 v53, v0
	v_mov_b32_e32 v54, v0
	v_mov_b32_e32 v55, v0
	v_mov_b32_e32 v8, v0
	v_mov_b32_e32 v9, v0
	v_mov_b32_e32 v10, v0
	v_mov_b32_e32 v11, v0
	v_mov_b32_e32 v12, v0
	v_mov_b32_e32 v13, v0
	v_mov_b32_e32 v14, v0
	v_mov_b32_e32 v15, v0
	v_mov_b32_e32 v24, v0
	v_mov_b32_e32 v25, v0
	v_mov_b32_e32 v26, v0
	v_mov_b32_e32 v27, v0
	v_mov_b32_e32 v28, v0
	v_mov_b32_e32 v29, v0
	v_mov_b32_e32 v30, v0
	v_mov_b32_e32 v31, v0
	v_mov_b32_e32 v40, v0
	v_mov_b32_e32 v41, v0
	v_mov_b32_e32 v42, v0
	v_mov_b32_e32 v43, v0
	v_mov_b32_e32 v44, v0
	v_mov_b32_e32 v45, v0
	v_mov_b32_e32 v46, v0
	v_mov_b32_e32 v47, v0
	v_mov_b32_e32 v56, v0
	v_mov_b32_e32 v57, v0
	v_mov_b32_e32 v58, v0
	v_mov_b32_e32 v59, v0
	v_mov_b32_e32 v60, v0
	v_mov_b32_e32 v61, v0
	v_mov_b32_e32 v62, v0
	v_mov_b32_e32 v63, v0
	v_mov_b32_e32 v64, v0
	v_mov_b32_e32 v65, v0
	v_mov_b32_e32 v66, v0
	v_mov_b32_e32 v67, v0
	v_mov_b32_e32 v68, v0
	v_mov_b32_e32 v69, v0
	v_mov_b32_e32 v70, v0
	v_mov_b32_e32 v71, v0
	v_mov_b32_e32 v80, v0
	v_mov_b32_e32 v81, v0
	v_mov_b32_e32 v82, v0
	v_mov_b32_e32 v83, v0
	v_mov_b32_e32 v84, v0
	v_mov_b32_e32 v85, v0
	v_mov_b32_e32 v86, v0
	v_mov_b32_e32 v87, v0
	v_mov_b32_e32 v96, v0
	v_mov_b32_e32 v97, v0
	v_mov_b32_e32 v98, v0
	v_mov_b32_e32 v99, v0
	v_mov_b32_e32 v100, v0
	v_mov_b32_e32 v101, v0
	v_mov_b32_e32 v102, v0
	v_mov_b32_e32 v103, v0
	v_mov_b32_e32 v112, v0
	v_mov_b32_e32 v113, v0
	v_mov_b32_e32 v114, v0
	v_mov_b32_e32 v115, v0
	v_mov_b32_e32 v116, v0
	v_mov_b32_e32 v117, v0
	v_mov_b32_e32 v118, v0
	v_mov_b32_e32 v119, v0
	v_mov_b32_e32 v72, v0
	v_mov_b32_e32 v73, v0
	v_mov_b32_e32 v74, v0
	v_mov_b32_e32 v75, v0
	v_mov_b32_e32 v76, v0
	v_mov_b32_e32 v77, v0
	v_mov_b32_e32 v78, v0
	v_mov_b32_e32 v79, v0
	v_mov_b32_e32 v88, v0
	v_mov_b32_e32 v89, v0
	v_mov_b32_e32 v90, v0
	v_mov_b32_e32 v91, v0
	v_mov_b32_e32 v92, v0
	v_mov_b32_e32 v93, v0
	v_mov_b32_e32 v94, v0
	v_mov_b32_e32 v95, v0
	v_mov_b32_e32 v104, v0
	v_mov_b32_e32 v105, v0
	v_mov_b32_e32 v106, v0
	v_mov_b32_e32 v107, v0
	v_mov_b32_e32 v108, v0
	v_mov_b32_e32 v109, v0
	v_mov_b32_e32 v110, v0
	v_mov_b32_e32 v111, v0
	v_mov_b32_e32 v120, v0
	v_mov_b32_e32 v121, v0
	v_mov_b32_e32 v122, v0
	v_mov_b32_e32 v123, v0
	v_mov_b32_e32 v124, v0
	v_mov_b32_e32 v125, v0
	v_mov_b32_e32 v126, v0
	v_mov_b32_e32 v127, v0
	v_add_u32_e32 v248, 0x18000, v157
	v_add_u32_e32 v249, 0x1c000, v157
	s_cmp_lt_u32 s81, 4
	s_cbranch_scc0 .Lsp_skip4
	s_setprio 1
.Lsp_skip4:
.LBB0_550:
	ds_read_b128 v[144:147], v161
	ds_read_b128 v[148:151], v161 offset:1024
	ds_read_b128 v[170:173], v161 offset:2048
	ds_read_b128 v[174:177], v161 offset:3072
	ds_read_b128 v[178:181], v163
	ds_read_b128 v[182:185], v163 offset:1024
	ds_read_b128 v[186:189], v163 offset:2048
	ds_read_b128 v[190:193], v163 offset:3072
	ds_read_b128 v[194:197], v166
	ds_read_b128 v[198:201], v166 offset:1024
	ds_read_b128 v[202:205], v166 offset:2048
	ds_read_b128 v[206:209], v166 offset:3072
	ds_read_b128 v[210:213], v166 offset:4096
	ds_read_b128 v[214:217], v166 offset:5120
	ds_read_b128 v[218:221], v166 offset:6144
	ds_read_b128 v[222:225], v166 offset:7168
	s_add_u32 s6, s4, 0xfff80080
	s_addc_u32 s7, s5, -1
	s_cmp_eq_u32 s64, 28
	s_cselect_b32 s39, s1, s7
	s_cselect_b32 s38, s31, s6
	s_cselect_b32 s7, s29, s63
	s_cselect_b32 s6, s61, s62
	s_add_i32 m0, s45, 0xc000
	s_nop 0
	global_load_lds_dwordx4 v138, s[4:5]
	s_add_i32 m0, s45, 0xe000
	s_nop 0
	global_load_lds_dwordx4 v136, s[4:5]
	s_waitcnt vmcnt(8)
	s_waitcnt lgkmcnt(0)
	s_barrier
	s_waitcnt lgkmcnt(0)
	v_mfma_i32_16x16x64_i8 v[124:127], v[144:147], v[194:197], v[124:127]
	v_mfma_i32_16x16x64_i8 v[120:123], v[170:173], v[194:197], v[120:123]
	v_mfma_i32_16x16x64_i8 v[108:111], v[144:147], v[202:205], v[108:111]
	v_mfma_i32_16x16x64_i8 v[104:107], v[170:173], v[202:205], v[104:107]
	s_add_u32 s98, s6, s16
	s_addc_u32 s99, s7, s17
	s_add_i32 s65, s53, s44
	v_mfma_i32_16x16x64_i8 v[92:95], v[144:147], v[210:213], v[92:95]
	s_add_u32 s100, s38, s16
	s_addc_u32 s101, s39, s17
	v_mfma_i32_16x16x64_i8 v[88:91], v[170:173], v[210:213], v[88:91]
	v_mfma_i32_16x16x64_i8 v[76:79], v[144:147], v[218:221], v[76:79]
	v_mfma_i32_16x16x64_i8 v[72:75], v[170:173], v[218:221], v[72:75]
	s_add_u32 s66, s6, 0x80000
	v_mfma_i32_16x16x64_i8 v[124:127], v[148:151], v[198:201], v[124:127]
	v_mfma_i32_16x16x64_i8 v[120:123], v[174:177], v[198:201], v[120:123]
	v_mfma_i32_16x16x64_i8 v[108:111], v[148:151], v[206:209], v[108:111]
	v_mfma_i32_16x16x64_i8 v[104:107], v[174:177], v[206:209], v[104:107]
	s_addc_u32 s67, s7, 0
	v_mfma_i32_16x16x64_i8 v[92:95], v[148:151], v[214:217], v[92:95]
	v_mfma_i32_16x16x64_i8 v[88:91], v[174:177], v[214:217], v[88:91]
	v_mfma_i32_16x16x64_i8 v[76:79], v[148:151], v[222:225], v[76:79]
	v_mfma_i32_16x16x64_i8 v[72:75], v[174:177], v[222:225], v[72:75]
	v_mfma_i32_16x16x64_i8 v[116:119], v[178:181], v[194:197], v[116:119]
	v_mfma_i32_16x16x64_i8 v[112:115], v[186:189], v[194:197], v[112:115]
	v_mfma_i32_16x16x64_i8 v[100:103], v[178:181], v[202:205], v[100:103]
	v_mfma_i32_16x16x64_i8 v[96:99], v[186:189], v[202:205], v[96:99]
	v_mfma_i32_16x16x64_i8 v[84:87], v[178:181], v[210:213], v[84:87]
	v_mfma_i32_16x16x64_i8 v[80:83], v[186:189], v[210:213], v[80:83]
	v_mfma_i32_16x16x64_i8 v[68:71], v[178:181], v[218:221], v[68:71]
	v_mfma_i32_16x16x64_i8 v[64:67], v[186:189], v[218:221], v[64:67]
	v_mfma_i32_16x16x64_i8 v[116:119], v[182:185], v[198:201], v[116:119]
	v_mfma_i32_16x16x64_i8 v[112:115], v[190:193], v[198:201], v[112:115]
	v_mfma_i32_16x16x64_i8 v[100:103], v[182:185], v[206:209], v[100:103]
	v_mfma_i32_16x16x64_i8 v[96:99], v[190:193], v[206:209], v[96:99]
	v_mfma_i32_16x16x64_i8 v[84:87], v[182:185], v[214:217], v[84:87]
	v_mfma_i32_16x16x64_i8 v[80:83], v[190:193], v[214:217], v[80:83]
	v_mfma_i32_16x16x64_i8 v[68:71], v[182:185], v[222:225], v[68:71]
	v_mfma_i32_16x16x64_i8 v[64:67], v[190:193], v[222:225], v[64:67]
	s_barrier
	ds_read_b128 v[194:197], v166 offset:16384
	ds_read_b128 v[198:201], v166 offset:17408
	ds_read_b128 v[202:205], v166 offset:18432
	ds_read_b128 v[206:209], v166 offset:19456
	ds_read_b128 v[210:213], v166 offset:20480
	ds_read_b128 v[214:217], v166 offset:21504
	ds_read_b128 v[218:221], v166 offset:22528
	ds_read_b128 v[222:225], v166 offset:23552
	s_mov_b32 m0, s65
	s_nop 0
	global_load_lds_dwordx4 v130, s[6:7]
	s_add_i32 m0, s65, 0x2000
	s_add_i32 s65, s54, s44
	global_load_lds_dwordx4 v134, s[6:7]
	s_mov_b32 m0, s65
	s_nop 0
	global_load_lds_dwordx4 v130, s[66:67]
	s_add_i32 m0, s65, 0x2000
	s_nop 0
	global_load_lds_dwordx4 v134, s[66:67]
	s_mov_b32 m0, s45
	s_nop 0
	global_load_lds_dwordx4 v128, s[38:39]
	s_mov_b32 m0, s46
	s_nop 0
	global_load_lds_dwordx4 v132, s[38:39]
	s_waitcnt vmcnt(8)
	s_waitcnt lgkmcnt(0)
	s_barrier
	s_waitcnt lgkmcnt(0)
	v_mfma_i32_16x16x64_i8 v[60:63], v[144:147], v[194:197], v[60:63]
	v_mfma_i32_16x16x64_i8 v[56:59], v[170:173], v[194:197], v[56:59]
	v_mfma_i32_16x16x64_i8 v[44:47], v[144:147], v[202:205], v[44:47]
	v_mfma_i32_16x16x64_i8 v[40:43], v[170:173], v[202:205], v[40:43]
	s_add_i32 s65, 0, 0x18000
	v_mfma_i32_16x16x64_i8 v[28:31], v[144:147], v[210:213], v[28:31]
	v_mfma_i32_16x16x64_i8 v[24:27], v[170:173], v[210:213], v[24:27]
	v_mfma_i32_16x16x64_i8 v[12:15], v[144:147], v[218:221], v[12:15]
	v_mfma_i32_16x16x64_i8 v[8:11], v[170:173], v[218:221], v[8:11]
	s_add_i32 s66, 0, 0x1c000
	v_mfma_i32_16x16x64_i8 v[60:63], v[148:151], v[198:201], v[60:63]
	v_mfma_i32_16x16x64_i8 v[56:59], v[174:177], v[198:201], v[56:59]
	s_add_u32 s38, s38, 0x80000
	v_mfma_i32_16x16x64_i8 v[44:47], v[148:151], v[206:209], v[44:47]
	v_mfma_i32_16x16x64_i8 v[40:43], v[174:177], v[206:209], v[40:43]
	s_addc_u32 s39, s39, 0
	v_mfma_i32_16x16x64_i8 v[28:31], v[148:151], v[214:217], v[28:31]
	v_mfma_i32_16x16x64_i8 v[24:27], v[174:177], v[214:217], v[24:27]
	v_mfma_i32_16x16x64_i8 v[12:15], v[148:151], v[222:225], v[12:15]
	v_mfma_i32_16x16x64_i8 v[8:11], v[174:177], v[222:225], v[8:11]
	v_mfma_i32_16x16x64_i8 v[52:55], v[178:181], v[194:197], v[52:55]
	v_mfma_i32_16x16x64_i8 v[48:51], v[186:189], v[194:197], v[48:51]
	v_mfma_i32_16x16x64_i8 v[36:39], v[178:181], v[202:205], v[36:39]
	v_mfma_i32_16x16x64_i8 v[32:35], v[186:189], v[202:205], v[32:35]
	v_mfma_i32_16x16x64_i8 v[20:23], v[178:181], v[210:213], v[20:23]
	v_mfma_i32_16x16x64_i8 v[16:19], v[186:189], v[210:213], v[16:19]
	v_mfma_i32_16x16x64_i8 v[4:7], v[178:181], v[218:221], v[4:7]
	v_mfma_i32_16x16x64_i8 v[0:3], v[186:189], v[218:221], v[0:3]
	v_mfma_i32_16x16x64_i8 v[52:55], v[182:185], v[198:201], v[52:55]
	v_mfma_i32_16x16x64_i8 v[48:51], v[190:193], v[198:201], v[48:51]
	v_mfma_i32_16x16x64_i8 v[36:39], v[182:185], v[206:209], v[36:39]
	v_mfma_i32_16x16x64_i8 v[32:35], v[190:193], v[206:209], v[32:35]
	v_mfma_i32_16x16x64_i8 v[20:23], v[182:185], v[214:217], v[20:23]
	v_mfma_i32_16x16x64_i8 v[16:19], v[190:193], v[214:217], v[16:19]
	v_mfma_i32_16x16x64_i8 v[4:7], v[182:185], v[222:225], v[4:7]
	v_mfma_i32_16x16x64_i8 v[0:3], v[190:193], v[222:225], v[0:3]
	s_barrier
	ds_read_b128 v[194:197], v166 offset:32768
	ds_read_b128 v[198:201], v166 offset:33792
	ds_read_b128 v[202:205], v166 offset:34816
	ds_read_b128 v[206:209], v166 offset:35840
	ds_read_b128 v[210:213], v166 offset:36864
	ds_read_b128 v[214:217], v166 offset:37888
	ds_read_b128 v[218:221], v166 offset:38912
	ds_read_b128 v[222:225], v166 offset:39936
	ds_read_b128 v[144:147], v248
	ds_read_b128 v[148:151], v248 offset:1024
	ds_read_b128 v[170:173], v248 offset:2048
	ds_read_b128 v[174:177], v248 offset:3072
	ds_read_b128 v[178:181], v249
	ds_read_b128 v[182:185], v249 offset:1024
	ds_read_b128 v[186:189], v249 offset:2048
	ds_read_b128 v[190:193], v249 offset:3072
	s_mov_b32 m0, s47
	s_nop 0
	global_load_lds_dwordx4 v128, s[38:39]
	s_mov_b32 m0, s48
	s_nop 0
	global_load_lds_dwordx4 v132, s[38:39]
	s_waitcnt vmcnt(8)
	s_waitcnt lgkmcnt(0)
	s_barrier
	s_waitcnt lgkmcnt(0)
	v_mfma_i32_16x16x64_i8 v[124:127], v[144:147], v[194:197], v[124:127]
	v_mfma_i32_16x16x64_i8 v[120:123], v[170:173], v[194:197], v[120:123]
	v_mfma_i32_16x16x64_i8 v[108:111], v[144:147], v[202:205], v[108:111]
	v_mfma_i32_16x16x64_i8 v[104:107], v[170:173], v[202:205], v[104:107]
	s_add_i32 s38, s65, s44
	v_mfma_i32_16x16x64_i8 v[92:95], v[144:147], v[210:213], v[92:95]
	v_mfma_i32_16x16x64_i8 v[88:91], v[170:173], v[210:213], v[88:91]
	v_mfma_i32_16x16x64_i8 v[76:79], v[144:147], v[218:221], v[76:79]
	v_mfma_i32_16x16x64_i8 v[72:75], v[170:173], v[218:221], v[72:75]
	s_add_u32 s6, s6, 0x80080
	v_mfma_i32_16x16x64_i8 v[124:127], v[148:151], v[198:201], v[124:127]
	v_mfma_i32_16x16x64_i8 v[120:123], v[174:177], v[198:201], v[120:123]
	v_mfma_i32_16x16x64_i8 v[108:111], v[148:151], v[206:209], v[108:111]
	v_mfma_i32_16x16x64_i8 v[104:107], v[174:177], v[206:209], v[104:107]
	s_addc_u32 s7, s7, 0
	v_mfma_i32_16x16x64_i8 v[92:95], v[148:151], v[214:217], v[92:95]
	v_mfma_i32_16x16x64_i8 v[88:91], v[174:177], v[214:217], v[88:91]
	v_mfma_i32_16x16x64_i8 v[76:79], v[148:151], v[222:225], v[76:79]
	v_mfma_i32_16x16x64_i8 v[72:75], v[174:177], v[222:225], v[72:75]
	v_mfma_i32_16x16x64_i8 v[116:119], v[178:181], v[194:197], v[116:119]
	v_mfma_i32_16x16x64_i8 v[112:115], v[186:189], v[194:197], v[112:115]
	v_mfma_i32_16x16x64_i8 v[100:103], v[178:181], v[202:205], v[100:103]
	v_mfma_i32_16x16x64_i8 v[96:99], v[186:189], v[202:205], v[96:99]
	v_mfma_i32_16x16x64_i8 v[84:87], v[178:181], v[210:213], v[84:87]
	v_mfma_i32_16x16x64_i8 v[80:83], v[186:189], v[210:213], v[80:83]
	v_mfma_i32_16x16x64_i8 v[68:71], v[178:181], v[218:221], v[68:71]
	v_mfma_i32_16x16x64_i8 v[64:67], v[186:189], v[218:221], v[64:67]
	v_mfma_i32_16x16x64_i8 v[116:119], v[182:185], v[198:201], v[116:119]
	v_mfma_i32_16x16x64_i8 v[112:115], v[190:193], v[198:201], v[112:115]
	v_mfma_i32_16x16x64_i8 v[100:103], v[182:185], v[206:209], v[100:103]
	v_mfma_i32_16x16x64_i8 v[96:99], v[190:193], v[206:209], v[96:99]
	v_mfma_i32_16x16x64_i8 v[84:87], v[182:185], v[214:217], v[84:87]
	v_mfma_i32_16x16x64_i8 v[80:83], v[190:193], v[214:217], v[80:83]
	v_mfma_i32_16x16x64_i8 v[68:71], v[182:185], v[222:225], v[68:71]
	v_mfma_i32_16x16x64_i8 v[64:67], v[190:193], v[222:225], v[64:67]
	s_barrier
	ds_read_b128 v[194:197], v166 offset:49152
	ds_read_b128 v[198:201], v166 offset:50176
	ds_read_b128 v[202:205], v166 offset:51200
	ds_read_b128 v[206:209], v166 offset:52224
	ds_read_b128 v[210:213], v166 offset:53248
	ds_read_b128 v[214:217], v166 offset:54272
	ds_read_b128 v[218:221], v166 offset:55296
	ds_read_b128 v[222:225], v166 offset:56320
	s_mov_b32 m0, s38
	s_nop 0
	global_load_lds_dwordx4 v130, s[98:99]
	s_add_i32 m0, s38, 0x2000
	s_add_i32 s38, s66, s44
	global_load_lds_dwordx4 v134, s[98:99]
	s_mov_b32 m0, s38
	s_nop 0
	global_load_lds_dwordx4 v130, s[6:7]
	s_add_i32 m0, s38, 0x2000
	s_nop 0
	global_load_lds_dwordx4 v134, s[6:7]
	s_mov_b32 m0, s50
	s_nop 0
	global_load_lds_dwordx4 v128, s[100:101]
	s_mov_b32 m0, s51
	s_nop 0
	global_load_lds_dwordx4 v132, s[100:101]
	s_waitcnt vmcnt(8)
	s_waitcnt lgkmcnt(0)
	s_barrier
	s_waitcnt lgkmcnt(0)
	v_mfma_i32_16x16x64_i8 v[60:63], v[144:147], v[194:197], v[60:63]
	v_mfma_i32_16x16x64_i8 v[56:59], v[170:173], v[194:197], v[56:59]
	v_mfma_i32_16x16x64_i8 v[44:47], v[144:147], v[202:205], v[44:47]
	v_mfma_i32_16x16x64_i8 v[40:43], v[170:173], v[202:205], v[40:43]
	v_mfma_i32_16x16x64_i8 v[28:31], v[144:147], v[210:213], v[28:31]
	v_mfma_i32_16x16x64_i8 v[24:27], v[170:173], v[210:213], v[24:27]
	v_mfma_i32_16x16x64_i8 v[12:15], v[144:147], v[218:221], v[12:15]
	v_mfma_i32_16x16x64_i8 v[8:11], v[170:173], v[218:221], v[8:11]
	v_mfma_i32_16x16x64_i8 v[60:63], v[148:151], v[198:201], v[60:63]
	v_mfma_i32_16x16x64_i8 v[56:59], v[174:177], v[198:201], v[56:59]
	v_mfma_i32_16x16x64_i8 v[44:47], v[148:151], v[206:209], v[44:47]
	v_mfma_i32_16x16x64_i8 v[40:43], v[174:177], v[206:209], v[40:43]
	v_mfma_i32_16x16x64_i8 v[28:31], v[148:151], v[214:217], v[28:31]
	v_mfma_i32_16x16x64_i8 v[24:27], v[174:177], v[214:217], v[24:27]
	v_mfma_i32_16x16x64_i8 v[12:15], v[148:151], v[222:225], v[12:15]
	v_mfma_i32_16x16x64_i8 v[8:11], v[174:177], v[222:225], v[8:11]
	v_mfma_i32_16x16x64_i8 v[52:55], v[178:181], v[194:197], v[52:55]
	v_mfma_i32_16x16x64_i8 v[48:51], v[186:189], v[194:197], v[48:51]
	v_mfma_i32_16x16x64_i8 v[36:39], v[178:181], v[202:205], v[36:39]
	v_mfma_i32_16x16x64_i8 v[32:35], v[186:189], v[202:205], v[32:35]
	v_mfma_i32_16x16x64_i8 v[20:23], v[178:181], v[210:213], v[20:23]
	v_mfma_i32_16x16x64_i8 v[16:19], v[186:189], v[210:213], v[16:19]
	v_mfma_i32_16x16x64_i8 v[4:7], v[178:181], v[218:221], v[4:7]
	v_mfma_i32_16x16x64_i8 v[0:3], v[186:189], v[218:221], v[0:3]
	v_mfma_i32_16x16x64_i8 v[52:55], v[182:185], v[198:201], v[52:55]
	v_mfma_i32_16x16x64_i8 v[48:51], v[190:193], v[198:201], v[48:51]
	v_mfma_i32_16x16x64_i8 v[36:39], v[182:185], v[206:209], v[36:39]
	v_mfma_i32_16x16x64_i8 v[32:35], v[190:193], v[206:209], v[32:35]
	v_mfma_i32_16x16x64_i8 v[20:23], v[182:185], v[214:217], v[20:23]
	v_mfma_i32_16x16x64_i8 v[16:19], v[190:193], v[214:217], v[16:19]
	v_mfma_i32_16x16x64_i8 v[4:7], v[182:185], v[222:225], v[4:7]
	v_mfma_i32_16x16x64_i8 v[0:3], v[190:193], v[222:225], v[0:3]
	s_barrier
	s_add_i32 s64, s64, 2
	s_add_u32 s62, s62, 0x100
	s_addc_u32 s63, s63, 0
	s_add_u32 s4, s4, 0x100
	s_addc_u32 s5, s5, 0
	s_cmp_gt_u32 s64, 29
	s_cbranch_scc0 .LBB0_550
	s_setprio 0
	s_and_b64 vcc, exec, s[18:19]
	s_cbranch_vccz .LBB0_553
	s_barrier

.LBB0_634:
	s_ashr_i32 s21, s20, 31
	s_mul_i32 s22, s20, 0x810000
	s_mov_b32 s23, 0
	s_add_u32 s22, s33, s22
	s_addc_u32 s23, s38, s23
	s_and_b64 s[24:25], s[4:5], exec
	s_cselect_b32 s21, s23, s35
	s_cselect_b32 s27, s22, s34
	s_ashr_i32 s19, s18, 31
	s_lshl_b64 s[24:25], s[18:19], 23
	s_add_u32 s24, s39, s24
	s_addc_u32 s25, s40, s25
	s_and_b64 s[36:37], s[4:5], exec
	s_cselect_b32 s19, s25, s31
	s_cselect_b32 s55, s24, s30
	s_add_u32 s56, s30, 0x100
	s_addc_u32 s57, s31, 0
	s_add_u32 s30, s34, 0x408080
	v_mov_b32_e32 v0, 0
	s_addc_u32 s31, s35, 0
	s_mov_b32 s58, -2
	s_waitcnt lgkmcnt(0)
	v_mov_b32_e32 v1, v0
	v_mov_b32_e32 v2, v0
	v_mov_b32_e32 v3, v0
	v_mov_b32_e32 v4, v0
	v_mov_b32_e32 v5, v0
	v_mov_b32_e32 v6, v0
	v_mov_b32_e32 v7, v0
	v_mov_b32_e32 v16, v0
	v_mov_b32_e32 v17, v0
	v_mov_b32_e32 v18, v0
	v_mov_b32_e32 v19, v0
	v_mov_b32_e32 v20, v0
	v_mov_b32_e32 v21, v0
	v_mov_b32_e32 v22, v0
	v_mov_b32_e32 v23, v0
	v_mov_b32_e32 v32, v0
	v_mov_b32_e32 v33, v0
	v_mov_b32_e32 v34, v0
	v_mov_b32_e32 v35, v0
	v_mov_b32_e32 v36, v0
	v_mov_b32_e32 v37, v0
	v_mov_b32_e32 v38, v0
	v_mov_b32_e32 v39, v0
	v_mov_b32_e32 v48, v0
	v_mov_b32_e32 v49, v0
	v_mov_b32_e32 v50, v0
	v_mov_b32_e32 v51, v0
	v_mov_b32_e32 v52, v0
	v_mov_b32_e32 v53, v0
	v_mov_b32_e32 v54, v0
	v_mov_b32_e32 v55, v0
	v_mov_b32_e32 v8, v0
	v_mov_b32_e32 v9, v0
	v_mov_b32_e32 v10, v0
	v_mov_b32_e32 v11, v0
	v_mov_b32_e32 v12, v0
	v_mov_b32_e32 v13, v0
	v_mov_b32_e32 v14, v0
	v_mov_b32_e32 v15, v0
	v_mov_b32_e32 v24, v0
	v_mov_b32_e32 v25, v0
	v_mov_b32_e32 v26, v0
	v_mov_b32_e32 v27, v0
	v_mov_b32_e32 v28, v0
	v_mov_b32_e32 v29, v0
	v_mov_b32_e32 v30, v0
	v_mov_b32_e32 v31, v0
	v_mov_b32_e32 v40, v0
	v_mov_b32_e32 v41, v0
	v_mov_b32_e32 v42, v0
	v_mov_b32_e32 v43, v0
	v_mov_b32_e32 v44, v0
	v_mov_b32_e32 v45, v0
	v_mov_b32_e32 v46, v0
	v_mov_b32_e32 v47, v0
	v_mov_b32_e32 v56, v0
	v_mov_b32_e32 v57, v0
	v_mov_b32_e32 v58, v0
	v_mov_b32_e32 v59, v0
	v_mov_b32_e32 v60, v0
	v_mov_b32_e32 v61, v0
	v_mov_b32_e32 v62, v0
	v_mov_b32_e32 v63, v0
	v_mov_b32_e32 v64, v0
	v_mov_b32_e32 v65, v0
	v_mov_b32_e32 v66, v0
	v_mov_b32_e32 v67, v0
	v_mov_b32_e32 v68, v0
	v_mov_b32_e32 v69, v0
	v_mov_b32_e32 v70, v0
	v_mov_b32_e32 v71, v0
	v_mov_b32_e32 v80, v0
	v_mov_b32_e32 v81, v0
	v_mov_b32_e32 v82, v0
	v_mov_b32_e32 v83, v0
	v_mov_b32_e32 v84, v0
	v_mov_b32_e32 v85, v0
	v_mov_b32_e32 v86, v0
	v_mov_b32_e32 v87, v0
	v_mov_b32_e32 v96, v0
	v_mov_b32_e32 v97, v0
	v_mov_b32_e32 v98, v0
	v_mov_b32_e32 v99, v0
	v_mov_b32_e32 v100, v0
	v_mov_b32_e32 v101, v0
	v_mov_b32_e32 v102, v0
	v_mov_b32_e32 v103, v0
	v_mov_b32_e32 v116, v0
	v_mov_b32_e32 v117, v0
	v_mov_b32_e32 v118, v0
	v_mov_b32_e32 v119, v0
	v_mov_b32_e32 v120, v0
	v_mov_b32_e32 v121, v0
	v_mov_b32_e32 v122, v0
	v_mov_b32_e32 v123, v0
	v_mov_b32_e32 v72, v0
	v_mov_b32_e32 v73, v0
	v_mov_b32_e32 v74, v0
	v_mov_b32_e32 v75, v0
	v_mov_b32_e32 v76, v0
	v_mov_b32_e32 v77, v0
	v_mov_b32_e32 v78, v0
	v_mov_b32_e32 v79, v0
	v_mov_b32_e32 v88, v0
	v_mov_b32_e32 v89, v0
	v_mov_b32_e32 v90, v0
	v_mov_b32_e32 v91, v0
	v_mov_b32_e32 v92, v0
	v_mov_b32_e32 v93, v0
	v_mov_b32_e32 v94, v0
	v_mov_b32_e32 v95, v0
	v_mov_b32_e32 v104, v0
	v_mov_b32_e32 v105, v0
	v_mov_b32_e32 v106, v0
	v_mov_b32_e32 v107, v0
	v_mov_b32_e32 v108, v0
	v_mov_b32_e32 v109, v0
	v_mov_b32_e32 v110, v0
	v_mov_b32_e32 v111, v0
	v_mov_b32_e32 v128, v0
	v_mov_b32_e32 v129, v0
	v_mov_b32_e32 v130, v0
	v_mov_b32_e32 v131, v0
	v_mov_b32_e32 v132, v0
	v_mov_b32_e32 v133, v0
	v_mov_b32_e32 v134, v0
	v_mov_b32_e32 v135, v0
	v_add_u32_e32 v248, 0x18000, v191
	v_add_u32_e32 v249, 0x1c000, v191
	s_cmp_lt_u32 s81, 4
	s_cbranch_scc0 .Lsp_skip5
	s_setprio 1
.Lsp_skip5:
.LBB0_635:
	ds_read_b128 v[112:115], v193
	ds_read_b128 v[124:127], v193 offset:1024
	ds_read_b128 v[136:139], v193 offset:2048
	ds_read_b128 v[140:143], v193 offset:3072
	ds_read_b128 v[144:147], v194
	ds_read_b128 v[148:151], v194 offset:1024
	ds_read_b128 v[168:171], v194 offset:2048
	ds_read_b128 v[172:175], v194 offset:3072
	ds_read_b128 v[176:179], v195
	ds_read_b128 v[180:183], v195 offset:1024
	ds_read_b128 v[184:187], v195 offset:2048
	ds_read_b128 v[200:203], v195 offset:3072
	ds_read_b128 v[204:207], v195 offset:4096
	ds_read_b128 v[208:211], v195 offset:5120
	ds_read_b128 v[212:215], v195 offset:6144
	ds_read_b128 v[216:219], v195 offset:7168
	s_add_u32 s34, s30, 0xffbf8080
	s_addc_u32 s35, s31, -1
	s_cmpk_eq_i32 s58, 0xfc
	s_cselect_b32 s37, s21, s35
	s_cselect_b32 s36, s27, s34
	s_cselect_b32 s35, s19, s57
	s_cselect_b32 s34, s55, s56
	s_add_i32 m0, s29, 0xc000
	s_nop 0
	global_load_lds_dwordx4 v162, s[30:31]
	s_add_i32 m0, s29, 0xe000
	s_nop 0
	global_load_lds_dwordx4 v160, s[30:31]
	s_waitcnt vmcnt(8)
	s_waitcnt lgkmcnt(0)
	s_barrier
	s_waitcnt lgkmcnt(0)
	v_mfma_f32_16x16x32_bf16 v[132:135], v[112:115], v[176:179], v[132:135]
	v_mfma_f32_16x16x32_bf16 v[128:131], v[136:139], v[176:179], v[128:131]
	v_mfma_f32_16x16x32_bf16 v[108:111], v[112:115], v[184:187], v[108:111]
	v_mfma_f32_16x16x32_bf16 v[104:107], v[136:139], v[184:187], v[104:107]
	s_add_u32 s98, s34, s14
	s_addc_u32 s99, s35, s15
	s_add_i32 s59, s50, s41
	v_mfma_f32_16x16x32_bf16 v[92:95], v[112:115], v[204:207], v[92:95]
	s_add_u32 s100, s36, s14
	s_addc_u32 s101, s37, s15
	v_mfma_f32_16x16x32_bf16 v[88:91], v[136:139], v[204:207], v[88:91]
	v_mfma_f32_16x16x32_bf16 v[76:79], v[112:115], v[212:215], v[76:79]
	v_mfma_f32_16x16x32_bf16 v[72:75], v[136:139], v[212:215], v[72:75]
	s_add_u32 s60, s34, 0x400000
	v_mfma_f32_16x16x32_bf16 v[132:135], v[124:127], v[180:183], v[132:135]
	v_mfma_f32_16x16x32_bf16 v[128:131], v[140:143], v[180:183], v[128:131]
	v_mfma_f32_16x16x32_bf16 v[108:111], v[124:127], v[200:203], v[108:111]
	v_mfma_f32_16x16x32_bf16 v[104:107], v[140:143], v[200:203], v[104:107]
	s_addc_u32 s61, s35, 0
	v_mfma_f32_16x16x32_bf16 v[92:95], v[124:127], v[208:211], v[92:95]
	v_mfma_f32_16x16x32_bf16 v[88:91], v[140:143], v[208:211], v[88:91]
	v_mfma_f32_16x16x32_bf16 v[76:79], v[124:127], v[216:219], v[76:79]
	v_mfma_f32_16x16x32_bf16 v[72:75], v[140:143], v[216:219], v[72:75]
	v_mfma_f32_16x16x32_bf16 v[120:123], v[144:147], v[176:179], v[120:123]
	v_mfma_f32_16x16x32_bf16 v[116:119], v[168:171], v[176:179], v[116:119]
	v_mfma_f32_16x16x32_bf16 v[100:103], v[144:147], v[184:187], v[100:103]
	v_mfma_f32_16x16x32_bf16 v[96:99], v[168:171], v[184:187], v[96:99]
	v_mfma_f32_16x16x32_bf16 v[84:87], v[144:147], v[204:207], v[84:87]
	v_mfma_f32_16x16x32_bf16 v[80:83], v[168:171], v[204:207], v[80:83]
	v_mfma_f32_16x16x32_bf16 v[68:71], v[144:147], v[212:215], v[68:71]
	v_mfma_f32_16x16x32_bf16 v[64:67], v[168:171], v[212:215], v[64:67]
	v_mfma_f32_16x16x32_bf16 v[120:123], v[148:151], v[180:183], v[120:123]
	v_mfma_f32_16x16x32_bf16 v[116:119], v[172:175], v[180:183], v[116:119]
	v_mfma_f32_16x16x32_bf16 v[100:103], v[148:151], v[200:203], v[100:103]
	v_mfma_f32_16x16x32_bf16 v[96:99], v[172:175], v[200:203], v[96:99]
	v_mfma_f32_16x16x32_bf16 v[84:87], v[148:151], v[208:211], v[84:87]
	v_mfma_f32_16x16x32_bf16 v[80:83], v[172:175], v[208:211], v[80:83]
	v_mfma_f32_16x16x32_bf16 v[68:71], v[148:151], v[216:219], v[68:71]
	v_mfma_f32_16x16x32_bf16 v[64:67], v[172:175], v[216:219], v[64:67]
	s_barrier
	ds_read_b128 v[176:179], v195 offset:16384
	ds_read_b128 v[180:183], v195 offset:17408
	ds_read_b128 v[184:187], v195 offset:18432
	ds_read_b128 v[200:203], v195 offset:19456
	ds_read_b128 v[204:207], v195 offset:20480
	ds_read_b128 v[208:211], v195 offset:21504
	ds_read_b128 v[212:215], v195 offset:22528
	ds_read_b128 v[216:219], v195 offset:23552
	s_mov_b32 m0, s59
	s_nop 0
	global_load_lds_dwordx4 v154, s[34:35]
	s_add_i32 m0, s59, 0x2000
	s_add_i32 s59, s51, s41
	global_load_lds_dwordx4 v158, s[34:35]
	s_mov_b32 m0, s59
	s_nop 0
	global_load_lds_dwordx4 v154, s[60:61]
	s_add_i32 m0, s59, 0x2000
	s_nop 0
	global_load_lds_dwordx4 v158, s[60:61]
	s_mov_b32 m0, s29
	s_nop 0
	global_load_lds_dwordx4 v152, s[36:37]
	s_mov_b32 m0, s42
	s_nop 0
	global_load_lds_dwordx4 v156, s[36:37]
	s_waitcnt vmcnt(8)
	s_waitcnt lgkmcnt(0)
	s_barrier
	s_waitcnt lgkmcnt(0)
	v_mfma_f32_16x16x32_bf16 v[60:63], v[112:115], v[176:179], v[60:63]
	v_mfma_f32_16x16x32_bf16 v[56:59], v[136:139], v[176:179], v[56:59]
	v_mfma_f32_16x16x32_bf16 v[44:47], v[112:115], v[184:187], v[44:47]
	v_mfma_f32_16x16x32_bf16 v[40:43], v[136:139], v[184:187], v[40:43]
	s_add_i32 s59, 0, 0x18000
	v_mfma_f32_16x16x32_bf16 v[28:31], v[112:115], v[204:207], v[28:31]
	v_mfma_f32_16x16x32_bf16 v[24:27], v[136:139], v[204:207], v[24:27]
	s_add_i32 s60, 0, 0x1c000
	v_mfma_f32_16x16x32_bf16 v[12:15], v[112:115], v[212:215], v[12:15]
	v_mfma_f32_16x16x32_bf16 v[8:11], v[136:139], v[212:215], v[8:11]
	s_add_u32 s36, s36, 0x408000
	v_mfma_f32_16x16x32_bf16 v[60:63], v[124:127], v[180:183], v[60:63]
	v_mfma_f32_16x16x32_bf16 v[56:59], v[140:143], v[180:183], v[56:59]
	s_addc_u32 s37, s37, 0
	v_mfma_f32_16x16x32_bf16 v[44:47], v[124:127], v[200:203], v[44:47]
	v_mfma_f32_16x16x32_bf16 v[40:43], v[140:143], v[200:203], v[40:43]
	v_mfma_f32_16x16x32_bf16 v[28:31], v[124:127], v[208:211], v[28:31]
	v_mfma_f32_16x16x32_bf16 v[24:27], v[140:143], v[208:211], v[24:27]
	v_mfma_f32_16x16x32_bf16 v[12:15], v[124:127], v[216:219], v[12:15]
	v_mfma_f32_16x16x32_bf16 v[8:11], v[140:143], v[216:219], v[8:11]
	v_mfma_f32_16x16x32_bf16 v[52:55], v[144:147], v[176:179], v[52:55]
	v_mfma_f32_16x16x32_bf16 v[48:51], v[168:171], v[176:179], v[48:51]
	v_mfma_f32_16x16x32_bf16 v[36:39], v[144:147], v[184:187], v[36:39]
	v_mfma_f32_16x16x32_bf16 v[32:35], v[168:171], v[184:187], v[32:35]
	v_mfma_f32_16x16x32_bf16 v[20:23], v[144:147], v[204:207], v[20:23]
	v_mfma_f32_16x16x32_bf16 v[16:19], v[168:171], v[204:207], v[16:19]
	v_mfma_f32_16x16x32_bf16 v[4:7], v[144:147], v[212:215], v[4:7]
	v_mfma_f32_16x16x32_bf16 v[0:3], v[168:171], v[212:215], v[0:3]
	v_mfma_f32_16x16x32_bf16 v[52:55], v[148:151], v[180:183], v[52:55]
	v_mfma_f32_16x16x32_bf16 v[48:51], v[172:175], v[180:183], v[48:51]
	v_mfma_f32_16x16x32_bf16 v[36:39], v[148:151], v[200:203], v[36:39]
	v_mfma_f32_16x16x32_bf16 v[32:35], v[172:175], v[200:203], v[32:35]
	v_mfma_f32_16x16x32_bf16 v[20:23], v[148:151], v[208:211], v[20:23]
	v_mfma_f32_16x16x32_bf16 v[16:19], v[172:175], v[208:211], v[16:19]
	v_mfma_f32_16x16x32_bf16 v[4:7], v[148:151], v[216:219], v[4:7]
	v_mfma_f32_16x16x32_bf16 v[0:3], v[172:175], v[216:219], v[0:3]
	s_barrier
	ds_read_b128 v[176:179], v195 offset:32768
	ds_read_b128 v[180:183], v195 offset:33792
	ds_read_b128 v[184:187], v195 offset:34816
	ds_read_b128 v[200:203], v195 offset:35840
	ds_read_b128 v[204:207], v195 offset:36864
	ds_read_b128 v[208:211], v195 offset:37888
	ds_read_b128 v[212:215], v195 offset:38912
	ds_read_b128 v[216:219], v195 offset:39936
	ds_read_b128 v[112:115], v248
	ds_read_b128 v[124:127], v248 offset:1024
	ds_read_b128 v[136:139], v248 offset:2048
	ds_read_b128 v[140:143], v248 offset:3072
	ds_read_b128 v[144:147], v249
	ds_read_b128 v[148:151], v249 offset:1024
	ds_read_b128 v[168:171], v249 offset:2048
	ds_read_b128 v[172:175], v249 offset:3072
	s_mov_b32 m0, s43
	s_nop 0
	global_load_lds_dwordx4 v152, s[36:37]
	s_mov_b32 m0, s44
	s_nop 0
	global_load_lds_dwordx4 v156, s[36:37]
	s_waitcnt vmcnt(8)
	s_waitcnt lgkmcnt(0)
	s_barrier
	s_waitcnt lgkmcnt(0)
	v_mfma_f32_16x16x32_bf16 v[132:135], v[112:115], v[176:179], v[132:135]
	v_mfma_f32_16x16x32_bf16 v[128:131], v[136:139], v[176:179], v[128:131]
	v_mfma_f32_16x16x32_bf16 v[108:111], v[112:115], v[184:187], v[108:111]
	v_mfma_f32_16x16x32_bf16 v[104:107], v[136:139], v[184:187], v[104:107]
	s_add_i32 s36, s59, s41
	v_mfma_f32_16x16x32_bf16 v[92:95], v[112:115], v[204:207], v[92:95]
	v_mfma_f32_16x16x32_bf16 v[88:91], v[136:139], v[204:207], v[88:91]
	v_mfma_f32_16x16x32_bf16 v[76:79], v[112:115], v[212:215], v[76:79]
	v_mfma_f32_16x16x32_bf16 v[72:75], v[136:139], v[212:215], v[72:75]
	s_add_u32 s34, s34, 0x400080
	v_mfma_f32_16x16x32_bf16 v[132:135], v[124:127], v[180:183], v[132:135]
	v_mfma_f32_16x16x32_bf16 v[128:131], v[140:143], v[180:183], v[128:131]
	v_mfma_f32_16x16x32_bf16 v[108:111], v[124:127], v[200:203], v[108:111]
	v_mfma_f32_16x16x32_bf16 v[104:107], v[140:143], v[200:203], v[104:107]
	s_addc_u32 s35, s35, 0
	v_mfma_f32_16x16x32_bf16 v[92:95], v[124:127], v[208:211], v[92:95]
	v_mfma_f32_16x16x32_bf16 v[88:91], v[140:143], v[208:211], v[88:91]
	v_mfma_f32_16x16x32_bf16 v[76:79], v[124:127], v[216:219], v[76:79]
	v_mfma_f32_16x16x32_bf16 v[72:75], v[140:143], v[216:219], v[72:75]
	v_mfma_f32_16x16x32_bf16 v[120:123], v[144:147], v[176:179], v[120:123]
	v_mfma_f32_16x16x32_bf16 v[116:119], v[168:171], v[176:179], v[116:119]
	v_mfma_f32_16x16x32_bf16 v[100:103], v[144:147], v[184:187], v[100:103]
	v_mfma_f32_16x16x32_bf16 v[96:99], v[168:171], v[184:187], v[96:99]
	v_mfma_f32_16x16x32_bf16 v[84:87], v[144:147], v[204:207], v[84:87]
	v_mfma_f32_16x16x32_bf16 v[80:83], v[168:171], v[204:207], v[80:83]
	v_mfma_f32_16x16x32_bf16 v[68:71], v[144:147], v[212:215], v[68:71]
	v_mfma_f32_16x16x32_bf16 v[64:67], v[168:171], v[212:215], v[64:67]
	v_mfma_f32_16x16x32_bf16 v[120:123], v[148:151], v[180:183], v[120:123]
	v_mfma_f32_16x16x32_bf16 v[116:119], v[172:175], v[180:183], v[116:119]
	v_mfma_f32_16x16x32_bf16 v[100:103], v[148:151], v[200:203], v[100:103]
	v_mfma_f32_16x16x32_bf16 v[96:99], v[172:175], v[200:203], v[96:99]
	v_mfma_f32_16x16x32_bf16 v[84:87], v[148:151], v[208:211], v[84:87]
	v_mfma_f32_16x16x32_bf16 v[80:83], v[172:175], v[208:211], v[80:83]
	v_mfma_f32_16x16x32_bf16 v[68:71], v[148:151], v[216:219], v[68:71]
	v_mfma_f32_16x16x32_bf16 v[64:67], v[172:175], v[216:219], v[64:67]
	s_barrier
	ds_read_b128 v[176:179], v195 offset:49152
	ds_read_b128 v[180:183], v195 offset:50176
	ds_read_b128 v[184:187], v195 offset:51200
	ds_read_b128 v[200:203], v195 offset:52224
	ds_read_b128 v[204:207], v195 offset:53248
	ds_read_b128 v[208:211], v195 offset:54272
	ds_read_b128 v[212:215], v195 offset:55296
	ds_read_b128 v[216:219], v195 offset:56320
	s_mov_b32 m0, s36
	s_nop 0
	global_load_lds_dwordx4 v154, s[98:99]
	s_add_i32 m0, s36, 0x2000
	s_add_i32 s36, s60, s41
	global_load_lds_dwordx4 v158, s[98:99]
	s_mov_b32 m0, s36
	s_nop 0
	global_load_lds_dwordx4 v154, s[34:35]
	s_add_i32 m0, s36, 0x2000
	s_nop 0
	global_load_lds_dwordx4 v158, s[34:35]
	s_mov_b32 m0, s46
	s_nop 0
	global_load_lds_dwordx4 v152, s[100:101]
	s_mov_b32 m0, s47
	s_nop 0
	global_load_lds_dwordx4 v156, s[100:101]
	s_waitcnt vmcnt(8)
	s_waitcnt lgkmcnt(0)
	s_barrier
	s_waitcnt lgkmcnt(0)
	v_mfma_f32_16x16x32_bf16 v[60:63], v[112:115], v[176:179], v[60:63]
	v_mfma_f32_16x16x32_bf16 v[56:59], v[136:139], v[176:179], v[56:59]
	v_mfma_f32_16x16x32_bf16 v[44:47], v[112:115], v[184:187], v[44:47]
	v_mfma_f32_16x16x32_bf16 v[40:43], v[136:139], v[184:187], v[40:43]
	v_mfma_f32_16x16x32_bf16 v[28:31], v[112:115], v[204:207], v[28:31]
	v_mfma_f32_16x16x32_bf16 v[24:27], v[136:139], v[204:207], v[24:27]
	v_mfma_f32_16x16x32_bf16 v[12:15], v[112:115], v[212:215], v[12:15]
	v_mfma_f32_16x16x32_bf16 v[8:11], v[136:139], v[212:215], v[8:11]
	v_mfma_f32_16x16x32_bf16 v[60:63], v[124:127], v[180:183], v[60:63]
	v_mfma_f32_16x16x32_bf16 v[56:59], v[140:143], v[180:183], v[56:59]
	v_mfma_f32_16x16x32_bf16 v[44:47], v[124:127], v[200:203], v[44:47]
	v_mfma_f32_16x16x32_bf16 v[40:43], v[140:143], v[200:203], v[40:43]
	v_mfma_f32_16x16x32_bf16 v[28:31], v[124:127], v[208:211], v[28:31]
	v_mfma_f32_16x16x32_bf16 v[24:27], v[140:143], v[208:211], v[24:27]
	v_mfma_f32_16x16x32_bf16 v[12:15], v[124:127], v[216:219], v[12:15]
	v_mfma_f32_16x16x32_bf16 v[8:11], v[140:143], v[216:219], v[8:11]
	v_mfma_f32_16x16x32_bf16 v[52:55], v[144:147], v[176:179], v[52:55]
	v_mfma_f32_16x16x32_bf16 v[48:51], v[168:171], v[176:179], v[48:51]
	v_mfma_f32_16x16x32_bf16 v[36:39], v[144:147], v[184:187], v[36:39]
	v_mfma_f32_16x16x32_bf16 v[32:35], v[168:171], v[184:187], v[32:35]
	v_mfma_f32_16x16x32_bf16 v[20:23], v[144:147], v[204:207], v[20:23]
	v_mfma_f32_16x16x32_bf16 v[16:19], v[168:171], v[204:207], v[16:19]
	v_mfma_f32_16x16x32_bf16 v[4:7], v[144:147], v[212:215], v[4:7]
	v_mfma_f32_16x16x32_bf16 v[0:3], v[168:171], v[212:215], v[0:3]
	v_mfma_f32_16x16x32_bf16 v[52:55], v[148:151], v[180:183], v[52:55]
	v_mfma_f32_16x16x32_bf16 v[48:51], v[172:175], v[180:183], v[48:51]
	v_mfma_f32_16x16x32_bf16 v[36:39], v[148:151], v[200:203], v[36:39]
	v_mfma_f32_16x16x32_bf16 v[32:35], v[172:175], v[200:203], v[32:35]
	v_mfma_f32_16x16x32_bf16 v[20:23], v[148:151], v[208:211], v[20:23]
	v_mfma_f32_16x16x32_bf16 v[16:19], v[172:175], v[208:211], v[16:19]
	v_mfma_f32_16x16x32_bf16 v[4:7], v[148:151], v[216:219], v[4:7]
	v_mfma_f32_16x16x32_bf16 v[0:3], v[172:175], v[216:219], v[0:3]
	s_barrier
	s_add_i32 s58, s58, 2
	s_add_u32 s56, s56, 0x100
	s_addc_u32 s57, s57, 0
	s_add_u32 s30, s30, 0x100
	s_addc_u32 s31, s31, 0
	s_cmpk_gt_u32 s58, 0xfd
	s_cbranch_scc0 .LBB0_635
	s_setprio 0
	s_and_b64 vcc, exec, s[16:17]
	s_cbranch_vccz .LBB0_638
	s_barrier

.LBB0_725:
	s_ashr_i32 s23, s22, 31
	s_lshl_b64 s[24:25], s[22:23], 20
	s_add_u32 s24, s30, s24
	s_addc_u32 s25, s31, s25
	s_and_b64 s[26:27], s[2:3], exec
	s_cselect_b32 s1, s25, s7
	s_cselect_b32 s23, s24, s6
	s_ashr_i32 s21, s20, 31
	s_lshl_b64 s[26:27], s[20:21], 20
	s_add_u32 s26, s33, s26
	s_addc_u32 s27, s34, s27
	s_and_b64 s[28:29], s[2:3], exec
	s_cselect_b32 s21, s27, s5
	s_cselect_b32 s51, s26, s4
	s_add_u32 s52, s4, 0x100
	s_addc_u32 s53, s5, 0
	s_add_u32 s4, s6, 0x80080
	v_mov_b32_e32 v0, 0
	s_addc_u32 s5, s7, 0
	s_mov_b32 s54, -2
	v_mov_b32_e32 v1, v0
	v_mov_b32_e32 v2, v0
	v_mov_b32_e32 v3, v0
	v_mov_b32_e32 v4, v0
	v_mov_b32_e32 v5, v0
	v_mov_b32_e32 v6, v0
	v_mov_b32_e32 v7, v0
	v_mov_b32_e32 v16, v0
	v_mov_b32_e32 v17, v0
	v_mov_b32_e32 v18, v0
	v_mov_b32_e32 v19, v0
	v_mov_b32_e32 v20, v0
	v_mov_b32_e32 v21, v0
	v_mov_b32_e32 v22, v0
	v_mov_b32_e32 v23, v0
	v_mov_b32_e32 v32, v0
	v_mov_b32_e32 v33, v0
	v_mov_b32_e32 v34, v0
	v_mov_b32_e32 v35, v0
	v_mov_b32_e32 v36, v0
	v_mov_b32_e32 v37, v0
	v_mov_b32_e32 v38, v0
	v_mov_b32_e32 v39, v0
	v_mov_b32_e32 v48, v0
	v_mov_b32_e32 v49, v0
	v_mov_b32_e32 v50, v0
	v_mov_b32_e32 v51, v0
	v_mov_b32_e32 v52, v0
	v_mov_b32_e32 v53, v0
	v_mov_b32_e32 v54, v0
	v_mov_b32_e32 v55, v0
	v_mov_b32_e32 v8, v0
	v_mov_b32_e32 v9, v0
	v_mov_b32_e32 v10, v0
	v_mov_b32_e32 v11, v0
	v_mov_b32_e32 v12, v0
	v_mov_b32_e32 v13, v0
	v_mov_b32_e32 v14, v0
	v_mov_b32_e32 v15, v0
	v_mov_b32_e32 v24, v0
	v_mov_b32_e32 v25, v0
	v_mov_b32_e32 v26, v0
	v_mov_b32_e32 v27, v0
	v_mov_b32_e32 v28, v0
	v_mov_b32_e32 v29, v0
	v_mov_b32_e32 v30, v0
	v_mov_b32_e32 v31, v0
	v_mov_b32_e32 v40, v0
	v_mov_b32_e32 v41, v0
	v_mov_b32_e32 v42, v0
	v_mov_b32_e32 v43, v0
	v_mov_b32_e32 v44, v0
	v_mov_b32_e32 v45, v0
	v_mov_b32_e32 v46, v0
	v_mov_b32_e32 v47, v0
	v_mov_b32_e32 v56, v0
	v_mov_b32_e32 v57, v0
	v_mov_b32_e32 v58, v0
	v_mov_b32_e32 v59, v0
	v_mov_b32_e32 v60, v0
	v_mov_b32_e32 v61, v0
	v_mov_b32_e32 v62, v0
	v_mov_b32_e32 v63, v0
	v_mov_b32_e32 v64, v0
	v_mov_b32_e32 v65, v0
	v_mov_b32_e32 v66, v0
	v_mov_b32_e32 v67, v0
	v_mov_b32_e32 v68, v0
	v_mov_b32_e32 v69, v0
	v_mov_b32_e32 v70, v0
	v_mov_b32_e32 v71, v0
	v_mov_b32_e32 v80, v0
	v_mov_b32_e32 v81, v0
	v_mov_b32_e32 v82, v0
	v_mov_b32_e32 v83, v0
	v_mov_b32_e32 v84, v0
	v_mov_b32_e32 v85, v0
	v_mov_b32_e32 v86, v0
	v_mov_b32_e32 v87, v0
	v_mov_b32_e32 v96, v0
	v_mov_b32_e32 v97, v0
	v_mov_b32_e32 v98, v0
	v_mov_b32_e32 v99, v0
	v_mov_b32_e32 v100, v0
	v_mov_b32_e32 v101, v0
	v_mov_b32_e32 v102, v0
	v_mov_b32_e32 v103, v0
	v_mov_b32_e32 v112, v0
	v_mov_b32_e32 v113, v0
	v_mov_b32_e32 v114, v0
	v_mov_b32_e32 v115, v0
	v_mov_b32_e32 v116, v0
	v_mov_b32_e32 v117, v0
	v_mov_b32_e32 v118, v0
	v_mov_b32_e32 v119, v0
	v_mov_b32_e32 v72, v0
	v_mov_b32_e32 v73, v0
	v_mov_b32_e32 v74, v0
	v_mov_b32_e32 v75, v0
	v_mov_b32_e32 v76, v0
	v_mov_b32_e32 v77, v0
	v_mov_b32_e32 v78, v0
	v_mov_b32_e32 v79, v0
	v_mov_b32_e32 v88, v0
	v_mov_b32_e32 v89, v0
	v_mov_b32_e32 v90, v0
	v_mov_b32_e32 v91, v0
	v_mov_b32_e32 v92, v0
	v_mov_b32_e32 v93, v0
	v_mov_b32_e32 v94, v0
	v_mov_b32_e32 v95, v0
	v_mov_b32_e32 v104, v0
	v_mov_b32_e32 v105, v0
	v_mov_b32_e32 v106, v0
	v_mov_b32_e32 v107, v0
	v_mov_b32_e32 v108, v0
	v_mov_b32_e32 v109, v0
	v_mov_b32_e32 v110, v0
	v_mov_b32_e32 v111, v0
	v_mov_b32_e32 v120, v0
	v_mov_b32_e32 v121, v0
	v_mov_b32_e32 v122, v0
	v_mov_b32_e32 v123, v0
	v_mov_b32_e32 v124, v0
	v_mov_b32_e32 v125, v0
	v_mov_b32_e32 v126, v0
	v_mov_b32_e32 v127, v0
	v_add_u32_e32 v248, 0x18000, v157
	v_add_u32_e32 v249, 0x1c000, v157
	s_cmp_lt_u32 s81, 4
	s_cbranch_scc0 .Lsp_skip6
	s_setprio 1
.Lsp_skip6:
.LBB0_726:
	ds_read_b128 v[144:147], v161
	ds_read_b128 v[148:151], v161 offset:1024
	ds_read_b128 v[168:171], v161 offset:2048
	ds_read_b128 v[172:175], v161 offset:3072
	ds_read_b128 v[176:179], v163
	ds_read_b128 v[180:183], v163 offset:1024
	ds_read_b128 v[184:187], v163 offset:2048
	ds_read_b128 v[188:191], v163 offset:3072
	ds_read_b128 v[192:195], v165
	ds_read_b128 v[196:199], v165 offset:1024
	ds_read_b128 v[200:203], v165 offset:2048
	ds_read_b128 v[204:207], v165 offset:3072
	ds_read_b128 v[208:211], v165 offset:4096
	ds_read_b128 v[212:215], v165 offset:5120
	ds_read_b128 v[216:219], v165 offset:6144
	ds_read_b128 v[220:223], v165 offset:7168
	s_add_u32 s6, s4, 0xfff80080
	s_addc_u32 s7, s5, -1
	s_cmp_eq_u32 s54, 28
	s_cselect_b32 s29, s1, s7
	s_cselect_b32 s28, s23, s6
	s_cselect_b32 s7, s21, s53
	s_cselect_b32 s6, s51, s52
	s_add_i32 m0, s38, 0xc000
	s_nop 0
	global_load_lds_dwordx4 v138, s[4:5]
	s_add_i32 m0, s38, 0xe000
	s_nop 0
	global_load_lds_dwordx4 v136, s[4:5]
	s_waitcnt vmcnt(8)
	s_waitcnt lgkmcnt(0)
	s_barrier
	s_waitcnt lgkmcnt(0)
	v_mfma_i32_16x16x64_i8 v[124:127], v[144:147], v[192:195], v[124:127]
	v_mfma_i32_16x16x64_i8 v[120:123], v[168:171], v[192:195], v[120:123]
	v_mfma_i32_16x16x64_i8 v[108:111], v[144:147], v[200:203], v[108:111]
	v_mfma_i32_16x16x64_i8 v[104:107], v[168:171], v[200:203], v[104:107]
	s_add_u32 s98, s6, s16
	s_addc_u32 s99, s7, s17
	s_add_i32 s55, s46, s35
	v_mfma_i32_16x16x64_i8 v[92:95], v[144:147], v[208:211], v[92:95]
	s_add_u32 s100, s28, s16
	s_addc_u32 s101, s29, s17
	v_mfma_i32_16x16x64_i8 v[88:91], v[168:171], v[208:211], v[88:91]
	v_mfma_i32_16x16x64_i8 v[76:79], v[144:147], v[216:219], v[76:79]
	v_mfma_i32_16x16x64_i8 v[72:75], v[168:171], v[216:219], v[72:75]
	s_add_u32 s56, s6, 0x80000
	v_mfma_i32_16x16x64_i8 v[124:127], v[148:151], v[196:199], v[124:127]
	v_mfma_i32_16x16x64_i8 v[120:123], v[172:175], v[196:199], v[120:123]
	v_mfma_i32_16x16x64_i8 v[108:111], v[148:151], v[204:207], v[108:111]
	v_mfma_i32_16x16x64_i8 v[104:107], v[172:175], v[204:207], v[104:107]
	s_addc_u32 s57, s7, 0
	v_mfma_i32_16x16x64_i8 v[92:95], v[148:151], v[212:215], v[92:95]
	v_mfma_i32_16x16x64_i8 v[88:91], v[172:175], v[212:215], v[88:91]
	v_mfma_i32_16x16x64_i8 v[76:79], v[148:151], v[220:223], v[76:79]
	v_mfma_i32_16x16x64_i8 v[72:75], v[172:175], v[220:223], v[72:75]
	v_mfma_i32_16x16x64_i8 v[116:119], v[176:179], v[192:195], v[116:119]
	v_mfma_i32_16x16x64_i8 v[112:115], v[184:187], v[192:195], v[112:115]
	v_mfma_i32_16x16x64_i8 v[100:103], v[176:179], v[200:203], v[100:103]
	v_mfma_i32_16x16x64_i8 v[96:99], v[184:187], v[200:203], v[96:99]
	v_mfma_i32_16x16x64_i8 v[84:87], v[176:179], v[208:211], v[84:87]
	v_mfma_i32_16x16x64_i8 v[80:83], v[184:187], v[208:211], v[80:83]
	v_mfma_i32_16x16x64_i8 v[68:71], v[176:179], v[216:219], v[68:71]
	v_mfma_i32_16x16x64_i8 v[64:67], v[184:187], v[216:219], v[64:67]
	v_mfma_i32_16x16x64_i8 v[116:119], v[180:183], v[196:199], v[116:119]
	v_mfma_i32_16x16x64_i8 v[112:115], v[188:191], v[196:199], v[112:115]
	v_mfma_i32_16x16x64_i8 v[100:103], v[180:183], v[204:207], v[100:103]
	v_mfma_i32_16x16x64_i8 v[96:99], v[188:191], v[204:207], v[96:99]
	v_mfma_i32_16x16x64_i8 v[84:87], v[180:183], v[212:215], v[84:87]
	v_mfma_i32_16x16x64_i8 v[80:83], v[188:191], v[212:215], v[80:83]
	v_mfma_i32_16x16x64_i8 v[68:71], v[180:183], v[220:223], v[68:71]
	v_mfma_i32_16x16x64_i8 v[64:67], v[188:191], v[220:223], v[64:67]
	s_barrier
	ds_read_b128 v[192:195], v165 offset:16384
	ds_read_b128 v[196:199], v165 offset:17408
	ds_read_b128 v[200:203], v165 offset:18432
	ds_read_b128 v[204:207], v165 offset:19456
	ds_read_b128 v[208:211], v165 offset:20480
	ds_read_b128 v[212:215], v165 offset:21504
	ds_read_b128 v[216:219], v165 offset:22528
	ds_read_b128 v[220:223], v165 offset:23552
	s_mov_b32 m0, s55
	s_nop 0
	global_load_lds_dwordx4 v132, s[6:7]
	s_add_i32 m0, s55, 0x2000
	s_add_i32 s55, s47, s35
	global_load_lds_dwordx4 v128, s[6:7]
	s_mov_b32 m0, s55
	s_nop 0
	global_load_lds_dwordx4 v132, s[56:57]
	s_add_i32 m0, s55, 0x2000
	s_nop 0
	global_load_lds_dwordx4 v128, s[56:57]
	s_mov_b32 m0, s38
	s_nop 0
	global_load_lds_dwordx4 v134, s[28:29]
	s_mov_b32 m0, s39
	s_nop 0
	global_load_lds_dwordx4 v130, s[28:29]
	s_waitcnt vmcnt(8)
	s_waitcnt lgkmcnt(0)
	s_barrier
	s_waitcnt lgkmcnt(0)
	v_mfma_i32_16x16x64_i8 v[60:63], v[144:147], v[192:195], v[60:63]
	v_mfma_i32_16x16x64_i8 v[56:59], v[168:171], v[192:195], v[56:59]
	v_mfma_i32_16x16x64_i8 v[44:47], v[144:147], v[200:203], v[44:47]
	v_mfma_i32_16x16x64_i8 v[40:43], v[168:171], v[200:203], v[40:43]
	s_add_i32 s55, 0, 0x18000
	v_mfma_i32_16x16x64_i8 v[28:31], v[144:147], v[208:211], v[28:31]
	v_mfma_i32_16x16x64_i8 v[24:27], v[168:171], v[208:211], v[24:27]
	v_mfma_i32_16x16x64_i8 v[12:15], v[144:147], v[216:219], v[12:15]
	v_mfma_i32_16x16x64_i8 v[8:11], v[168:171], v[216:219], v[8:11]
	s_add_i32 s56, 0, 0x1c000
	v_mfma_i32_16x16x64_i8 v[60:63], v[148:151], v[196:199], v[60:63]
	v_mfma_i32_16x16x64_i8 v[56:59], v[172:175], v[196:199], v[56:59]
	s_add_u32 s28, s28, 0x80000
	v_mfma_i32_16x16x64_i8 v[44:47], v[148:151], v[204:207], v[44:47]
	v_mfma_i32_16x16x64_i8 v[40:43], v[172:175], v[204:207], v[40:43]
	s_addc_u32 s29, s29, 0
	v_mfma_i32_16x16x64_i8 v[28:31], v[148:151], v[212:215], v[28:31]
	v_mfma_i32_16x16x64_i8 v[24:27], v[172:175], v[212:215], v[24:27]
	v_mfma_i32_16x16x64_i8 v[12:15], v[148:151], v[220:223], v[12:15]
	v_mfma_i32_16x16x64_i8 v[8:11], v[172:175], v[220:223], v[8:11]
	v_mfma_i32_16x16x64_i8 v[52:55], v[176:179], v[192:195], v[52:55]
	v_mfma_i32_16x16x64_i8 v[48:51], v[184:187], v[192:195], v[48:51]
	v_mfma_i32_16x16x64_i8 v[36:39], v[176:179], v[200:203], v[36:39]
	v_mfma_i32_16x16x64_i8 v[32:35], v[184:187], v[200:203], v[32:35]
	v_mfma_i32_16x16x64_i8 v[20:23], v[176:179], v[208:211], v[20:23]
	v_mfma_i32_16x16x64_i8 v[16:19], v[184:187], v[208:211], v[16:19]
	v_mfma_i32_16x16x64_i8 v[4:7], v[176:179], v[216:219], v[4:7]
	v_mfma_i32_16x16x64_i8 v[0:3], v[184:187], v[216:219], v[0:3]
	v_mfma_i32_16x16x64_i8 v[52:55], v[180:183], v[196:199], v[52:55]
	v_mfma_i32_16x16x64_i8 v[48:51], v[188:191], v[196:199], v[48:51]
	v_mfma_i32_16x16x64_i8 v[36:39], v[180:183], v[204:207], v[36:39]
	v_mfma_i32_16x16x64_i8 v[32:35], v[188:191], v[204:207], v[32:35]
	v_mfma_i32_16x16x64_i8 v[20:23], v[180:183], v[212:215], v[20:23]
	v_mfma_i32_16x16x64_i8 v[16:19], v[188:191], v[212:215], v[16:19]
	v_mfma_i32_16x16x64_i8 v[4:7], v[180:183], v[220:223], v[4:7]
	v_mfma_i32_16x16x64_i8 v[0:3], v[188:191], v[220:223], v[0:3]
	s_barrier
	ds_read_b128 v[192:195], v165 offset:32768
	ds_read_b128 v[196:199], v165 offset:33792
	ds_read_b128 v[200:203], v165 offset:34816
	ds_read_b128 v[204:207], v165 offset:35840
	ds_read_b128 v[208:211], v165 offset:36864
	ds_read_b128 v[212:215], v165 offset:37888
	ds_read_b128 v[216:219], v165 offset:38912
	ds_read_b128 v[220:223], v165 offset:39936
	ds_read_b128 v[144:147], v248
	ds_read_b128 v[148:151], v248 offset:1024
	ds_read_b128 v[168:171], v248 offset:2048
	ds_read_b128 v[172:175], v248 offset:3072
	ds_read_b128 v[176:179], v249
	ds_read_b128 v[180:183], v249 offset:1024
	ds_read_b128 v[184:187], v249 offset:2048
	ds_read_b128 v[188:191], v249 offset:3072
	s_mov_b32 m0, s40
	s_nop 0
	global_load_lds_dwordx4 v134, s[28:29]
	s_mov_b32 m0, s41
	s_nop 0
	global_load_lds_dwordx4 v130, s[28:29]
	s_waitcnt vmcnt(8)
	s_waitcnt lgkmcnt(0)
	s_barrier
	s_waitcnt lgkmcnt(0)
	v_mfma_i32_16x16x64_i8 v[124:127], v[144:147], v[192:195], v[124:127]
	v_mfma_i32_16x16x64_i8 v[120:123], v[168:171], v[192:195], v[120:123]
	v_mfma_i32_16x16x64_i8 v[108:111], v[144:147], v[200:203], v[108:111]
	v_mfma_i32_16x16x64_i8 v[104:107], v[168:171], v[200:203], v[104:107]
	s_add_i32 s28, s55, s35
	v_mfma_i32_16x16x64_i8 v[92:95], v[144:147], v[208:211], v[92:95]
	v_mfma_i32_16x16x64_i8 v[88:91], v[168:171], v[208:211], v[88:91]
	v_mfma_i32_16x16x64_i8 v[76:79], v[144:147], v[216:219], v[76:79]
	v_mfma_i32_16x16x64_i8 v[72:75], v[168:171], v[216:219], v[72:75]
	s_add_u32 s6, s6, 0x80080
	v_mfma_i32_16x16x64_i8 v[124:127], v[148:151], v[196:199], v[124:127]
	v_mfma_i32_16x16x64_i8 v[120:123], v[172:175], v[196:199], v[120:123]
	v_mfma_i32_16x16x64_i8 v[108:111], v[148:151], v[204:207], v[108:111]
	v_mfma_i32_16x16x64_i8 v[104:107], v[172:175], v[204:207], v[104:107]
	s_addc_u32 s7, s7, 0
	v_mfma_i32_16x16x64_i8 v[92:95], v[148:151], v[212:215], v[92:95]
	v_mfma_i32_16x16x64_i8 v[88:91], v[172:175], v[212:215], v[88:91]
	v_mfma_i32_16x16x64_i8 v[76:79], v[148:151], v[220:223], v[76:79]
	v_mfma_i32_16x16x64_i8 v[72:75], v[172:175], v[220:223], v[72:75]
	v_mfma_i32_16x16x64_i8 v[116:119], v[176:179], v[192:195], v[116:119]
	v_mfma_i32_16x16x64_i8 v[112:115], v[184:187], v[192:195], v[112:115]
	v_mfma_i32_16x16x64_i8 v[100:103], v[176:179], v[200:203], v[100:103]
	v_mfma_i32_16x16x64_i8 v[96:99], v[184:187], v[200:203], v[96:99]
	v_mfma_i32_16x16x64_i8 v[84:87], v[176:179], v[208:211], v[84:87]
	v_mfma_i32_16x16x64_i8 v[80:83], v[184:187], v[208:211], v[80:83]
	v_mfma_i32_16x16x64_i8 v[68:71], v[176:179], v[216:219], v[68:71]
	v_mfma_i32_16x16x64_i8 v[64:67], v[184:187], v[216:219], v[64:67]
	v_mfma_i32_16x16x64_i8 v[116:119], v[180:183], v[196:199], v[116:119]
	v_mfma_i32_16x16x64_i8 v[112:115], v[188:191], v[196:199], v[112:115]
	v_mfma_i32_16x16x64_i8 v[100:103], v[180:183], v[204:207], v[100:103]
	v_mfma_i32_16x16x64_i8 v[96:99], v[188:191], v[204:207], v[96:99]
	v_mfma_i32_16x16x64_i8 v[84:87], v[180:183], v[212:215], v[84:87]
	v_mfma_i32_16x16x64_i8 v[80:83], v[188:191], v[212:215], v[80:83]
	v_mfma_i32_16x16x64_i8 v[68:71], v[180:183], v[220:223], v[68:71]
	v_mfma_i32_16x16x64_i8 v[64:67], v[188:191], v[220:223], v[64:67]
	s_barrier
	ds_read_b128 v[192:195], v165 offset:49152
	ds_read_b128 v[196:199], v165 offset:50176
	ds_read_b128 v[200:203], v165 offset:51200
	ds_read_b128 v[204:207], v165 offset:52224
	ds_read_b128 v[208:211], v165 offset:53248
	ds_read_b128 v[212:215], v165 offset:54272
	ds_read_b128 v[216:219], v165 offset:55296
	ds_read_b128 v[220:223], v165 offset:56320
	s_mov_b32 m0, s28
	s_nop 0
	global_load_lds_dwordx4 v132, s[98:99]
	s_add_i32 m0, s28, 0x2000
	s_add_i32 s28, s56, s35
	global_load_lds_dwordx4 v128, s[98:99]
	s_mov_b32 m0, s28
	s_nop 0
	global_load_lds_dwordx4 v132, s[6:7]
	s_add_i32 m0, s28, 0x2000
	s_nop 0
	global_load_lds_dwordx4 v128, s[6:7]
	s_mov_b32 m0, s43
	s_nop 0
	global_load_lds_dwordx4 v134, s[100:101]
	s_mov_b32 m0, s44
	s_nop 0
	global_load_lds_dwordx4 v130, s[100:101]
	s_waitcnt vmcnt(8)
	s_waitcnt lgkmcnt(0)
	s_barrier
	s_waitcnt lgkmcnt(0)
	v_mfma_i32_16x16x64_i8 v[60:63], v[144:147], v[192:195], v[60:63]
	v_mfma_i32_16x16x64_i8 v[56:59], v[168:171], v[192:195], v[56:59]
	v_mfma_i32_16x16x64_i8 v[44:47], v[144:147], v[200:203], v[44:47]
	v_mfma_i32_16x16x64_i8 v[40:43], v[168:171], v[200:203], v[40:43]
	v_mfma_i32_16x16x64_i8 v[28:31], v[144:147], v[208:211], v[28:31]
	v_mfma_i32_16x16x64_i8 v[24:27], v[168:171], v[208:211], v[24:27]
	v_mfma_i32_16x16x64_i8 v[12:15], v[144:147], v[216:219], v[12:15]
	v_mfma_i32_16x16x64_i8 v[8:11], v[168:171], v[216:219], v[8:11]
	v_mfma_i32_16x16x64_i8 v[60:63], v[148:151], v[196:199], v[60:63]
	v_mfma_i32_16x16x64_i8 v[56:59], v[172:175], v[196:199], v[56:59]
	v_mfma_i32_16x16x64_i8 v[44:47], v[148:151], v[204:207], v[44:47]
	v_mfma_i32_16x16x64_i8 v[40:43], v[172:175], v[204:207], v[40:43]
	v_mfma_i32_16x16x64_i8 v[28:31], v[148:151], v[212:215], v[28:31]
	v_mfma_i32_16x16x64_i8 v[24:27], v[172:175], v[212:215], v[24:27]
	v_mfma_i32_16x16x64_i8 v[12:15], v[148:151], v[220:223], v[12:15]
	v_mfma_i32_16x16x64_i8 v[8:11], v[172:175], v[220:223], v[8:11]
	v_mfma_i32_16x16x64_i8 v[52:55], v[176:179], v[192:195], v[52:55]
	v_mfma_i32_16x16x64_i8 v[48:51], v[184:187], v[192:195], v[48:51]
	v_mfma_i32_16x16x64_i8 v[36:39], v[176:179], v[200:203], v[36:39]
	v_mfma_i32_16x16x64_i8 v[32:35], v[184:187], v[200:203], v[32:35]
	v_mfma_i32_16x16x64_i8 v[20:23], v[176:179], v[208:211], v[20:23]
	v_mfma_i32_16x16x64_i8 v[16:19], v[184:187], v[208:211], v[16:19]
	v_mfma_i32_16x16x64_i8 v[4:7], v[176:179], v[216:219], v[4:7]
	v_mfma_i32_16x16x64_i8 v[0:3], v[184:187], v[216:219], v[0:3]
	v_mfma_i32_16x16x64_i8 v[52:55], v[180:183], v[196:199], v[52:55]
	v_mfma_i32_16x16x64_i8 v[48:51], v[188:191], v[196:199], v[48:51]
	v_mfma_i32_16x16x64_i8 v[36:39], v[180:183], v[204:207], v[36:39]
	v_mfma_i32_16x16x64_i8 v[32:35], v[188:191], v[204:207], v[32:35]
	v_mfma_i32_16x16x64_i8 v[20:23], v[180:183], v[212:215], v[20:23]
	v_mfma_i32_16x16x64_i8 v[16:19], v[188:191], v[212:215], v[16:19]
	v_mfma_i32_16x16x64_i8 v[4:7], v[180:183], v[220:223], v[4:7]
	v_mfma_i32_16x16x64_i8 v[0:3], v[188:191], v[220:223], v[0:3]
	s_barrier
	s_add_i32 s54, s54, 2
	s_add_u32 s52, s52, 0x100
	s_addc_u32 s53, s53, 0
	s_add_u32 s4, s4, 0x100
	s_addc_u32 s5, s5, 0
	s_cmp_gt_u32 s54, 29
	s_cbranch_scc0 .LBB0_726
	s_setprio 0
	s_and_b64 vcc, exec, s[18:19]
	s_cbranch_vccz .LBB0_729
	s_barrier

.LBB0_1355:
	s_ashr_i32 s23, s22, 31
	s_lshl_b64 s[24:25], s[22:23], 20
	s_add_u32 s24, s38, s24
	s_addc_u32 s25, s39, s25
	s_and_b64 s[26:27], s[2:3], exec
	s_cselect_b32 s1, s25, s35
	s_cselect_b32 s23, s24, s34
	s_ashr_i32 s21, s20, 31
	s_lshl_b64 s[26:27], s[20:21], 20
	s_add_u32 s26, s40, s26
	s_addc_u32 s27, s41, s27
	s_and_b64 s[36:37], s[2:3], exec
	s_cselect_b32 s21, s27, s31
	s_cselect_b32 s29, s26, s30
	s_add_u32 s33, s30, 0x100
	s_addc_u32 s57, s31, 0
	s_add_u32 s30, s34, 0x80080
	v_mov_b32_e32 v0, 0
	s_addc_u32 s31, s35, 0
	s_mov_b32 s58, -2
	v_mov_b32_e32 v1, v0
	v_mov_b32_e32 v2, v0
	v_mov_b32_e32 v3, v0
	v_mov_b32_e32 v4, v0
	v_mov_b32_e32 v5, v0
	v_mov_b32_e32 v6, v0
	v_mov_b32_e32 v7, v0
	v_mov_b32_e32 v16, v0
	v_mov_b32_e32 v17, v0
	v_mov_b32_e32 v18, v0
	v_mov_b32_e32 v19, v0
	v_mov_b32_e32 v20, v0
	v_mov_b32_e32 v21, v0
	v_mov_b32_e32 v22, v0
	v_mov_b32_e32 v23, v0
	v_mov_b32_e32 v32, v0
	v_mov_b32_e32 v33, v0
	v_mov_b32_e32 v34, v0
	v_mov_b32_e32 v35, v0
	v_mov_b32_e32 v36, v0
	v_mov_b32_e32 v37, v0
	v_mov_b32_e32 v38, v0
	v_mov_b32_e32 v39, v0
	v_mov_b32_e32 v48, v0
	v_mov_b32_e32 v49, v0
	v_mov_b32_e32 v50, v0
	v_mov_b32_e32 v51, v0
	v_mov_b32_e32 v52, v0
	v_mov_b32_e32 v53, v0
	v_mov_b32_e32 v54, v0
	v_mov_b32_e32 v55, v0
	v_mov_b32_e32 v8, v0
	v_mov_b32_e32 v9, v0
	v_mov_b32_e32 v10, v0
	v_mov_b32_e32 v11, v0
	v_mov_b32_e32 v12, v0
	v_mov_b32_e32 v13, v0
	v_mov_b32_e32 v14, v0
	v_mov_b32_e32 v15, v0
	v_mov_b32_e32 v24, v0
	v_mov_b32_e32 v25, v0
	v_mov_b32_e32 v26, v0
	v_mov_b32_e32 v27, v0
	v_mov_b32_e32 v28, v0
	v_mov_b32_e32 v29, v0
	v_mov_b32_e32 v30, v0
	v_mov_b32_e32 v31, v0
	v_mov_b32_e32 v40, v0
	v_mov_b32_e32 v41, v0
	v_mov_b32_e32 v42, v0
	v_mov_b32_e32 v43, v0
	v_mov_b32_e32 v44, v0
	v_mov_b32_e32 v45, v0
	v_mov_b32_e32 v46, v0
	v_mov_b32_e32 v47, v0
	v_mov_b32_e32 v56, v0
	v_mov_b32_e32 v57, v0
	v_mov_b32_e32 v58, v0
	v_mov_b32_e32 v59, v0
	v_mov_b32_e32 v60, v0
	v_mov_b32_e32 v61, v0
	v_mov_b32_e32 v62, v0
	v_mov_b32_e32 v63, v0
	v_mov_b32_e32 v64, v0
	v_mov_b32_e32 v65, v0
	v_mov_b32_e32 v66, v0
	v_mov_b32_e32 v67, v0
	v_mov_b32_e32 v68, v0
	v_mov_b32_e32 v69, v0
	v_mov_b32_e32 v70, v0
	v_mov_b32_e32 v71, v0
	v_mov_b32_e32 v80, v0
	v_mov_b32_e32 v81, v0
	v_mov_b32_e32 v82, v0
	v_mov_b32_e32 v83, v0
	v_mov_b32_e32 v84, v0
	v_mov_b32_e32 v85, v0
	v_mov_b32_e32 v86, v0
	v_mov_b32_e32 v87, v0
	v_mov_b32_e32 v96, v0
	v_mov_b32_e32 v97, v0
	v_mov_b32_e32 v98, v0
	v_mov_b32_e32 v99, v0
	v_mov_b32_e32 v100, v0
	v_mov_b32_e32 v101, v0
	v_mov_b32_e32 v102, v0
	v_mov_b32_e32 v103, v0
	v_mov_b32_e32 v112, v0
	v_mov_b32_e32 v113, v0
	v_mov_b32_e32 v114, v0
	v_mov_b32_e32 v115, v0
	v_mov_b32_e32 v116, v0
	v_mov_b32_e32 v117, v0
	v_mov_b32_e32 v118, v0
	v_mov_b32_e32 v119, v0
	v_mov_b32_e32 v72, v0
	v_mov_b32_e32 v73, v0
	v_mov_b32_e32 v74, v0
	v_mov_b32_e32 v75, v0
	v_mov_b32_e32 v76, v0
	v_mov_b32_e32 v77, v0
	v_mov_b32_e32 v78, v0
	v_mov_b32_e32 v79, v0
	v_mov_b32_e32 v88, v0
	v_mov_b32_e32 v89, v0
	v_mov_b32_e32 v90, v0
	v_mov_b32_e32 v91, v0
	v_mov_b32_e32 v92, v0
	v_mov_b32_e32 v93, v0
	v_mov_b32_e32 v94, v0
	v_mov_b32_e32 v95, v0
	v_mov_b32_e32 v104, v0
	v_mov_b32_e32 v105, v0
	v_mov_b32_e32 v106, v0
	v_mov_b32_e32 v107, v0
	v_mov_b32_e32 v108, v0
	v_mov_b32_e32 v109, v0
	v_mov_b32_e32 v110, v0
	v_mov_b32_e32 v111, v0
	v_mov_b32_e32 v120, v0
	v_mov_b32_e32 v121, v0
	v_mov_b32_e32 v122, v0
	v_mov_b32_e32 v123, v0
	v_mov_b32_e32 v124, v0
	v_mov_b32_e32 v125, v0
	v_mov_b32_e32 v126, v0
	v_mov_b32_e32 v127, v0
	v_add_u32_e32 v248, 0x18000, v178
	v_add_u32_e32 v249, 0x1c000, v178
	s_cmp_lt_u32 s81, 4
	s_cbranch_scc0 .Lsp_skip8
	s_setprio 1
.Lsp_skip8:
.LBB0_1356:
	ds_read_b128 v[144:147], v180
	ds_read_b128 v[148:151], v180 offset:1024
	ds_read_b128 v[152:155], v180 offset:2048
	ds_read_b128 v[156:159], v180 offset:3072
	ds_read_b128 v[160:163], v181
	ds_read_b128 v[164:167], v181 offset:1024
	ds_read_b128 v[168:171], v181 offset:2048
	ds_read_b128 v[172:175], v181 offset:3072
	ds_read_b128 v[186:189], v182
	ds_read_b128 v[190:193], v182 offset:1024
	ds_read_b128 v[194:197], v182 offset:2048
	ds_read_b128 v[198:201], v182 offset:3072
	ds_read_b128 v[202:205], v182 offset:4096
	ds_read_b128 v[206:209], v182 offset:5120
	ds_read_b128 v[210:213], v182 offset:6144
	ds_read_b128 v[214:217], v182 offset:7168
	s_add_u32 s34, s30, 0xfff80080
	s_addc_u32 s35, s31, -1
	s_cmp_eq_u32 s58, 28
	s_cselect_b32 s37, s1, s35
	s_cselect_b32 s36, s23, s34
	s_cselect_b32 s35, s21, s57
	s_cselect_b32 s34, s29, s33
	s_add_i32 m0, s43, 0xc000
	s_nop 0
	global_load_lds_dwordx4 v138, s[30:31]
	s_add_i32 m0, s43, 0xe000
	s_nop 0
	global_load_lds_dwordx4 v136, s[30:31]
	s_waitcnt vmcnt(8)
	s_waitcnt lgkmcnt(0)
	s_barrier
	s_waitcnt lgkmcnt(0)
	v_mfma_i32_16x16x64_i8 v[124:127], v[144:147], v[186:189], v[124:127]
	v_mfma_i32_16x16x64_i8 v[120:123], v[152:155], v[186:189], v[120:123]
	v_mfma_i32_16x16x64_i8 v[108:111], v[144:147], v[194:197], v[108:111]
	v_mfma_i32_16x16x64_i8 v[104:107], v[152:155], v[194:197], v[104:107]
	s_add_u32 s98, s34, s16
	s_addc_u32 s99, s35, s17
	s_add_i32 s59, s52, s42
	v_mfma_i32_16x16x64_i8 v[92:95], v[144:147], v[202:205], v[92:95]
	s_add_u32 s100, s36, s16
	s_addc_u32 s101, s37, s17
	v_mfma_i32_16x16x64_i8 v[88:91], v[152:155], v[202:205], v[88:91]
	v_mfma_i32_16x16x64_i8 v[76:79], v[144:147], v[210:213], v[76:79]
	v_mfma_i32_16x16x64_i8 v[72:75], v[152:155], v[210:213], v[72:75]
	s_add_u32 s60, s34, 0x80000
	v_mfma_i32_16x16x64_i8 v[124:127], v[148:151], v[190:193], v[124:127]
	v_mfma_i32_16x16x64_i8 v[120:123], v[156:159], v[190:193], v[120:123]
	v_mfma_i32_16x16x64_i8 v[108:111], v[148:151], v[198:201], v[108:111]
	v_mfma_i32_16x16x64_i8 v[104:107], v[156:159], v[198:201], v[104:107]
	s_addc_u32 s61, s35, 0
	v_mfma_i32_16x16x64_i8 v[92:95], v[148:151], v[206:209], v[92:95]
	v_mfma_i32_16x16x64_i8 v[88:91], v[156:159], v[206:209], v[88:91]
	v_mfma_i32_16x16x64_i8 v[76:79], v[148:151], v[214:217], v[76:79]
	v_mfma_i32_16x16x64_i8 v[72:75], v[156:159], v[214:217], v[72:75]
	v_mfma_i32_16x16x64_i8 v[116:119], v[160:163], v[186:189], v[116:119]
	v_mfma_i32_16x16x64_i8 v[112:115], v[168:171], v[186:189], v[112:115]
	v_mfma_i32_16x16x64_i8 v[100:103], v[160:163], v[194:197], v[100:103]
	v_mfma_i32_16x16x64_i8 v[96:99], v[168:171], v[194:197], v[96:99]
	v_mfma_i32_16x16x64_i8 v[84:87], v[160:163], v[202:205], v[84:87]
	v_mfma_i32_16x16x64_i8 v[80:83], v[168:171], v[202:205], v[80:83]
	v_mfma_i32_16x16x64_i8 v[68:71], v[160:163], v[210:213], v[68:71]
	v_mfma_i32_16x16x64_i8 v[64:67], v[168:171], v[210:213], v[64:67]
	v_mfma_i32_16x16x64_i8 v[116:119], v[164:167], v[190:193], v[116:119]
	v_mfma_i32_16x16x64_i8 v[112:115], v[172:175], v[190:193], v[112:115]
	v_mfma_i32_16x16x64_i8 v[100:103], v[164:167], v[198:201], v[100:103]
	v_mfma_i32_16x16x64_i8 v[96:99], v[172:175], v[198:201], v[96:99]
	v_mfma_i32_16x16x64_i8 v[84:87], v[164:167], v[206:209], v[84:87]
	v_mfma_i32_16x16x64_i8 v[80:83], v[172:175], v[206:209], v[80:83]
	v_mfma_i32_16x16x64_i8 v[68:71], v[164:167], v[214:217], v[68:71]
	v_mfma_i32_16x16x64_i8 v[64:67], v[172:175], v[214:217], v[64:67]
	s_barrier
	ds_read_b128 v[186:189], v182 offset:16384
	ds_read_b128 v[190:193], v182 offset:17408
	ds_read_b128 v[194:197], v182 offset:18432
	ds_read_b128 v[198:201], v182 offset:19456
	ds_read_b128 v[202:205], v182 offset:20480
	ds_read_b128 v[206:209], v182 offset:21504
	ds_read_b128 v[210:213], v182 offset:22528
	ds_read_b128 v[214:217], v182 offset:23552
	s_mov_b32 m0, s59
	s_nop 0
	global_load_lds_dwordx4 v130, s[34:35]
	s_add_i32 m0, s59, 0x2000
	s_add_i32 s59, s53, s42
	global_load_lds_dwordx4 v134, s[34:35]
	s_mov_b32 m0, s59
	s_nop 0
	global_load_lds_dwordx4 v130, s[60:61]
	s_add_i32 m0, s59, 0x2000
	s_nop 0
	global_load_lds_dwordx4 v134, s[60:61]
	s_mov_b32 m0, s43
	s_nop 0
	global_load_lds_dwordx4 v128, s[36:37]
	s_mov_b32 m0, s44
	s_nop 0
	global_load_lds_dwordx4 v132, s[36:37]
	s_waitcnt vmcnt(8)
	s_waitcnt lgkmcnt(0)
	s_barrier
	s_waitcnt lgkmcnt(0)
	v_mfma_i32_16x16x64_i8 v[60:63], v[144:147], v[186:189], v[60:63]
	v_mfma_i32_16x16x64_i8 v[56:59], v[152:155], v[186:189], v[56:59]
	v_mfma_i32_16x16x64_i8 v[44:47], v[144:147], v[194:197], v[44:47]
	v_mfma_i32_16x16x64_i8 v[40:43], v[152:155], v[194:197], v[40:43]
	s_add_i32 s59, 0, 0x18000
	v_mfma_i32_16x16x64_i8 v[28:31], v[144:147], v[202:205], v[28:31]
	v_mfma_i32_16x16x64_i8 v[24:27], v[152:155], v[202:205], v[24:27]
	s_add_i32 s60, 0, 0x1c000
	v_mfma_i32_16x16x64_i8 v[12:15], v[144:147], v[210:213], v[12:15]
	v_mfma_i32_16x16x64_i8 v[8:11], v[152:155], v[210:213], v[8:11]
	s_add_u32 s36, s36, 0x80000
	v_mfma_i32_16x16x64_i8 v[60:63], v[148:151], v[190:193], v[60:63]
	v_mfma_i32_16x16x64_i8 v[56:59], v[156:159], v[190:193], v[56:59]
	s_addc_u32 s37, s37, 0
	v_mfma_i32_16x16x64_i8 v[44:47], v[148:151], v[198:201], v[44:47]
	v_mfma_i32_16x16x64_i8 v[40:43], v[156:159], v[198:201], v[40:43]
	v_mfma_i32_16x16x64_i8 v[28:31], v[148:151], v[206:209], v[28:31]
	v_mfma_i32_16x16x64_i8 v[24:27], v[156:159], v[206:209], v[24:27]
	v_mfma_i32_16x16x64_i8 v[12:15], v[148:151], v[214:217], v[12:15]
	v_mfma_i32_16x16x64_i8 v[8:11], v[156:159], v[214:217], v[8:11]
	v_mfma_i32_16x16x64_i8 v[52:55], v[160:163], v[186:189], v[52:55]
	v_mfma_i32_16x16x64_i8 v[48:51], v[168:171], v[186:189], v[48:51]
	v_mfma_i32_16x16x64_i8 v[36:39], v[160:163], v[194:197], v[36:39]
	v_mfma_i32_16x16x64_i8 v[32:35], v[168:171], v[194:197], v[32:35]
	v_mfma_i32_16x16x64_i8 v[20:23], v[160:163], v[202:205], v[20:23]
	v_mfma_i32_16x16x64_i8 v[16:19], v[168:171], v[202:205], v[16:19]
	v_mfma_i32_16x16x64_i8 v[4:7], v[160:163], v[210:213], v[4:7]
	v_mfma_i32_16x16x64_i8 v[0:3], v[168:171], v[210:213], v[0:3]
	v_mfma_i32_16x16x64_i8 v[52:55], v[164:167], v[190:193], v[52:55]
	v_mfma_i32_16x16x64_i8 v[48:51], v[172:175], v[190:193], v[48:51]
	v_mfma_i32_16x16x64_i8 v[36:39], v[164:167], v[198:201], v[36:39]
	v_mfma_i32_16x16x64_i8 v[32:35], v[172:175], v[198:201], v[32:35]
	v_mfma_i32_16x16x64_i8 v[20:23], v[164:167], v[206:209], v[20:23]
	v_mfma_i32_16x16x64_i8 v[16:19], v[172:175], v[206:209], v[16:19]
	v_mfma_i32_16x16x64_i8 v[4:7], v[164:167], v[214:217], v[4:7]
	v_mfma_i32_16x16x64_i8 v[0:3], v[172:175], v[214:217], v[0:3]
	s_barrier
	ds_read_b128 v[186:189], v182 offset:32768
	ds_read_b128 v[190:193], v182 offset:33792
	ds_read_b128 v[194:197], v182 offset:34816
	ds_read_b128 v[198:201], v182 offset:35840
	ds_read_b128 v[202:205], v182 offset:36864
	ds_read_b128 v[206:209], v182 offset:37888
	ds_read_b128 v[210:213], v182 offset:38912
	ds_read_b128 v[214:217], v182 offset:39936
	ds_read_b128 v[144:147], v248
	ds_read_b128 v[148:151], v248 offset:1024
	ds_read_b128 v[152:155], v248 offset:2048
	ds_read_b128 v[156:159], v248 offset:3072
	ds_read_b128 v[160:163], v249
	ds_read_b128 v[164:167], v249 offset:1024
	ds_read_b128 v[168:171], v249 offset:2048
	ds_read_b128 v[172:175], v249 offset:3072
	s_mov_b32 m0, s45
	s_nop 0
	global_load_lds_dwordx4 v128, s[36:37]
	s_mov_b32 m0, s46
	s_nop 0
	global_load_lds_dwordx4 v132, s[36:37]
	s_waitcnt vmcnt(8)
	s_waitcnt lgkmcnt(0)
	s_barrier
	s_waitcnt lgkmcnt(0)
	v_mfma_i32_16x16x64_i8 v[124:127], v[144:147], v[186:189], v[124:127]
	v_mfma_i32_16x16x64_i8 v[120:123], v[152:155], v[186:189], v[120:123]
	v_mfma_i32_16x16x64_i8 v[108:111], v[144:147], v[194:197], v[108:111]
	v_mfma_i32_16x16x64_i8 v[104:107], v[152:155], v[194:197], v[104:107]
	s_add_i32 s36, s59, s42
	v_mfma_i32_16x16x64_i8 v[92:95], v[144:147], v[202:205], v[92:95]
	v_mfma_i32_16x16x64_i8 v[88:91], v[152:155], v[202:205], v[88:91]
	v_mfma_i32_16x16x64_i8 v[76:79], v[144:147], v[210:213], v[76:79]
	v_mfma_i32_16x16x64_i8 v[72:75], v[152:155], v[210:213], v[72:75]
	s_add_u32 s34, s34, 0x80080
	v_mfma_i32_16x16x64_i8 v[124:127], v[148:151], v[190:193], v[124:127]
	v_mfma_i32_16x16x64_i8 v[120:123], v[156:159], v[190:193], v[120:123]
	v_mfma_i32_16x16x64_i8 v[108:111], v[148:151], v[198:201], v[108:111]
	v_mfma_i32_16x16x64_i8 v[104:107], v[156:159], v[198:201], v[104:107]
	s_addc_u32 s35, s35, 0
	v_mfma_i32_16x16x64_i8 v[92:95], v[148:151], v[206:209], v[92:95]
	v_mfma_i32_16x16x64_i8 v[88:91], v[156:159], v[206:209], v[88:91]
	v_mfma_i32_16x16x64_i8 v[76:79], v[148:151], v[214:217], v[76:79]
	v_mfma_i32_16x16x64_i8 v[72:75], v[156:159], v[214:217], v[72:75]
	v_mfma_i32_16x16x64_i8 v[116:119], v[160:163], v[186:189], v[116:119]
	v_mfma_i32_16x16x64_i8 v[112:115], v[168:171], v[186:189], v[112:115]
	v_mfma_i32_16x16x64_i8 v[100:103], v[160:163], v[194:197], v[100:103]
	v_mfma_i32_16x16x64_i8 v[96:99], v[168:171], v[194:197], v[96:99]
	v_mfma_i32_16x16x64_i8 v[84:87], v[160:163], v[202:205], v[84:87]
	v_mfma_i32_16x16x64_i8 v[80:83], v[168:171], v[202:205], v[80:83]
	v_mfma_i32_16x16x64_i8 v[68:71], v[160:163], v[210:213], v[68:71]
	v_mfma_i32_16x16x64_i8 v[64:67], v[168:171], v[210:213], v[64:67]
	v_mfma_i32_16x16x64_i8 v[116:119], v[164:167], v[190:193], v[116:119]
	v_mfma_i32_16x16x64_i8 v[112:115], v[172:175], v[190:193], v[112:115]
	v_mfma_i32_16x16x64_i8 v[100:103], v[164:167], v[198:201], v[100:103]
	v_mfma_i32_16x16x64_i8 v[96:99], v[172:175], v[198:201], v[96:99]
	v_mfma_i32_16x16x64_i8 v[84:87], v[164:167], v[206:209], v[84:87]
	v_mfma_i32_16x16x64_i8 v[80:83], v[172:175], v[206:209], v[80:83]
	v_mfma_i32_16x16x64_i8 v[68:71], v[164:167], v[214:217], v[68:71]
	v_mfma_i32_16x16x64_i8 v[64:67], v[172:175], v[214:217], v[64:67]
	s_barrier
	ds_read_b128 v[186:189], v182 offset:49152
	ds_read_b128 v[190:193], v182 offset:50176
	ds_read_b128 v[194:197], v182 offset:51200
	ds_read_b128 v[198:201], v182 offset:52224
	ds_read_b128 v[202:205], v182 offset:53248
	ds_read_b128 v[206:209], v182 offset:54272
	ds_read_b128 v[210:213], v182 offset:55296
	ds_read_b128 v[214:217], v182 offset:56320
	s_mov_b32 m0, s36
	s_nop 0
	global_load_lds_dwordx4 v130, s[98:99]
	s_add_i32 m0, s36, 0x2000
	s_add_i32 s36, s60, s42
	global_load_lds_dwordx4 v134, s[98:99]
	s_mov_b32 m0, s36
	s_nop 0
	global_load_lds_dwordx4 v130, s[34:35]
	s_add_i32 m0, s36, 0x2000
	s_nop 0
	global_load_lds_dwordx4 v134, s[34:35]
	s_mov_b32 m0, s48
	s_nop 0
	global_load_lds_dwordx4 v128, s[100:101]
	s_mov_b32 m0, s49
	s_nop 0
	global_load_lds_dwordx4 v132, s[100:101]
	s_waitcnt vmcnt(8)
	s_waitcnt lgkmcnt(0)
	s_barrier
	s_waitcnt lgkmcnt(0)
	v_mfma_i32_16x16x64_i8 v[60:63], v[144:147], v[186:189], v[60:63]
	v_mfma_i32_16x16x64_i8 v[56:59], v[152:155], v[186:189], v[56:59]
	v_mfma_i32_16x16x64_i8 v[44:47], v[144:147], v[194:197], v[44:47]
	v_mfma_i32_16x16x64_i8 v[40:43], v[152:155], v[194:197], v[40:43]
	v_mfma_i32_16x16x64_i8 v[28:31], v[144:147], v[202:205], v[28:31]
	v_mfma_i32_16x16x64_i8 v[24:27], v[152:155], v[202:205], v[24:27]
	v_mfma_i32_16x16x64_i8 v[12:15], v[144:147], v[210:213], v[12:15]
	v_mfma_i32_16x16x64_i8 v[8:11], v[152:155], v[210:213], v[8:11]
	v_mfma_i32_16x16x64_i8 v[60:63], v[148:151], v[190:193], v[60:63]
	v_mfma_i32_16x16x64_i8 v[56:59], v[156:159], v[190:193], v[56:59]
	v_mfma_i32_16x16x64_i8 v[44:47], v[148:151], v[198:201], v[44:47]
	v_mfma_i32_16x16x64_i8 v[40:43], v[156:159], v[198:201], v[40:43]
	v_mfma_i32_16x16x64_i8 v[28:31], v[148:151], v[206:209], v[28:31]
	v_mfma_i32_16x16x64_i8 v[24:27], v[156:159], v[206:209], v[24:27]
	v_mfma_i32_16x16x64_i8 v[12:15], v[148:151], v[214:217], v[12:15]
	v_mfma_i32_16x16x64_i8 v[8:11], v[156:159], v[214:217], v[8:11]
	v_mfma_i32_16x16x64_i8 v[52:55], v[160:163], v[186:189], v[52:55]
	v_mfma_i32_16x16x64_i8 v[48:51], v[168:171], v[186:189], v[48:51]
	v_mfma_i32_16x16x64_i8 v[36:39], v[160:163], v[194:197], v[36:39]
	v_mfma_i32_16x16x64_i8 v[32:35], v[168:171], v[194:197], v[32:35]
	v_mfma_i32_16x16x64_i8 v[20:23], v[160:163], v[202:205], v[20:23]
	v_mfma_i32_16x16x64_i8 v[16:19], v[168:171], v[202:205], v[16:19]
	v_mfma_i32_16x16x64_i8 v[4:7], v[160:163], v[210:213], v[4:7]
	v_mfma_i32_16x16x64_i8 v[0:3], v[168:171], v[210:213], v[0:3]
	v_mfma_i32_16x16x64_i8 v[52:55], v[164:167], v[190:193], v[52:55]
	v_mfma_i32_16x16x64_i8 v[48:51], v[172:175], v[190:193], v[48:51]
	v_mfma_i32_16x16x64_i8 v[36:39], v[164:167], v[198:201], v[36:39]
	v_mfma_i32_16x16x64_i8 v[32:35], v[172:175], v[198:201], v[32:35]
	v_mfma_i32_16x16x64_i8 v[20:23], v[164:167], v[206:209], v[20:23]
	v_mfma_i32_16x16x64_i8 v[16:19], v[172:175], v[206:209], v[16:19]
	v_mfma_i32_16x16x64_i8 v[4:7], v[164:167], v[214:217], v[4:7]
	v_mfma_i32_16x16x64_i8 v[0:3], v[172:175], v[214:217], v[0:3]
	s_barrier
	s_add_i32 s58, s58, 2
	s_add_u32 s33, s33, 0x100
	s_addc_u32 s57, s57, 0
	s_add_u32 s30, s30, 0x100
	s_addc_u32 s31, s31, 0
	s_cmp_gt_u32 s58, 29
	s_cbranch_scc0 .LBB0_1356
	s_setprio 0
	s_and_b64 vcc, exec, s[18:19]
	s_cbranch_vccz .LBB0_1359
	s_barrier

.LBB0_1840:
	s_ashr_i32 s19, s18, 31
	s_lshl_b64 s[20:21], s[18:19], 22
	s_add_u32 s20, s15, s20
	s_addc_u32 s21, s33, s21
	s_and_b64 s[22:23], s[4:5], exec
	s_cselect_b32 s19, s21, s31
	s_cselect_b32 s25, s20, s30
	s_ashr_i32 s17, s16, 31
	s_lshl_b64 s[22:23], s[16:17], 22
	s_add_u32 s22, s36, s22
	s_addc_u32 s23, s37, s23
	s_and_b64 s[34:35], s[4:5], exec
	s_cselect_b32 s17, s23, s29
	s_cselect_b32 s50, s22, s28
	s_add_u32 s51, s28, 0x100
	s_addc_u32 s52, s29, 0
	s_add_u32 s28, s30, 0x200080
	s_waitcnt vmcnt(0) lgkmcnt(0)
	v_mov_b64_e32 v[18:19], v[2:3]
	v_mov_b64_e32 v[22:23], v[6:7]
	v_mov_b64_e32 v[34:35], v[2:3]
	v_mov_b64_e32 v[38:39], v[6:7]
	v_mov_b64_e32 v[50:51], v[2:3]
	v_mov_b64_e32 v[54:55], v[6:7]
	v_mov_b64_e32 v[26:27], v[10:11]
	v_mov_b64_e32 v[30:31], v[14:15]
	v_mov_b64_e32 v[42:43], v[10:11]
	v_mov_b64_e32 v[46:47], v[14:15]
	v_mov_b64_e32 v[58:59], v[10:11]
	v_mov_b64_e32 v[62:63], v[14:15]
	v_mov_b64_e32 v[66:67], v[2:3]
	v_mov_b64_e32 v[70:71], v[6:7]
	v_mov_b64_e32 v[82:83], v[2:3]
	v_mov_b64_e32 v[86:87], v[6:7]
	v_mov_b64_e32 v[98:99], v[2:3]
	v_mov_b64_e32 v[102:103], v[6:7]
	v_mov_b64_e32 v[122:123], v[2:3]
	v_mov_b64_e32 v[130:131], v[6:7]
	v_mov_b64_e32 v[74:75], v[10:11]
	v_mov_b64_e32 v[78:79], v[14:15]
	v_mov_b64_e32 v[90:91], v[10:11]
	v_mov_b64_e32 v[94:95], v[14:15]
	v_mov_b64_e32 v[110:111], v[10:11]
	v_mov_b64_e32 v[114:115], v[14:15]
	v_mov_b64_e32 v[106:107], v[10:11]
	v_mov_b64_e32 v[118:119], v[14:15]
	s_addc_u32 s29, s31, 0
	s_mov_b32 s53, -2
	v_mov_b64_e32 v[16:17], v[0:1]
	v_mov_b64_e32 v[20:21], v[4:5]
	v_mov_b64_e32 v[32:33], v[0:1]
	v_mov_b64_e32 v[36:37], v[4:5]
	v_mov_b64_e32 v[48:49], v[0:1]
	v_mov_b64_e32 v[52:53], v[4:5]
	v_mov_b64_e32 v[24:25], v[8:9]
	v_mov_b64_e32 v[28:29], v[12:13]
	v_mov_b64_e32 v[40:41], v[8:9]
	v_mov_b64_e32 v[44:45], v[12:13]
	v_mov_b64_e32 v[56:57], v[8:9]
	v_mov_b64_e32 v[60:61], v[12:13]
	v_mov_b64_e32 v[64:65], v[0:1]
	v_mov_b64_e32 v[68:69], v[4:5]
	v_mov_b64_e32 v[80:81], v[0:1]
	v_mov_b64_e32 v[84:85], v[4:5]
	v_mov_b64_e32 v[96:97], v[0:1]
	v_mov_b64_e32 v[100:101], v[4:5]
	v_mov_b64_e32 v[120:121], v[0:1]
	v_mov_b64_e32 v[128:129], v[4:5]
	v_mov_b64_e32 v[72:73], v[8:9]
	v_mov_b64_e32 v[76:77], v[12:13]
	v_mov_b64_e32 v[88:89], v[8:9]
	v_mov_b64_e32 v[92:93], v[12:13]
	v_mov_b64_e32 v[108:109], v[8:9]
	v_mov_b64_e32 v[112:113], v[12:13]
	v_mov_b64_e32 v[104:105], v[8:9]
	v_mov_b64_e32 v[116:117], v[12:13]
	v_add_u32_e32 v248, s47, v181
	v_add_u32_e32 v249, s48, v181
	v_add_u32_e32 v250, 0x18000, v181
	v_add_u32_e32 v251, 0x1c000, v181
	s_cmp_lt_u32 s81, 4
	s_cbranch_scc0 .Lsp_skip9
	s_setprio 1
.Lsp_skip9:
.LBB0_1841:
	ds_read_b128 v[186:189], v183
	ds_read_b128 v[190:193], v183 offset:1024
	ds_read_b128 v[194:197], v183 offset:2048
	ds_read_b128 v[198:201], v183 offset:3072
	ds_read_b128 v[202:205], v183 offset:4096
	ds_read_b128 v[206:209], v183 offset:5120
	ds_read_b128 v[210:213], v183 offset:6144
	ds_read_b128 v[214:217], v183 offset:7168
	ds_read_b128 v[124:127], v248
	ds_read_b128 v[132:135], v248 offset:1024
	ds_read_b128 v[136:139], v248 offset:2048
	ds_read_b128 v[140:143], v248 offset:3072
	ds_read_b128 v[162:165], v249
	ds_read_b128 v[166:169], v249 offset:1024
	ds_read_b128 v[170:173], v249 offset:2048
	ds_read_b128 v[174:177], v249 offset:3072
	s_add_u32 s30, s28, 0xffe00080
	s_addc_u32 s31, s29, -1
	s_cmpk_eq_i32 s53, 0x7c
	s_cselect_b32 s35, s19, s31
	s_cselect_b32 s34, s25, s30
	s_cselect_b32 s31, s17, s52
	s_cselect_b32 s30, s50, s51
	s_add_i32 m0, s27, 0xc000
	s_nop 0
	global_load_lds_dwordx4 v156, s[28:29]
	s_add_i32 m0, s27, 0xe000
	s_nop 0
	global_load_lds_dwordx4 v154, s[28:29]
	s_waitcnt vmcnt(8)
	s_waitcnt lgkmcnt(0)
	s_barrier
	s_waitcnt lgkmcnt(0)
	v_mfma_i32_16x16x64_i8 v[116:119], v[124:127], v[186:189], v[116:119]
	v_mfma_i32_16x16x64_i8 v[104:107], v[136:139], v[186:189], v[104:107]
	v_mfma_i32_16x16x64_i8 v[112:115], v[124:127], v[194:197], v[112:115]
	v_mfma_i32_16x16x64_i8 v[108:111], v[136:139], v[194:197], v[108:111]
	s_add_u32 s98, s30, s10
	s_addc_u32 s99, s31, s11
	s_add_i32 s54, s47, s38
	v_mfma_i32_16x16x64_i8 v[92:95], v[124:127], v[202:205], v[92:95]
	s_add_u32 s100, s34, s10
	s_addc_u32 s101, s35, s11
	v_mfma_i32_16x16x64_i8 v[88:91], v[136:139], v[202:205], v[88:91]
	v_mfma_i32_16x16x64_i8 v[76:79], v[124:127], v[210:213], v[76:79]
	v_mfma_i32_16x16x64_i8 v[72:75], v[136:139], v[210:213], v[72:75]
	v_mfma_i32_16x16x64_i8 v[116:119], v[132:135], v[190:193], v[116:119]
	v_mfma_i32_16x16x64_i8 v[104:107], v[140:143], v[190:193], v[104:107]
	s_add_i32 s56, s48, s38
	v_mfma_i32_16x16x64_i8 v[112:115], v[132:135], v[198:201], v[112:115]
	v_mfma_i32_16x16x64_i8 v[108:111], v[140:143], v[198:201], v[108:111]
	v_mfma_i32_16x16x64_i8 v[92:95], v[132:135], v[206:209], v[92:95]
	v_mfma_i32_16x16x64_i8 v[88:91], v[140:143], v[206:209], v[88:91]
	v_mfma_i32_16x16x64_i8 v[76:79], v[132:135], v[214:217], v[76:79]
	v_mfma_i32_16x16x64_i8 v[72:75], v[140:143], v[214:217], v[72:75]
	v_mfma_i32_16x16x64_i8 v[128:131], v[162:165], v[186:189], v[128:131]
	v_mfma_i32_16x16x64_i8 v[120:123], v[170:173], v[186:189], v[120:123]
	v_mfma_i32_16x16x64_i8 v[100:103], v[162:165], v[194:197], v[100:103]
	v_mfma_i32_16x16x64_i8 v[96:99], v[170:173], v[194:197], v[96:99]
	v_mfma_i32_16x16x64_i8 v[84:87], v[162:165], v[202:205], v[84:87]
	v_mfma_i32_16x16x64_i8 v[80:83], v[170:173], v[202:205], v[80:83]
	v_mfma_i32_16x16x64_i8 v[68:71], v[162:165], v[210:213], v[68:71]
	v_mfma_i32_16x16x64_i8 v[64:67], v[170:173], v[210:213], v[64:67]
	v_mfma_i32_16x16x64_i8 v[128:131], v[166:169], v[190:193], v[128:131]
	v_mfma_i32_16x16x64_i8 v[120:123], v[174:177], v[190:193], v[120:123]
	v_mfma_i32_16x16x64_i8 v[100:103], v[166:169], v[198:201], v[100:103]
	v_mfma_i32_16x16x64_i8 v[96:99], v[174:177], v[198:201], v[96:99]
	v_mfma_i32_16x16x64_i8 v[84:87], v[166:169], v[206:209], v[84:87]
	v_mfma_i32_16x16x64_i8 v[80:83], v[174:177], v[206:209], v[80:83]
	v_mfma_i32_16x16x64_i8 v[68:71], v[166:169], v[214:217], v[68:71]
	v_mfma_i32_16x16x64_i8 v[64:67], v[174:177], v[214:217], v[64:67]
	s_barrier
	ds_read_b128 v[186:189], v183 offset:16384
	ds_read_b128 v[190:193], v183 offset:17408
	ds_read_b128 v[194:197], v183 offset:18432
	ds_read_b128 v[198:201], v183 offset:19456
	ds_read_b128 v[202:205], v183 offset:20480
	ds_read_b128 v[206:209], v183 offset:21504
	ds_read_b128 v[210:213], v183 offset:22528
	ds_read_b128 v[214:217], v183 offset:23552
	s_mov_b32 m0, s54
	s_nop 0
	global_load_lds_dwordx4 v146, s[30:31]
	s_add_i32 m0, s54, 0x2000
	s_add_u32 s54, s30, 0x200000
	s_addc_u32 s55, s31, 0
	global_load_lds_dwordx4 v150, s[30:31]
	s_mov_b32 m0, s56
	s_nop 0
	global_load_lds_dwordx4 v146, s[54:55]
	s_add_i32 m0, s56, 0x2000
	s_nop 0
	global_load_lds_dwordx4 v150, s[54:55]
	s_mov_b32 m0, s27
	s_nop 0
	global_load_lds_dwordx4 v144, s[34:35]
	s_mov_b32 m0, s39
	s_nop 0
	global_load_lds_dwordx4 v148, s[34:35]
	s_waitcnt vmcnt(8)
	s_waitcnt lgkmcnt(0)
	s_barrier
	s_waitcnt lgkmcnt(0)
	v_mfma_i32_16x16x64_i8 v[60:63], v[124:127], v[186:189], v[60:63]
	v_mfma_i32_16x16x64_i8 v[56:59], v[136:139], v[186:189], v[56:59]
	v_mfma_i32_16x16x64_i8 v[44:47], v[124:127], v[194:197], v[44:47]
	v_mfma_i32_16x16x64_i8 v[40:43], v[136:139], v[194:197], v[40:43]
	s_add_i32 s54, 0, 0x18000
	v_mfma_i32_16x16x64_i8 v[28:31], v[124:127], v[202:205], v[28:31]
	v_mfma_i32_16x16x64_i8 v[24:27], v[136:139], v[202:205], v[24:27]
	s_add_i32 s55, 0, 0x1c000
	v_mfma_i32_16x16x64_i8 v[12:15], v[124:127], v[210:213], v[12:15]
	v_mfma_i32_16x16x64_i8 v[8:11], v[136:139], v[210:213], v[8:11]
	s_add_u32 s34, s34, 0x200000
	v_mfma_i32_16x16x64_i8 v[60:63], v[132:135], v[190:193], v[60:63]
	v_mfma_i32_16x16x64_i8 v[56:59], v[140:143], v[190:193], v[56:59]
	s_addc_u32 s35, s35, 0
	v_mfma_i32_16x16x64_i8 v[44:47], v[132:135], v[198:201], v[44:47]
	v_mfma_i32_16x16x64_i8 v[40:43], v[140:143], v[198:201], v[40:43]
	v_mfma_i32_16x16x64_i8 v[28:31], v[132:135], v[206:209], v[28:31]
	v_mfma_i32_16x16x64_i8 v[24:27], v[140:143], v[206:209], v[24:27]
	v_mfma_i32_16x16x64_i8 v[12:15], v[132:135], v[214:217], v[12:15]
	v_mfma_i32_16x16x64_i8 v[8:11], v[140:143], v[214:217], v[8:11]
	v_mfma_i32_16x16x64_i8 v[52:55], v[162:165], v[186:189], v[52:55]
	v_mfma_i32_16x16x64_i8 v[48:51], v[170:173], v[186:189], v[48:51]
	v_mfma_i32_16x16x64_i8 v[36:39], v[162:165], v[194:197], v[36:39]
	v_mfma_i32_16x16x64_i8 v[32:35], v[170:173], v[194:197], v[32:35]
	v_mfma_i32_16x16x64_i8 v[20:23], v[162:165], v[202:205], v[20:23]
	v_mfma_i32_16x16x64_i8 v[16:19], v[170:173], v[202:205], v[16:19]
	v_mfma_i32_16x16x64_i8 v[4:7], v[162:165], v[210:213], v[4:7]
	v_mfma_i32_16x16x64_i8 v[0:3], v[170:173], v[210:213], v[0:3]
	v_mfma_i32_16x16x64_i8 v[52:55], v[166:169], v[190:193], v[52:55]
	v_mfma_i32_16x16x64_i8 v[48:51], v[174:177], v[190:193], v[48:51]
	v_mfma_i32_16x16x64_i8 v[36:39], v[166:169], v[198:201], v[36:39]
	v_mfma_i32_16x16x64_i8 v[32:35], v[174:177], v[198:201], v[32:35]
	v_mfma_i32_16x16x64_i8 v[20:23], v[166:169], v[206:209], v[20:23]
	v_mfma_i32_16x16x64_i8 v[16:19], v[174:177], v[206:209], v[16:19]
	v_mfma_i32_16x16x64_i8 v[4:7], v[166:169], v[214:217], v[4:7]
	v_mfma_i32_16x16x64_i8 v[0:3], v[174:177], v[214:217], v[0:3]
	s_barrier
	ds_read_b128 v[186:189], v183 offset:32768
	ds_read_b128 v[190:193], v183 offset:33792
	ds_read_b128 v[194:197], v183 offset:34816
	ds_read_b128 v[198:201], v183 offset:35840
	ds_read_b128 v[202:205], v183 offset:36864
	ds_read_b128 v[206:209], v183 offset:37888
	ds_read_b128 v[210:213], v183 offset:38912
	ds_read_b128 v[214:217], v183 offset:39936
	ds_read_b128 v[124:127], v250
	ds_read_b128 v[132:135], v250 offset:1024
	ds_read_b128 v[136:139], v250 offset:2048
	ds_read_b128 v[140:143], v250 offset:3072
	ds_read_b128 v[162:165], v251
	ds_read_b128 v[166:169], v251 offset:1024
	ds_read_b128 v[170:173], v251 offset:2048
	ds_read_b128 v[174:177], v251 offset:3072
	s_mov_b32 m0, s40
	s_nop 0
	global_load_lds_dwordx4 v144, s[34:35]
	s_mov_b32 m0, s41
	s_nop 0
	global_load_lds_dwordx4 v148, s[34:35]
	s_waitcnt vmcnt(8)
	s_waitcnt lgkmcnt(0)
	s_barrier
	s_waitcnt lgkmcnt(0)
	v_mfma_i32_16x16x64_i8 v[116:119], v[124:127], v[186:189], v[116:119]
	v_mfma_i32_16x16x64_i8 v[104:107], v[136:139], v[186:189], v[104:107]
	v_mfma_i32_16x16x64_i8 v[112:115], v[124:127], v[194:197], v[112:115]
	v_mfma_i32_16x16x64_i8 v[108:111], v[136:139], v[194:197], v[108:111]
	s_add_i32 s34, s54, s38
	v_mfma_i32_16x16x64_i8 v[92:95], v[124:127], v[202:205], v[92:95]
	v_mfma_i32_16x16x64_i8 v[88:91], v[136:139], v[202:205], v[88:91]
	v_mfma_i32_16x16x64_i8 v[76:79], v[124:127], v[210:213], v[76:79]
	v_mfma_i32_16x16x64_i8 v[72:75], v[136:139], v[210:213], v[72:75]
	s_add_u32 s30, s30, 0x200080
	v_mfma_i32_16x16x64_i8 v[116:119], v[132:135], v[190:193], v[116:119]
	v_mfma_i32_16x16x64_i8 v[104:107], v[140:143], v[190:193], v[104:107]
	v_mfma_i32_16x16x64_i8 v[112:115], v[132:135], v[198:201], v[112:115]
	v_mfma_i32_16x16x64_i8 v[108:111], v[140:143], v[198:201], v[108:111]
	s_addc_u32 s31, s31, 0
	v_mfma_i32_16x16x64_i8 v[92:95], v[132:135], v[206:209], v[92:95]
	v_mfma_i32_16x16x64_i8 v[88:91], v[140:143], v[206:209], v[88:91]
	v_mfma_i32_16x16x64_i8 v[76:79], v[132:135], v[214:217], v[76:79]
	v_mfma_i32_16x16x64_i8 v[72:75], v[140:143], v[214:217], v[72:75]
	v_mfma_i32_16x16x64_i8 v[128:131], v[162:165], v[186:189], v[128:131]
	v_mfma_i32_16x16x64_i8 v[120:123], v[170:173], v[186:189], v[120:123]
	v_mfma_i32_16x16x64_i8 v[100:103], v[162:165], v[194:197], v[100:103]
	v_mfma_i32_16x16x64_i8 v[96:99], v[170:173], v[194:197], v[96:99]
	v_mfma_i32_16x16x64_i8 v[84:87], v[162:165], v[202:205], v[84:87]
	v_mfma_i32_16x16x64_i8 v[80:83], v[170:173], v[202:205], v[80:83]
	v_mfma_i32_16x16x64_i8 v[68:71], v[162:165], v[210:213], v[68:71]
	v_mfma_i32_16x16x64_i8 v[64:67], v[170:173], v[210:213], v[64:67]
	v_mfma_i32_16x16x64_i8 v[128:131], v[166:169], v[190:193], v[128:131]
	v_mfma_i32_16x16x64_i8 v[120:123], v[174:177], v[190:193], v[120:123]
	v_mfma_i32_16x16x64_i8 v[100:103], v[166:169], v[198:201], v[100:103]
	v_mfma_i32_16x16x64_i8 v[96:99], v[174:177], v[198:201], v[96:99]
	v_mfma_i32_16x16x64_i8 v[84:87], v[166:169], v[206:209], v[84:87]
	v_mfma_i32_16x16x64_i8 v[80:83], v[174:177], v[206:209], v[80:83]
	v_mfma_i32_16x16x64_i8 v[68:71], v[166:169], v[214:217], v[68:71]
	v_mfma_i32_16x16x64_i8 v[64:67], v[174:177], v[214:217], v[64:67]
	s_barrier
	ds_read_b128 v[186:189], v183 offset:49152
	ds_read_b128 v[190:193], v183 offset:50176
	ds_read_b128 v[194:197], v183 offset:51200
	ds_read_b128 v[198:201], v183 offset:52224
	ds_read_b128 v[202:205], v183 offset:53248
	ds_read_b128 v[206:209], v183 offset:54272
	ds_read_b128 v[210:213], v183 offset:55296
	ds_read_b128 v[214:217], v183 offset:56320
	s_mov_b32 m0, s34
	s_nop 0
	global_load_lds_dwordx4 v146, s[98:99]
	s_add_i32 m0, s34, 0x2000
	s_add_i32 s34, s55, s38
	global_load_lds_dwordx4 v150, s[98:99]
	s_mov_b32 m0, s34
	s_nop 0
	global_load_lds_dwordx4 v146, s[30:31]
	s_add_i32 m0, s34, 0x2000
	s_nop 0
	global_load_lds_dwordx4 v150, s[30:31]
	s_mov_b32 m0, s43
	s_nop 0
	global_load_lds_dwordx4 v144, s[100:101]
	s_mov_b32 m0, s44
	s_nop 0
	global_load_lds_dwordx4 v148, s[100:101]
	s_waitcnt vmcnt(8)
	s_waitcnt lgkmcnt(0)
	s_barrier
	s_waitcnt lgkmcnt(0)
	v_mfma_i32_16x16x64_i8 v[60:63], v[124:127], v[186:189], v[60:63]
	v_mfma_i32_16x16x64_i8 v[56:59], v[136:139], v[186:189], v[56:59]
	v_mfma_i32_16x16x64_i8 v[44:47], v[124:127], v[194:197], v[44:47]
	v_mfma_i32_16x16x64_i8 v[40:43], v[136:139], v[194:197], v[40:43]
	v_mfma_i32_16x16x64_i8 v[28:31], v[124:127], v[202:205], v[28:31]
	v_mfma_i32_16x16x64_i8 v[24:27], v[136:139], v[202:205], v[24:27]
	v_mfma_i32_16x16x64_i8 v[12:15], v[124:127], v[210:213], v[12:15]
	v_mfma_i32_16x16x64_i8 v[8:11], v[136:139], v[210:213], v[8:11]
	v_mfma_i32_16x16x64_i8 v[60:63], v[132:135], v[190:193], v[60:63]
	v_mfma_i32_16x16x64_i8 v[56:59], v[140:143], v[190:193], v[56:59]
	v_mfma_i32_16x16x64_i8 v[44:47], v[132:135], v[198:201], v[44:47]
	v_mfma_i32_16x16x64_i8 v[40:43], v[140:143], v[198:201], v[40:43]
	v_mfma_i32_16x16x64_i8 v[28:31], v[132:135], v[206:209], v[28:31]
	v_mfma_i32_16x16x64_i8 v[24:27], v[140:143], v[206:209], v[24:27]
	v_mfma_i32_16x16x64_i8 v[12:15], v[132:135], v[214:217], v[12:15]
	v_mfma_i32_16x16x64_i8 v[8:11], v[140:143], v[214:217], v[8:11]
	v_mfma_i32_16x16x64_i8 v[52:55], v[162:165], v[186:189], v[52:55]
	v_mfma_i32_16x16x64_i8 v[48:51], v[170:173], v[186:189], v[48:51]
	v_mfma_i32_16x16x64_i8 v[36:39], v[162:165], v[194:197], v[36:39]
	v_mfma_i32_16x16x64_i8 v[32:35], v[170:173], v[194:197], v[32:35]
	v_mfma_i32_16x16x64_i8 v[20:23], v[162:165], v[202:205], v[20:23]
	v_mfma_i32_16x16x64_i8 v[16:19], v[170:173], v[202:205], v[16:19]
	v_mfma_i32_16x16x64_i8 v[4:7], v[162:165], v[210:213], v[4:7]
	v_mfma_i32_16x16x64_i8 v[0:3], v[170:173], v[210:213], v[0:3]
	v_mfma_i32_16x16x64_i8 v[52:55], v[166:169], v[190:193], v[52:55]
	v_mfma_i32_16x16x64_i8 v[48:51], v[174:177], v[190:193], v[48:51]
	v_mfma_i32_16x16x64_i8 v[36:39], v[166:169], v[198:201], v[36:39]
	v_mfma_i32_16x16x64_i8 v[32:35], v[174:177], v[198:201], v[32:35]
	v_mfma_i32_16x16x64_i8 v[20:23], v[166:169], v[206:209], v[20:23]
	v_mfma_i32_16x16x64_i8 v[16:19], v[174:177], v[206:209], v[16:19]
	v_mfma_i32_16x16x64_i8 v[4:7], v[166:169], v[214:217], v[4:7]
	v_mfma_i32_16x16x64_i8 v[0:3], v[174:177], v[214:217], v[0:3]
	s_barrier
	s_add_i32 s53, s53, 2
	s_add_u32 s51, s51, 0x100
	s_addc_u32 s52, s52, 0
	s_add_u32 s28, s28, 0x100
	s_addc_u32 s29, s29, 0
	s_cmpk_gt_u32 s53, 0x7d
	s_cbranch_scc0 .LBB0_1841
	s_setprio 0
	s_and_b64 vcc, exec, s[12:13]
	s_cbranch_vccz .LBB0_1844
	s_barrier
